# v2c + all per-cluster s_setprio flips removed from the 12 GEMM K-loops
# speedup vs baseline: 1.0105x; 1.0024x over previous
.LBB0_156:
	v_add_u32_e32 v139, 0x10000, v137
	ds_read_b128 v[140:143], v139
	ds_read_b128 v[144:147], v139 offset:1024
	ds_read_b128 v[148:151], v139 offset:2048
	ds_read_b128 v[152:155], v139 offset:3072
	v_add_u32_e32 v139, 0x14000, v137
	ds_read_b128 v[156:159], v139
	ds_read_b128 v[160:163], v139 offset:1024
	ds_read_b128 v[164:167], v139 offset:2048
	ds_read_b128 v[168:171], v139 offset:3072
	s_add_u32 s0, s52, 0x100
	s_addc_u32 s1, s53, 0
	s_cmp_eq_u32 s89, 12
	s_cselect_b32 s34, s15, s0
	s_cselect_b32 s35, s14, s1
	s_cselect_b32 s56, s41, s87
	s_cselect_b32 s57, s11, s88
	s_add_u32 s54, s34, 0x80
	s_addc_u32 s55, s35, 0
	ds_read_b128 v[172:175], v138
	ds_read_b128 v[176:179], v138 offset:1024
	ds_read_b128 v[180:183], v138 offset:2048
	ds_read_b128 v[184:187], v138 offset:3072
	ds_read_b128 v[188:191], v138 offset:4096
	ds_read_b128 v[192:195], v138 offset:5120
	ds_read_b128 v[196:199], v138 offset:6144
	ds_read_b128 v[200:203], v138 offset:7168
	s_add_u32 s90, s52, 0x40080
	s_addc_u32 s91, s53, 0
	s_mov_b32 s12, m0
	s_mov_b32 m0, s83
	s_nop 4
	global_load_lds_dwordx4 v1, s[90:91]
	s_mov_b32 m0, s12
	s_add_u32 s52, s52, 0x60080
	s_addc_u32 s53, s53, 0
	s_add_i32 s12, s51, 0xe000
	s_mov_b32 s13, m0
	s_mov_b32 m0, s12
	s_nop 4
	global_load_lds_dwordx4 v1, s[52:53]
	s_mov_b32 m0, s13
	s_waitcnt vmcnt(8)
	s_waitcnt lgkmcnt(0)
	s_barrier
	s_waitcnt lgkmcnt(7)
	v_mfma_f32_16x16x32_bf16 v[122:125], v[140:143], v[172:175], v[122:125]
	v_mfma_f32_16x16x32_bf16 v[114:117], v[148:151], v[172:175], v[114:117]
	s_waitcnt lgkmcnt(5)
	v_mfma_f32_16x16x32_bf16 v[106:109], v[140:143], v[180:183], v[106:109]
	v_mfma_f32_16x16x32_bf16 v[98:101], v[148:151], v[180:183], v[98:101]
	s_waitcnt lgkmcnt(3)
	v_mfma_f32_16x16x32_bf16 v[90:93], v[140:143], v[188:191], v[90:93]
	v_mfma_f32_16x16x32_bf16 v[82:85], v[148:151], v[188:191], v[82:85]
	s_waitcnt lgkmcnt(1)
	v_mfma_f32_16x16x32_bf16 v[74:77], v[140:143], v[196:199], v[74:77]
	v_mfma_f32_16x16x32_bf16 v[66:69], v[148:151], v[196:199], v[66:69]
	v_mfma_f32_16x16x32_bf16 v[122:125], v[144:147], v[176:179], v[122:125]
	v_mfma_f32_16x16x32_bf16 v[114:117], v[152:155], v[176:179], v[114:117]
	v_mfma_f32_16x16x32_bf16 v[106:109], v[144:147], v[184:187], v[106:109]
	v_mfma_f32_16x16x32_bf16 v[98:101], v[152:155], v[184:187], v[98:101]
	v_mfma_f32_16x16x32_bf16 v[90:93], v[144:147], v[192:195], v[90:93]
	v_mfma_f32_16x16x32_bf16 v[82:85], v[152:155], v[192:195], v[82:85]
	s_waitcnt lgkmcnt(0)
	v_mfma_f32_16x16x32_bf16 v[74:77], v[144:147], v[200:203], v[74:77]
	v_mfma_f32_16x16x32_bf16 v[66:69], v[152:155], v[200:203], v[66:69]
	v_mfma_f32_16x16x32_bf16 v[126:129], v[156:159], v[172:175], v[126:129]
	v_mfma_f32_16x16x32_bf16 v[118:121], v[164:167], v[172:175], v[118:121]
	v_mfma_f32_16x16x32_bf16 v[110:113], v[156:159], v[180:183], v[110:113]
	v_mfma_f32_16x16x32_bf16 v[102:105], v[164:167], v[180:183], v[102:105]
	v_mfma_f32_16x16x32_bf16 v[94:97], v[156:159], v[188:191], v[94:97]
	v_mfma_f32_16x16x32_bf16 v[86:89], v[164:167], v[188:191], v[86:89]
	v_mfma_f32_16x16x32_bf16 v[78:81], v[156:159], v[196:199], v[78:81]
	v_mfma_f32_16x16x32_bf16 v[70:73], v[164:167], v[196:199], v[70:73]
	v_mfma_f32_16x16x32_bf16 v[126:129], v[160:163], v[176:179], v[126:129]
	v_mfma_f32_16x16x32_bf16 v[118:121], v[168:171], v[176:179], v[118:121]
	v_mfma_f32_16x16x32_bf16 v[110:113], v[160:163], v[184:187], v[110:113]
	v_mfma_f32_16x16x32_bf16 v[102:105], v[168:171], v[184:187], v[102:105]
	v_mfma_f32_16x16x32_bf16 v[94:97], v[160:163], v[192:195], v[94:97]
	v_mfma_f32_16x16x32_bf16 v[86:89], v[168:171], v[192:195], v[86:89]
	v_mfma_f32_16x16x32_bf16 v[78:81], v[160:163], v[200:203], v[78:81]
	v_mfma_f32_16x16x32_bf16 v[70:73], v[168:171], v[200:203], v[70:73]
	s_barrier
	s_add_u32 s52, s56, 0x20000
	ds_read_b128 v[172:175], v138 offset:16384
	ds_read_b128 v[176:179], v138 offset:17408
	ds_read_b128 v[180:183], v138 offset:18432
	ds_read_b128 v[184:187], v138 offset:19456
	ds_read_b128 v[188:191], v138 offset:20480
	ds_read_b128 v[192:195], v138 offset:21504
	ds_read_b128 v[196:199], v138 offset:22528
	ds_read_b128 v[200:203], v138 offset:23552
	s_mov_b32 s12, m0
	s_mov_b32 m0, s62
	s_nop 4
	global_load_lds_dwordx4 v134, s[56:57]
	s_mov_b32 m0, s12
	s_addc_u32 s53, s57, 0
	s_mov_b32 s12, m0
	s_mov_b32 m0, s63
	s_nop 4
	global_load_lds_dwordx4 v134, s[52:53]
	s_mov_b32 m0, s12
	s_add_u32 s52, s56, 0x40000
	s_addc_u32 s53, s57, 0
	s_mov_b32 s12, m0
	s_mov_b32 m0, s64
	s_nop 4
	global_load_lds_dwordx4 v134, s[52:53]
	s_mov_b32 m0, s12
	s_add_u32 s52, s56, 0x60000
	s_addc_u32 s53, s57, 0
	s_mov_b32 s12, m0
	s_mov_b32 m0, s65
	s_nop 4
	global_load_lds_dwordx4 v134, s[52:53]
	s_mov_b32 m0, s12
	s_add_u32 s52, s34, 0x20000
	s_mov_b32 s12, m0
	s_mov_b32 m0, s51
	s_nop 4
	global_load_lds_dwordx4 v1, s[34:35]
	s_mov_b32 m0, s12
	s_addc_u32 s53, s35, 0
	s_mov_b32 s12, m0
	s_mov_b32 m0, s73
	s_nop 4
	global_load_lds_dwordx4 v1, s[52:53]
	s_mov_b32 m0, s12
	s_waitcnt vmcnt(8)
	s_waitcnt lgkmcnt(0)
	s_barrier
	s_waitcnt lgkmcnt(7)
	v_mfma_f32_16x16x32_bf16 v[58:61], v[140:143], v[172:175], v[58:61]
	v_mfma_f32_16x16x32_bf16 v[50:53], v[148:151], v[172:175], v[50:53]
	s_waitcnt lgkmcnt(5)
	v_mfma_f32_16x16x32_bf16 v[42:45], v[140:143], v[180:183], v[42:45]
	v_mfma_f32_16x16x32_bf16 v[34:37], v[148:151], v[180:183], v[34:37]
	s_waitcnt lgkmcnt(3)
	v_mfma_f32_16x16x32_bf16 v[26:29], v[140:143], v[188:191], v[26:29]
	v_mfma_f32_16x16x32_bf16 v[18:21], v[148:151], v[188:191], v[18:21]
	s_waitcnt lgkmcnt(1)
	v_mfma_f32_16x16x32_bf16 v[10:13], v[140:143], v[196:199], v[10:13]
	v_mfma_f32_16x16x32_bf16 v[2:5], v[148:151], v[196:199], v[2:5]
	v_mfma_f32_16x16x32_bf16 v[58:61], v[144:147], v[176:179], v[58:61]
	v_mfma_f32_16x16x32_bf16 v[50:53], v[152:155], v[176:179], v[50:53]
	v_mfma_f32_16x16x32_bf16 v[42:45], v[144:147], v[184:187], v[42:45]
	v_mfma_f32_16x16x32_bf16 v[34:37], v[152:155], v[184:187], v[34:37]
	v_mfma_f32_16x16x32_bf16 v[26:29], v[144:147], v[192:195], v[26:29]
	v_mfma_f32_16x16x32_bf16 v[18:21], v[152:155], v[192:195], v[18:21]
	s_waitcnt lgkmcnt(0)
	v_mfma_f32_16x16x32_bf16 v[10:13], v[144:147], v[200:203], v[10:13]
	v_mfma_f32_16x16x32_bf16 v[2:5], v[152:155], v[200:203], v[2:5]
	v_mfma_f32_16x16x32_bf16 v[62:65], v[156:159], v[172:175], v[62:65]
	v_mfma_f32_16x16x32_bf16 v[54:57], v[164:167], v[172:175], v[54:57]
	v_mfma_f32_16x16x32_bf16 v[46:49], v[156:159], v[180:183], v[46:49]
	v_mfma_f32_16x16x32_bf16 v[38:41], v[164:167], v[180:183], v[38:41]
	v_mfma_f32_16x16x32_bf16 v[30:33], v[156:159], v[188:191], v[30:33]
	v_mfma_f32_16x16x32_bf16 v[22:25], v[164:167], v[188:191], v[22:25]
	v_mfma_f32_16x16x32_bf16 v[14:17], v[156:159], v[196:199], v[14:17]
	v_mfma_f32_16x16x32_bf16 v[6:9], v[164:167], v[196:199], v[6:9]
	v_mfma_f32_16x16x32_bf16 v[62:65], v[160:163], v[176:179], v[62:65]
	v_mfma_f32_16x16x32_bf16 v[54:57], v[168:171], v[176:179], v[54:57]
	v_mfma_f32_16x16x32_bf16 v[46:49], v[160:163], v[184:187], v[46:49]
	v_mfma_f32_16x16x32_bf16 v[38:41], v[168:171], v[184:187], v[38:41]
	v_mfma_f32_16x16x32_bf16 v[30:33], v[160:163], v[192:195], v[30:33]
	v_mfma_f32_16x16x32_bf16 v[22:25], v[168:171], v[192:195], v[22:25]
	v_mfma_f32_16x16x32_bf16 v[14:17], v[160:163], v[200:203], v[14:17]
	v_mfma_f32_16x16x32_bf16 v[6:9], v[168:171], v[200:203], v[6:9]
	s_barrier
	v_add_u32_e32 v139, 0x18000, v137
	ds_read_b128 v[140:143], v139
	ds_read_b128 v[144:147], v139 offset:1024
	ds_read_b128 v[148:151], v139 offset:2048
	ds_read_b128 v[152:155], v139 offset:3072
	v_add_u32_e32 v139, 0x1c000, v137
	ds_read_b128 v[156:159], v139
	ds_read_b128 v[160:163], v139 offset:1024
	ds_read_b128 v[164:167], v139 offset:2048
	ds_read_b128 v[168:171], v139 offset:3072
	ds_read_b128 v[172:175], v138 offset:32768
	ds_read_b128 v[176:179], v138 offset:33792
	ds_read_b128 v[180:183], v138 offset:34816
	ds_read_b128 v[184:187], v138 offset:35840
	ds_read_b128 v[188:191], v138 offset:36864
	ds_read_b128 v[192:195], v138 offset:37888
	ds_read_b128 v[196:199], v138 offset:38912
	ds_read_b128 v[200:203], v138 offset:39936
	s_add_u32 s52, s34, 0x40000
	s_addc_u32 s53, s35, 0
	s_mov_b32 s12, m0
	s_mov_b32 m0, s74
	s_nop 4
	global_load_lds_dwordx4 v1, s[52:53]
	s_mov_b32 m0, s12
	s_add_u32 s52, s34, 0x60000
	s_addc_u32 s53, s35, 0
	s_mov_b32 s12, m0
	s_mov_b32 m0, s75
	s_nop 4
	global_load_lds_dwordx4 v1, s[52:53]
	s_mov_b32 m0, s12
	s_waitcnt vmcnt(8)
	s_waitcnt lgkmcnt(0)
	s_barrier
	s_waitcnt lgkmcnt(7)
	v_mfma_f32_16x16x32_bf16 v[122:125], v[140:143], v[172:175], v[122:125]
	v_mfma_f32_16x16x32_bf16 v[114:117], v[148:151], v[172:175], v[114:117]
	s_waitcnt lgkmcnt(5)
	v_mfma_f32_16x16x32_bf16 v[106:109], v[140:143], v[180:183], v[106:109]
	v_mfma_f32_16x16x32_bf16 v[98:101], v[148:151], v[180:183], v[98:101]
	s_waitcnt lgkmcnt(3)
	v_mfma_f32_16x16x32_bf16 v[90:93], v[140:143], v[188:191], v[90:93]
	v_mfma_f32_16x16x32_bf16 v[82:85], v[148:151], v[188:191], v[82:85]
	s_waitcnt lgkmcnt(1)
	v_mfma_f32_16x16x32_bf16 v[74:77], v[140:143], v[196:199], v[74:77]
	v_mfma_f32_16x16x32_bf16 v[66:69], v[148:151], v[196:199], v[66:69]
	v_mfma_f32_16x16x32_bf16 v[122:125], v[144:147], v[176:179], v[122:125]
	v_mfma_f32_16x16x32_bf16 v[114:117], v[152:155], v[176:179], v[114:117]
	v_mfma_f32_16x16x32_bf16 v[106:109], v[144:147], v[184:187], v[106:109]
	v_mfma_f32_16x16x32_bf16 v[98:101], v[152:155], v[184:187], v[98:101]
	v_mfma_f32_16x16x32_bf16 v[90:93], v[144:147], v[192:195], v[90:93]
	v_mfma_f32_16x16x32_bf16 v[82:85], v[152:155], v[192:195], v[82:85]
	s_waitcnt lgkmcnt(0)
	v_mfma_f32_16x16x32_bf16 v[74:77], v[144:147], v[200:203], v[74:77]
	v_mfma_f32_16x16x32_bf16 v[66:69], v[152:155], v[200:203], v[66:69]
	v_mfma_f32_16x16x32_bf16 v[126:129], v[156:159], v[172:175], v[126:129]
	v_mfma_f32_16x16x32_bf16 v[118:121], v[164:167], v[172:175], v[118:121]
	v_mfma_f32_16x16x32_bf16 v[110:113], v[156:159], v[180:183], v[110:113]
	v_mfma_f32_16x16x32_bf16 v[102:105], v[164:167], v[180:183], v[102:105]
	v_mfma_f32_16x16x32_bf16 v[94:97], v[156:159], v[188:191], v[94:97]
	v_mfma_f32_16x16x32_bf16 v[86:89], v[164:167], v[188:191], v[86:89]
	v_mfma_f32_16x16x32_bf16 v[78:81], v[156:159], v[196:199], v[78:81]
	v_mfma_f32_16x16x32_bf16 v[70:73], v[164:167], v[196:199], v[70:73]
	v_mfma_f32_16x16x32_bf16 v[126:129], v[160:163], v[176:179], v[126:129]
	v_mfma_f32_16x16x32_bf16 v[118:121], v[168:171], v[176:179], v[118:121]
	v_mfma_f32_16x16x32_bf16 v[110:113], v[160:163], v[184:187], v[110:113]
	v_mfma_f32_16x16x32_bf16 v[102:105], v[168:171], v[184:187], v[102:105]
	v_mfma_f32_16x16x32_bf16 v[94:97], v[160:163], v[192:195], v[94:97]
	v_mfma_f32_16x16x32_bf16 v[86:89], v[168:171], v[192:195], v[86:89]
	v_mfma_f32_16x16x32_bf16 v[78:81], v[160:163], v[200:203], v[78:81]
	v_mfma_f32_16x16x32_bf16 v[70:73], v[168:171], v[200:203], v[70:73]
	s_barrier
	s_add_u32 s52, s56, 0x80
	s_addc_u32 s53, s57, 0
	ds_read_b128 v[172:175], v138 offset:49152
	ds_read_b128 v[176:179], v138 offset:50176
	ds_read_b128 v[180:183], v138 offset:51200
	ds_read_b128 v[184:187], v138 offset:52224
	ds_read_b128 v[188:191], v138 offset:53248
	ds_read_b128 v[192:195], v138 offset:54272
	ds_read_b128 v[196:199], v138 offset:55296
	ds_read_b128 v[200:203], v138 offset:56320
	s_mov_b32 s12, m0
	s_mov_b32 m0, s76
	s_nop 4
	global_load_lds_dwordx4 v134, s[52:53]
	s_mov_b32 m0, s12
	s_add_u32 s52, s56, 0x20080
	s_addc_u32 s53, s57, 0
	s_mov_b32 s12, m0
	s_mov_b32 m0, s77
	s_nop 4
	global_load_lds_dwordx4 v134, s[52:53]
	s_mov_b32 m0, s12
	s_add_u32 s52, s56, 0x40080
	s_addc_u32 s53, s57, 0
	s_mov_b32 s12, m0
	s_mov_b32 m0, s80
	s_nop 4
	global_load_lds_dwordx4 v134, s[52:53]
	s_mov_b32 m0, s12
	s_add_u32 s52, s56, 0x60080
	s_addc_u32 s53, s57, 0
	s_mov_b32 s12, m0
	s_mov_b32 m0, s81
	s_nop 4
	global_load_lds_dwordx4 v134, s[52:53]
	s_mov_b32 m0, s12
	s_add_u32 s34, s34, 0x20080
	s_mov_b32 s12, m0
	s_mov_b32 m0, s78
	s_nop 4
	global_load_lds_dwordx4 v1, s[54:55]
	s_mov_b32 m0, s12
	s_addc_u32 s35, s35, 0
	s_mov_b32 s12, m0
	s_mov_b32 m0, s79
	s_nop 4
	global_load_lds_dwordx4 v1, s[34:35]
	s_mov_b32 m0, s12
	s_waitcnt vmcnt(8)
	s_waitcnt lgkmcnt(0)
	s_barrier
	s_waitcnt lgkmcnt(7)
	v_mfma_f32_16x16x32_bf16 v[58:61], v[140:143], v[172:175], v[58:61]
	v_mfma_f32_16x16x32_bf16 v[50:53], v[148:151], v[172:175], v[50:53]
	s_waitcnt lgkmcnt(5)
	v_mfma_f32_16x16x32_bf16 v[42:45], v[140:143], v[180:183], v[42:45]
	v_mfma_f32_16x16x32_bf16 v[34:37], v[148:151], v[180:183], v[34:37]
	s_waitcnt lgkmcnt(3)
	v_mfma_f32_16x16x32_bf16 v[26:29], v[140:143], v[188:191], v[26:29]
	v_mfma_f32_16x16x32_bf16 v[18:21], v[148:151], v[188:191], v[18:21]
	s_waitcnt lgkmcnt(1)
	v_mfma_f32_16x16x32_bf16 v[10:13], v[140:143], v[196:199], v[10:13]
	v_mfma_f32_16x16x32_bf16 v[2:5], v[148:151], v[196:199], v[2:5]
	v_mfma_f32_16x16x32_bf16 v[58:61], v[144:147], v[176:179], v[58:61]
	v_mfma_f32_16x16x32_bf16 v[50:53], v[152:155], v[176:179], v[50:53]
	v_mfma_f32_16x16x32_bf16 v[42:45], v[144:147], v[184:187], v[42:45]
	v_mfma_f32_16x16x32_bf16 v[34:37], v[152:155], v[184:187], v[34:37]
	v_mfma_f32_16x16x32_bf16 v[26:29], v[144:147], v[192:195], v[26:29]
	v_mfma_f32_16x16x32_bf16 v[18:21], v[152:155], v[192:195], v[18:21]
	s_waitcnt lgkmcnt(0)
	v_mfma_f32_16x16x32_bf16 v[10:13], v[144:147], v[200:203], v[10:13]
	v_mfma_f32_16x16x32_bf16 v[2:5], v[152:155], v[200:203], v[2:5]
	v_mfma_f32_16x16x32_bf16 v[62:65], v[156:159], v[172:175], v[62:65]
	v_mfma_f32_16x16x32_bf16 v[54:57], v[164:167], v[172:175], v[54:57]
	v_mfma_f32_16x16x32_bf16 v[46:49], v[156:159], v[180:183], v[46:49]
	v_mfma_f32_16x16x32_bf16 v[38:41], v[164:167], v[180:183], v[38:41]
	v_mfma_f32_16x16x32_bf16 v[30:33], v[156:159], v[188:191], v[30:33]
	v_mfma_f32_16x16x32_bf16 v[22:25], v[164:167], v[188:191], v[22:25]
	v_mfma_f32_16x16x32_bf16 v[14:17], v[156:159], v[196:199], v[14:17]
	v_mfma_f32_16x16x32_bf16 v[6:9], v[164:167], v[196:199], v[6:9]
	v_mfma_f32_16x16x32_bf16 v[62:65], v[160:163], v[176:179], v[62:65]
	v_mfma_f32_16x16x32_bf16 v[54:57], v[168:171], v[176:179], v[54:57]
	v_mfma_f32_16x16x32_bf16 v[46:49], v[160:163], v[184:187], v[46:49]
	v_mfma_f32_16x16x32_bf16 v[38:41], v[168:171], v[184:187], v[38:41]
	v_mfma_f32_16x16x32_bf16 v[30:33], v[160:163], v[192:195], v[30:33]
	v_mfma_f32_16x16x32_bf16 v[22:25], v[168:171], v[192:195], v[22:25]
	v_mfma_f32_16x16x32_bf16 v[14:17], v[160:163], v[200:203], v[14:17]
	v_mfma_f32_16x16x32_bf16 v[6:9], v[168:171], v[200:203], v[6:9]
	s_barrier
	s_add_i32 s89, s89, 2
	s_add_u32 s87, s87, 0x100
	s_addc_u32 s88, s88, 0
	s_cmp_gt_u32 s89, 13
	s_mov_b64 s[52:53], s[0:1]
	s_cbranch_scc0 .LBB0_156
	s_and_b64 vcc, exec, s[8:9]
	s_cbranch_vccz .LBB0_159
	s_barrier

.LBB0_236:
	ds_read_b128 v[138:141], v132
	ds_read_b128 v[142:145], v132 offset:1024
	ds_read_b128 v[146:149], v132 offset:2048
	ds_read_b128 v[150:153], v132 offset:3072
	ds_read_b128 v[154:157], v133
	ds_read_b128 v[158:161], v133 offset:1024
	ds_read_b128 v[166:169], v133 offset:2048
	ds_read_b128 v[170:173], v133 offset:3072
	s_add_u32 s0, s52, 0xea350080
	s_addc_u32 s1, s53, -1
	s_cmp_lg_u32 s92, 40
	s_cselect_b32 s3, s0, 0
	s_cselect_b32 s2, s1, 0
	s_add_u32 s0, s10, s3
	s_addc_u32 s1, s11, s2
	s_add_u32 s34, s0, 0x80
	s_addc_u32 s35, s1, 0
	s_add_u32 s54, s6, s3
	s_addc_u32 s55, s7, s2
	ds_read_b128 v[174:177], v134
	ds_read_b128 v[184:187], v134 offset:1024
	ds_read_b128 v[188:191], v134 offset:2048
	ds_read_b128 v[192:195], v134 offset:3072
	ds_read_b128 v[196:199], v134 offset:4096
	ds_read_b128 v[200:203], v134 offset:5120
	ds_read_b128 v[204:207], v134 offset:6144
	ds_read_b128 v[208:211], v134 offset:7168
	s_add_u32 s94, s90, s52
	s_addc_u32 s95, s91, s53
	s_mov_b32 s2, m0
	s_mov_b32 m0, s89
	s_nop 4
	global_load_lds_dwordx4 v130, s[94:95]
	s_mov_b32 m0, s2
	s_add_u32 s94, s94, 0x58000
	s_addc_u32 s95, s95, 0
	s_add_i32 s2, s65, 0xe000
	s_mov_b32 s3, m0
	s_mov_b32 m0, s2
	s_nop 4
	global_load_lds_dwordx4 v130, s[94:95]
	s_mov_b32 m0, s3
	s_waitcnt vmcnt(8)
	s_waitcnt lgkmcnt(0)
	s_barrier
	s_waitcnt lgkmcnt(7)
	v_mfma_f32_16x16x32_bf16 v[2:5], v[138:141], v[174:177], v[2:5]
	v_mfma_f32_16x16x32_bf16 v[6:9], v[146:149], v[174:177], v[6:9]
	s_waitcnt lgkmcnt(5)
	v_mfma_f32_16x16x32_bf16 v[30:33], v[138:141], v[188:191], v[30:33]
	v_mfma_f32_16x16x32_bf16 v[34:37], v[146:149], v[188:191], v[34:37]
	s_waitcnt lgkmcnt(3)
	v_mfma_f32_16x16x32_bf16 v[54:57], v[138:141], v[196:199], v[54:57]
	v_mfma_f32_16x16x32_bf16 v[50:53], v[146:149], v[196:199], v[50:53]
	s_waitcnt lgkmcnt(1)
	v_mfma_f32_16x16x32_bf16 v[70:73], v[138:141], v[204:207], v[70:73]
	v_mfma_f32_16x16x32_bf16 v[62:65], v[146:149], v[204:207], v[62:65]
	v_mfma_f32_16x16x32_bf16 v[2:5], v[142:145], v[184:187], v[2:5]
	v_mfma_f32_16x16x32_bf16 v[6:9], v[150:153], v[184:187], v[6:9]
	v_mfma_f32_16x16x32_bf16 v[30:33], v[142:145], v[192:195], v[30:33]
	v_mfma_f32_16x16x32_bf16 v[34:37], v[150:153], v[192:195], v[34:37]
	v_mfma_f32_16x16x32_bf16 v[54:57], v[142:145], v[200:203], v[54:57]
	v_mfma_f32_16x16x32_bf16 v[50:53], v[150:153], v[200:203], v[50:53]
	s_waitcnt lgkmcnt(0)
	v_mfma_f32_16x16x32_bf16 v[70:73], v[142:145], v[208:211], v[70:73]
	v_mfma_f32_16x16x32_bf16 v[62:65], v[150:153], v[208:211], v[62:65]
	v_mfma_f32_16x16x32_bf16 v[10:13], v[154:157], v[174:177], v[10:13]
	v_mfma_f32_16x16x32_bf16 v[14:17], v[166:169], v[174:177], v[14:17]
	v_mfma_f32_16x16x32_bf16 v[22:25], v[154:157], v[188:191], v[22:25]
	v_mfma_f32_16x16x32_bf16 v[18:21], v[166:169], v[188:191], v[18:21]
	v_mfma_f32_16x16x32_bf16 v[38:41], v[154:157], v[196:199], v[38:41]
	v_mfma_f32_16x16x32_bf16 v[26:29], v[166:169], v[196:199], v[26:29]
	v_mfma_f32_16x16x32_bf16 v[46:49], v[154:157], v[204:207], v[46:49]
	v_mfma_f32_16x16x32_bf16 v[42:45], v[166:169], v[204:207], v[42:45]
	v_mfma_f32_16x16x32_bf16 v[10:13], v[158:161], v[184:187], v[10:13]
	v_mfma_f32_16x16x32_bf16 v[14:17], v[170:173], v[184:187], v[14:17]
	v_mfma_f32_16x16x32_bf16 v[22:25], v[158:161], v[192:195], v[22:25]
	v_mfma_f32_16x16x32_bf16 v[18:21], v[170:173], v[192:195], v[18:21]
	v_mfma_f32_16x16x32_bf16 v[38:41], v[158:161], v[200:203], v[38:41]
	v_mfma_f32_16x16x32_bf16 v[26:29], v[170:173], v[200:203], v[26:29]
	v_mfma_f32_16x16x32_bf16 v[46:49], v[158:161], v[208:211], v[46:49]
	v_mfma_f32_16x16x32_bf16 v[42:45], v[170:173], v[208:211], v[42:45]
	s_barrier
	s_add_u32 s94, s54, 0x58000
	ds_read_b128 v[174:177], v134 offset:16384
	ds_read_b128 v[184:187], v134 offset:17408
	ds_read_b128 v[188:191], v134 offset:18432
	ds_read_b128 v[192:195], v134 offset:19456
	ds_read_b128 v[196:199], v134 offset:20480
	ds_read_b128 v[200:203], v134 offset:21504
	ds_read_b128 v[204:207], v134 offset:22528
	ds_read_b128 v[208:211], v134 offset:23552
	s_mov_b32 s2, m0
	s_mov_b32 m0, s73
	s_nop 4
	global_load_lds_dwordx4 v131, s[54:55]
	s_mov_b32 m0, s2
	s_addc_u32 s95, s55, 0
	s_mov_b32 s2, m0
	s_mov_b32 m0, s74
	s_nop 4
	global_load_lds_dwordx4 v131, s[94:95]
	s_mov_b32 m0, s2
	s_add_u32 s94, s54, 0xb0000
	s_addc_u32 s95, s55, 0
	s_mov_b32 s2, m0
	s_mov_b32 m0, s75
	s_nop 4
	global_load_lds_dwordx4 v131, s[94:95]
	s_mov_b32 m0, s2
	s_add_u32 s94, s54, 0x108000
	s_addc_u32 s95, s55, 0
	s_mov_b32 s2, m0
	s_mov_b32 m0, s76
	s_nop 4
	global_load_lds_dwordx4 v131, s[94:95]
	s_mov_b32 m0, s2
	s_add_u32 s94, s0, 0x58000
	s_mov_b32 s2, m0
	s_mov_b32 m0, s65
	s_nop 4
	global_load_lds_dwordx4 v130, s[0:1]
	s_mov_b32 m0, s2
	s_addc_u32 s95, s1, 0
	s_mov_b32 s2, m0
	s_mov_b32 m0, s77
	s_nop 4
	global_load_lds_dwordx4 v130, s[94:95]
	s_mov_b32 m0, s2
	s_waitcnt vmcnt(8)
	s_waitcnt lgkmcnt(0)
	s_barrier
	s_waitcnt lgkmcnt(7)
	v_mfma_f32_16x16x32_bf16 v[82:85], v[138:141], v[174:177], v[82:85]
	v_mfma_f32_16x16x32_bf16 v[74:77], v[146:149], v[174:177], v[74:77]
	s_waitcnt lgkmcnt(5)
	v_mfma_f32_16x16x32_bf16 v[98:101], v[138:141], v[188:191], v[98:101]
	v_mfma_f32_16x16x32_bf16 v[90:93], v[146:149], v[188:191], v[90:93]
	s_waitcnt lgkmcnt(3)
	v_mfma_f32_16x16x32_bf16 v[114:117], v[138:141], v[196:199], v[114:117]
	v_mfma_f32_16x16x32_bf16 v[110:113], v[146:149], v[196:199], v[110:113]
	s_waitcnt lgkmcnt(1)
	v_mfma_f32_16x16x32_bf16 v[126:129], v[138:141], v[204:207], v[126:129]
	v_mfma_f32_16x16x32_bf16 v[122:125], v[146:149], v[204:207], v[122:125]
	v_mfma_f32_16x16x32_bf16 v[82:85], v[142:145], v[184:187], v[82:85]
	v_mfma_f32_16x16x32_bf16 v[74:77], v[150:153], v[184:187], v[74:77]
	v_mfma_f32_16x16x32_bf16 v[98:101], v[142:145], v[192:195], v[98:101]
	v_mfma_f32_16x16x32_bf16 v[90:93], v[150:153], v[192:195], v[90:93]
	v_mfma_f32_16x16x32_bf16 v[114:117], v[142:145], v[200:203], v[114:117]
	v_mfma_f32_16x16x32_bf16 v[110:113], v[150:153], v[200:203], v[110:113]
	s_waitcnt lgkmcnt(0)
	v_mfma_f32_16x16x32_bf16 v[126:129], v[142:145], v[208:211], v[126:129]
	v_mfma_f32_16x16x32_bf16 v[122:125], v[150:153], v[208:211], v[122:125]
	v_mfma_f32_16x16x32_bf16 v[66:69], v[154:157], v[174:177], v[66:69]
	v_mfma_f32_16x16x32_bf16 v[58:61], v[166:169], v[174:177], v[58:61]
	v_mfma_f32_16x16x32_bf16 v[86:89], v[154:157], v[188:191], v[86:89]
	v_mfma_f32_16x16x32_bf16 v[78:81], v[166:169], v[188:191], v[78:81]
	v_mfma_f32_16x16x32_bf16 v[102:105], v[154:157], v[196:199], v[102:105]
	v_mfma_f32_16x16x32_bf16 v[94:97], v[166:169], v[196:199], v[94:97]
	v_mfma_f32_16x16x32_bf16 v[118:121], v[154:157], v[204:207], v[118:121]
	v_mfma_f32_16x16x32_bf16 v[106:109], v[166:169], v[204:207], v[106:109]
	v_mfma_f32_16x16x32_bf16 v[66:69], v[158:161], v[184:187], v[66:69]
	v_mfma_f32_16x16x32_bf16 v[58:61], v[170:173], v[184:187], v[58:61]
	v_mfma_f32_16x16x32_bf16 v[86:89], v[158:161], v[192:195], v[86:89]
	v_mfma_f32_16x16x32_bf16 v[78:81], v[170:173], v[192:195], v[78:81]
	v_mfma_f32_16x16x32_bf16 v[102:105], v[158:161], v[200:203], v[102:105]
	v_mfma_f32_16x16x32_bf16 v[94:97], v[170:173], v[200:203], v[94:97]
	v_mfma_f32_16x16x32_bf16 v[118:121], v[158:161], v[208:211], v[118:121]
	v_mfma_f32_16x16x32_bf16 v[106:109], v[170:173], v[208:211], v[106:109]
	s_barrier
	ds_read_b128 v[138:141], v135
	ds_read_b128 v[142:145], v135 offset:1024
	ds_read_b128 v[146:149], v135 offset:2048
	ds_read_b128 v[150:153], v135 offset:3072
	ds_read_b128 v[154:157], v136
	ds_read_b128 v[158:161], v136 offset:1024
	ds_read_b128 v[166:169], v136 offset:2048
	ds_read_b128 v[170:173], v136 offset:3072
	ds_read_b128 v[174:177], v134 offset:32768
	ds_read_b128 v[184:187], v134 offset:33792
	ds_read_b128 v[188:191], v134 offset:34816
	ds_read_b128 v[192:195], v134 offset:35840
	ds_read_b128 v[196:199], v134 offset:36864
	ds_read_b128 v[200:203], v134 offset:37888
	ds_read_b128 v[204:207], v134 offset:38912
	ds_read_b128 v[208:211], v134 offset:39936
	s_add_u32 s94, s0, 0xb0000
	s_addc_u32 s95, s1, 0
	s_mov_b32 s2, m0
	s_mov_b32 m0, s78
	s_nop 4
	global_load_lds_dwordx4 v130, s[94:95]
	s_mov_b32 m0, s2
	s_add_u32 s94, s0, 0x108000
	s_addc_u32 s95, s1, 0
	s_mov_b32 s2, m0
	s_mov_b32 m0, s80
	s_nop 4
	global_load_lds_dwordx4 v130, s[94:95]
	s_mov_b32 m0, s2
	s_waitcnt vmcnt(8)
	s_waitcnt lgkmcnt(0)
	s_barrier
	s_waitcnt lgkmcnt(7)
	v_mfma_f32_16x16x32_bf16 v[2:5], v[138:141], v[174:177], v[2:5]
	v_mfma_f32_16x16x32_bf16 v[6:9], v[146:149], v[174:177], v[6:9]
	s_waitcnt lgkmcnt(5)
	v_mfma_f32_16x16x32_bf16 v[30:33], v[138:141], v[188:191], v[30:33]
	v_mfma_f32_16x16x32_bf16 v[34:37], v[146:149], v[188:191], v[34:37]
	s_waitcnt lgkmcnt(3)
	v_mfma_f32_16x16x32_bf16 v[54:57], v[138:141], v[196:199], v[54:57]
	v_mfma_f32_16x16x32_bf16 v[50:53], v[146:149], v[196:199], v[50:53]
	s_waitcnt lgkmcnt(1)
	v_mfma_f32_16x16x32_bf16 v[70:73], v[138:141], v[204:207], v[70:73]
	v_mfma_f32_16x16x32_bf16 v[62:65], v[146:149], v[204:207], v[62:65]
	v_mfma_f32_16x16x32_bf16 v[2:5], v[142:145], v[184:187], v[2:5]
	v_mfma_f32_16x16x32_bf16 v[6:9], v[150:153], v[184:187], v[6:9]
	v_mfma_f32_16x16x32_bf16 v[30:33], v[142:145], v[192:195], v[30:33]
	v_mfma_f32_16x16x32_bf16 v[34:37], v[150:153], v[192:195], v[34:37]
	v_mfma_f32_16x16x32_bf16 v[54:57], v[142:145], v[200:203], v[54:57]
	v_mfma_f32_16x16x32_bf16 v[50:53], v[150:153], v[200:203], v[50:53]
	s_waitcnt lgkmcnt(0)
	v_mfma_f32_16x16x32_bf16 v[70:73], v[142:145], v[208:211], v[70:73]
	v_mfma_f32_16x16x32_bf16 v[62:65], v[150:153], v[208:211], v[62:65]
	v_mfma_f32_16x16x32_bf16 v[10:13], v[154:157], v[174:177], v[10:13]
	v_mfma_f32_16x16x32_bf16 v[14:17], v[166:169], v[174:177], v[14:17]
	v_mfma_f32_16x16x32_bf16 v[22:25], v[154:157], v[188:191], v[22:25]
	v_mfma_f32_16x16x32_bf16 v[18:21], v[166:169], v[188:191], v[18:21]
	v_mfma_f32_16x16x32_bf16 v[38:41], v[154:157], v[196:199], v[38:41]
	v_mfma_f32_16x16x32_bf16 v[26:29], v[166:169], v[196:199], v[26:29]
	v_mfma_f32_16x16x32_bf16 v[46:49], v[154:157], v[204:207], v[46:49]
	v_mfma_f32_16x16x32_bf16 v[42:45], v[166:169], v[204:207], v[42:45]
	v_mfma_f32_16x16x32_bf16 v[10:13], v[158:161], v[184:187], v[10:13]
	v_mfma_f32_16x16x32_bf16 v[14:17], v[170:173], v[184:187], v[14:17]
	v_mfma_f32_16x16x32_bf16 v[22:25], v[158:161], v[192:195], v[22:25]
	v_mfma_f32_16x16x32_bf16 v[18:21], v[170:173], v[192:195], v[18:21]
	v_mfma_f32_16x16x32_bf16 v[38:41], v[158:161], v[200:203], v[38:41]
	v_mfma_f32_16x16x32_bf16 v[26:29], v[170:173], v[200:203], v[26:29]
	v_mfma_f32_16x16x32_bf16 v[46:49], v[158:161], v[208:211], v[46:49]
	v_mfma_f32_16x16x32_bf16 v[42:45], v[170:173], v[208:211], v[42:45]
	s_barrier
	s_add_u32 s94, s54, 0x80
	s_addc_u32 s95, s55, 0
	ds_read_b128 v[174:177], v134 offset:49152
	ds_read_b128 v[184:187], v134 offset:50176
	ds_read_b128 v[188:191], v134 offset:51200
	ds_read_b128 v[192:195], v134 offset:52224
	ds_read_b128 v[196:199], v134 offset:53248
	ds_read_b128 v[200:203], v134 offset:54272
	ds_read_b128 v[204:207], v134 offset:55296
	ds_read_b128 v[208:211], v134 offset:56320
	s_mov_b32 s2, m0
	s_mov_b32 m0, s81
	s_nop 4
	global_load_lds_dwordx4 v131, s[94:95]
	s_mov_b32 m0, s2
	s_add_u32 s94, s54, 0x58080
	s_addc_u32 s95, s55, 0
	s_mov_b32 s2, m0
	s_mov_b32 m0, s84
	s_nop 4
	global_load_lds_dwordx4 v131, s[94:95]
	s_mov_b32 m0, s2
	s_add_u32 s94, s54, 0xb0080
	s_addc_u32 s95, s55, 0
	s_mov_b32 s2, m0
	s_mov_b32 m0, s87
	s_nop 4
	global_load_lds_dwordx4 v131, s[94:95]
	s_mov_b32 m0, s2
	s_add_u32 s54, s54, 0x108080
	s_addc_u32 s55, s55, 0
	s_mov_b32 s2, m0
	s_mov_b32 m0, s88
	s_nop 4
	global_load_lds_dwordx4 v131, s[54:55]
	s_mov_b32 m0, s2
	s_add_u32 s0, s0, 0x58080
	s_mov_b32 s2, m0
	s_mov_b32 m0, s85
	s_nop 4
	global_load_lds_dwordx4 v130, s[34:35]
	s_mov_b32 m0, s2
	s_addc_u32 s1, s1, 0
	s_mov_b32 s2, m0
	s_mov_b32 m0, s86
	s_nop 4
	global_load_lds_dwordx4 v130, s[0:1]
	s_mov_b32 m0, s2
	s_waitcnt vmcnt(8)
	s_waitcnt lgkmcnt(0)
	s_barrier
	s_waitcnt lgkmcnt(7)
	v_mfma_f32_16x16x32_bf16 v[82:85], v[138:141], v[174:177], v[82:85]
	v_mfma_f32_16x16x32_bf16 v[74:77], v[146:149], v[174:177], v[74:77]
	s_waitcnt lgkmcnt(5)
	v_mfma_f32_16x16x32_bf16 v[98:101], v[138:141], v[188:191], v[98:101]
	v_mfma_f32_16x16x32_bf16 v[90:93], v[146:149], v[188:191], v[90:93]
	s_waitcnt lgkmcnt(3)
	v_mfma_f32_16x16x32_bf16 v[114:117], v[138:141], v[196:199], v[114:117]
	v_mfma_f32_16x16x32_bf16 v[110:113], v[146:149], v[196:199], v[110:113]
	s_waitcnt lgkmcnt(1)
	v_mfma_f32_16x16x32_bf16 v[126:129], v[138:141], v[204:207], v[126:129]
	v_mfma_f32_16x16x32_bf16 v[122:125], v[146:149], v[204:207], v[122:125]
	v_mfma_f32_16x16x32_bf16 v[82:85], v[142:145], v[184:187], v[82:85]
	v_mfma_f32_16x16x32_bf16 v[74:77], v[150:153], v[184:187], v[74:77]
	v_mfma_f32_16x16x32_bf16 v[98:101], v[142:145], v[192:195], v[98:101]
	v_mfma_f32_16x16x32_bf16 v[90:93], v[150:153], v[192:195], v[90:93]
	v_mfma_f32_16x16x32_bf16 v[114:117], v[142:145], v[200:203], v[114:117]
	v_mfma_f32_16x16x32_bf16 v[110:113], v[150:153], v[200:203], v[110:113]
	s_waitcnt lgkmcnt(0)
	v_mfma_f32_16x16x32_bf16 v[126:129], v[142:145], v[208:211], v[126:129]
	v_mfma_f32_16x16x32_bf16 v[122:125], v[150:153], v[208:211], v[122:125]
	v_mfma_f32_16x16x32_bf16 v[66:69], v[154:157], v[174:177], v[66:69]
	v_mfma_f32_16x16x32_bf16 v[58:61], v[166:169], v[174:177], v[58:61]
	v_mfma_f32_16x16x32_bf16 v[86:89], v[154:157], v[188:191], v[86:89]
	v_mfma_f32_16x16x32_bf16 v[78:81], v[166:169], v[188:191], v[78:81]
	v_mfma_f32_16x16x32_bf16 v[102:105], v[154:157], v[196:199], v[102:105]
	v_mfma_f32_16x16x32_bf16 v[94:97], v[166:169], v[196:199], v[94:97]
	v_mfma_f32_16x16x32_bf16 v[118:121], v[154:157], v[204:207], v[118:121]
	v_mfma_f32_16x16x32_bf16 v[106:109], v[166:169], v[204:207], v[106:109]
	v_mfma_f32_16x16x32_bf16 v[66:69], v[158:161], v[184:187], v[66:69]
	v_mfma_f32_16x16x32_bf16 v[58:61], v[170:173], v[184:187], v[58:61]
	v_mfma_f32_16x16x32_bf16 v[86:89], v[158:161], v[192:195], v[86:89]
	v_mfma_f32_16x16x32_bf16 v[78:81], v[170:173], v[192:195], v[78:81]
	v_mfma_f32_16x16x32_bf16 v[102:105], v[158:161], v[200:203], v[102:105]
	v_mfma_f32_16x16x32_bf16 v[94:97], v[170:173], v[200:203], v[94:97]
	v_mfma_f32_16x16x32_bf16 v[118:121], v[158:161], v[208:211], v[118:121]
	v_mfma_f32_16x16x32_bf16 v[106:109], v[170:173], v[208:211], v[106:109]
	s_barrier
	s_add_i32 s92, s92, 2
	s_add_u32 s52, s52, 0x100
	s_addc_u32 s53, s53, 0
	s_cmp_lt_u32 s92, 42
	s_cbranch_scc1 .LBB0_236
	s_waitcnt vmcnt(0)
	s_cmpk_gt_u32 s63, 0xff
	s_cbranch_scc1 .LBB0_239
	s_barrier

.LBB0_419:
	v_add_u32_e32 v134, 0x10000, v145
	ds_read_b128 v[136:139], v134
	ds_read_b128 v[148:151], v134 offset:1024
	ds_read_b128 v[152:155], v134 offset:2048
	ds_read_b128 v[156:159], v134 offset:3072
	v_add_u32_e32 v134, 0x14000, v145
	ds_read_b128 v[160:163], v134
	ds_read_b128 v[164:167], v134 offset:1024
	ds_read_b128 v[168:171], v134 offset:2048
	ds_read_b128 v[172:175], v134 offset:3072
	s_add_u32 s0, s50, 0x100
	s_addc_u32 s1, s51, 0
	s_cmp_eq_u32 s81, 12
	s_cselect_b32 s34, s15, s0
	s_cselect_b32 s35, s14, s1
	s_cselect_b32 s54, s37, s79
	s_cselect_b32 s55, s27, s80
	s_add_u32 s52, s34, 0x80
	s_addc_u32 s53, s35, 0
	ds_read_b128 v[176:179], v146
	ds_read_b128 v[180:183], v146 offset:1024
	ds_read_b128 v[184:187], v146 offset:2048
	ds_read_b128 v[188:191], v146 offset:3072
	ds_read_b128 v[192:195], v146 offset:4096
	ds_read_b128 v[196:199], v146 offset:5120
	ds_read_b128 v[200:203], v146 offset:6144
	ds_read_b128 v[204:207], v146 offset:7168
	s_add_u32 s84, s50, 0x40080
	s_addc_u32 s85, s51, 0
	s_mov_b32 s2, m0
	s_mov_b32 m0, s76
	s_nop 4
	global_load_lds_dwordx4 v1, s[84:85]
	s_mov_b32 m0, s2
	s_add_u32 s50, s50, 0x60080
	s_addc_u32 s51, s51, 0
	s_add_i32 s2, s45, 0xe000
	s_mov_b32 s3, m0
	s_mov_b32 m0, s2
	s_nop 4
	global_load_lds_dwordx4 v1, s[50:51]
	s_mov_b32 m0, s3
	s_waitcnt vmcnt(8)
	s_waitcnt lgkmcnt(0)
	s_barrier
	s_waitcnt lgkmcnt(7)
	v_mfma_f32_16x16x32_bf16 v[122:125], v[136:139], v[176:179], v[122:125]
	v_mfma_f32_16x16x32_bf16 v[114:117], v[152:155], v[176:179], v[114:117]
	s_waitcnt lgkmcnt(5)
	v_mfma_f32_16x16x32_bf16 v[106:109], v[136:139], v[184:187], v[106:109]
	v_mfma_f32_16x16x32_bf16 v[98:101], v[152:155], v[184:187], v[98:101]
	s_waitcnt lgkmcnt(3)
	v_mfma_f32_16x16x32_bf16 v[90:93], v[136:139], v[192:195], v[90:93]
	v_mfma_f32_16x16x32_bf16 v[82:85], v[152:155], v[192:195], v[82:85]
	s_waitcnt lgkmcnt(1)
	v_mfma_f32_16x16x32_bf16 v[74:77], v[136:139], v[200:203], v[74:77]
	v_mfma_f32_16x16x32_bf16 v[66:69], v[152:155], v[200:203], v[66:69]
	v_mfma_f32_16x16x32_bf16 v[122:125], v[148:151], v[180:183], v[122:125]
	v_mfma_f32_16x16x32_bf16 v[114:117], v[156:159], v[180:183], v[114:117]
	v_mfma_f32_16x16x32_bf16 v[106:109], v[148:151], v[188:191], v[106:109]
	v_mfma_f32_16x16x32_bf16 v[98:101], v[156:159], v[188:191], v[98:101]
	v_mfma_f32_16x16x32_bf16 v[90:93], v[148:151], v[196:199], v[90:93]
	v_mfma_f32_16x16x32_bf16 v[82:85], v[156:159], v[196:199], v[82:85]
	s_waitcnt lgkmcnt(0)
	v_mfma_f32_16x16x32_bf16 v[74:77], v[148:151], v[204:207], v[74:77]
	v_mfma_f32_16x16x32_bf16 v[66:69], v[156:159], v[204:207], v[66:69]
	v_mfma_f32_16x16x32_bf16 v[126:129], v[160:163], v[176:179], v[126:129]
	v_mfma_f32_16x16x32_bf16 v[118:121], v[168:171], v[176:179], v[118:121]
	v_mfma_f32_16x16x32_bf16 v[110:113], v[160:163], v[184:187], v[110:113]
	v_mfma_f32_16x16x32_bf16 v[102:105], v[168:171], v[184:187], v[102:105]
	v_mfma_f32_16x16x32_bf16 v[94:97], v[160:163], v[192:195], v[94:97]
	v_mfma_f32_16x16x32_bf16 v[86:89], v[168:171], v[192:195], v[86:89]
	v_mfma_f32_16x16x32_bf16 v[78:81], v[160:163], v[200:203], v[78:81]
	v_mfma_f32_16x16x32_bf16 v[70:73], v[168:171], v[200:203], v[70:73]
	v_mfma_f32_16x16x32_bf16 v[126:129], v[164:167], v[180:183], v[126:129]
	v_mfma_f32_16x16x32_bf16 v[118:121], v[172:175], v[180:183], v[118:121]
	v_mfma_f32_16x16x32_bf16 v[110:113], v[164:167], v[188:191], v[110:113]
	v_mfma_f32_16x16x32_bf16 v[102:105], v[172:175], v[188:191], v[102:105]
	v_mfma_f32_16x16x32_bf16 v[94:97], v[164:167], v[196:199], v[94:97]
	v_mfma_f32_16x16x32_bf16 v[86:89], v[172:175], v[196:199], v[86:89]
	v_mfma_f32_16x16x32_bf16 v[78:81], v[164:167], v[204:207], v[78:81]
	v_mfma_f32_16x16x32_bf16 v[70:73], v[172:175], v[204:207], v[70:73]
	s_barrier
	s_add_u32 s50, s54, 0x20000
	ds_read_b128 v[176:179], v146 offset:16384
	ds_read_b128 v[180:183], v146 offset:17408
	ds_read_b128 v[184:187], v146 offset:18432
	ds_read_b128 v[188:191], v146 offset:19456
	ds_read_b128 v[192:195], v146 offset:20480
	ds_read_b128 v[196:199], v146 offset:21504
	ds_read_b128 v[200:203], v146 offset:22528
	ds_read_b128 v[204:207], v146 offset:23552
	s_mov_b32 s2, m0
	s_mov_b32 m0, s58
	s_nop 4
	global_load_lds_dwordx4 v142, s[54:55]
	s_mov_b32 m0, s2
	s_addc_u32 s51, s55, 0
	s_mov_b32 s2, m0
	s_mov_b32 m0, s59
	s_nop 4
	global_load_lds_dwordx4 v142, s[50:51]
	s_mov_b32 m0, s2
	s_add_u32 s50, s54, 0x40000
	s_addc_u32 s51, s55, 0
	s_mov_b32 s2, m0
	s_mov_b32 m0, s60
	s_nop 4
	global_load_lds_dwordx4 v142, s[50:51]
	s_mov_b32 m0, s2
	s_add_u32 s50, s54, 0x60000
	s_addc_u32 s51, s55, 0
	s_mov_b32 s2, m0
	s_mov_b32 m0, s61
	s_nop 4
	global_load_lds_dwordx4 v142, s[50:51]
	s_mov_b32 m0, s2
	s_add_u32 s50, s34, 0x20000
	s_mov_b32 s2, m0
	s_mov_b32 m0, s45
	s_nop 4
	global_load_lds_dwordx4 v1, s[34:35]
	s_mov_b32 m0, s2
	s_addc_u32 s51, s35, 0
	s_mov_b32 s2, m0
	s_mov_b32 m0, s62
	s_nop 4
	global_load_lds_dwordx4 v1, s[50:51]
	s_mov_b32 m0, s2
	s_waitcnt vmcnt(8)
	s_waitcnt lgkmcnt(0)
	s_barrier
	s_waitcnt lgkmcnt(7)
	v_mfma_f32_16x16x32_bf16 v[58:61], v[136:139], v[176:179], v[58:61]
	v_mfma_f32_16x16x32_bf16 v[50:53], v[152:155], v[176:179], v[50:53]
	s_waitcnt lgkmcnt(5)
	v_mfma_f32_16x16x32_bf16 v[42:45], v[136:139], v[184:187], v[42:45]
	v_mfma_f32_16x16x32_bf16 v[34:37], v[152:155], v[184:187], v[34:37]
	s_waitcnt lgkmcnt(3)
	v_mfma_f32_16x16x32_bf16 v[26:29], v[136:139], v[192:195], v[26:29]
	v_mfma_f32_16x16x32_bf16 v[18:21], v[152:155], v[192:195], v[18:21]
	s_waitcnt lgkmcnt(1)
	v_mfma_f32_16x16x32_bf16 v[10:13], v[136:139], v[200:203], v[10:13]
	v_mfma_f32_16x16x32_bf16 v[2:5], v[152:155], v[200:203], v[2:5]
	v_mfma_f32_16x16x32_bf16 v[58:61], v[148:151], v[180:183], v[58:61]
	v_mfma_f32_16x16x32_bf16 v[50:53], v[156:159], v[180:183], v[50:53]
	v_mfma_f32_16x16x32_bf16 v[42:45], v[148:151], v[188:191], v[42:45]
	v_mfma_f32_16x16x32_bf16 v[34:37], v[156:159], v[188:191], v[34:37]
	v_mfma_f32_16x16x32_bf16 v[26:29], v[148:151], v[196:199], v[26:29]
	v_mfma_f32_16x16x32_bf16 v[18:21], v[156:159], v[196:199], v[18:21]
	s_waitcnt lgkmcnt(0)
	v_mfma_f32_16x16x32_bf16 v[10:13], v[148:151], v[204:207], v[10:13]
	v_mfma_f32_16x16x32_bf16 v[2:5], v[156:159], v[204:207], v[2:5]
	v_mfma_f32_16x16x32_bf16 v[62:65], v[160:163], v[176:179], v[62:65]
	v_mfma_f32_16x16x32_bf16 v[54:57], v[168:171], v[176:179], v[54:57]
	v_mfma_f32_16x16x32_bf16 v[46:49], v[160:163], v[184:187], v[46:49]
	v_mfma_f32_16x16x32_bf16 v[38:41], v[168:171], v[184:187], v[38:41]
	v_mfma_f32_16x16x32_bf16 v[30:33], v[160:163], v[192:195], v[30:33]
	v_mfma_f32_16x16x32_bf16 v[22:25], v[168:171], v[192:195], v[22:25]
	v_mfma_f32_16x16x32_bf16 v[14:17], v[160:163], v[200:203], v[14:17]
	v_mfma_f32_16x16x32_bf16 v[6:9], v[168:171], v[200:203], v[6:9]
	v_mfma_f32_16x16x32_bf16 v[62:65], v[164:167], v[180:183], v[62:65]
	v_mfma_f32_16x16x32_bf16 v[54:57], v[172:175], v[180:183], v[54:57]
	v_mfma_f32_16x16x32_bf16 v[46:49], v[164:167], v[188:191], v[46:49]
	v_mfma_f32_16x16x32_bf16 v[38:41], v[172:175], v[188:191], v[38:41]
	v_mfma_f32_16x16x32_bf16 v[30:33], v[164:167], v[196:199], v[30:33]
	v_mfma_f32_16x16x32_bf16 v[22:25], v[172:175], v[196:199], v[22:25]
	v_mfma_f32_16x16x32_bf16 v[14:17], v[164:167], v[204:207], v[14:17]
	v_mfma_f32_16x16x32_bf16 v[6:9], v[172:175], v[204:207], v[6:9]
	s_barrier
	v_add_u32_e32 v134, 0x18000, v145
	ds_read_b128 v[136:139], v134
	ds_read_b128 v[148:151], v134 offset:1024
	ds_read_b128 v[152:155], v134 offset:2048
	ds_read_b128 v[156:159], v134 offset:3072
	v_add_u32_e32 v134, 0x1c000, v145
	ds_read_b128 v[160:163], v134
	ds_read_b128 v[164:167], v134 offset:1024
	ds_read_b128 v[168:171], v134 offset:2048
	ds_read_b128 v[172:175], v134 offset:3072
	ds_read_b128 v[176:179], v146 offset:32768
	ds_read_b128 v[180:183], v146 offset:33792
	ds_read_b128 v[184:187], v146 offset:34816
	ds_read_b128 v[188:191], v146 offset:35840
	ds_read_b128 v[192:195], v146 offset:36864
	ds_read_b128 v[196:199], v146 offset:37888
	ds_read_b128 v[200:203], v146 offset:38912
	ds_read_b128 v[204:207], v146 offset:39936
	s_add_u32 s50, s34, 0x40000
	s_addc_u32 s51, s35, 0
	s_mov_b32 s2, m0
	s_mov_b32 m0, s63
	s_nop 4
	global_load_lds_dwordx4 v1, s[50:51]
	s_mov_b32 m0, s2
	s_add_u32 s50, s34, 0x60000
	s_addc_u32 s51, s35, 0
	s_mov_b32 s2, m0
	s_mov_b32 m0, s64
	s_nop 4
	global_load_lds_dwordx4 v1, s[50:51]
	s_mov_b32 m0, s2
	s_waitcnt vmcnt(8)
	s_waitcnt lgkmcnt(0)
	s_barrier
	s_waitcnt lgkmcnt(7)
	v_mfma_f32_16x16x32_bf16 v[122:125], v[136:139], v[176:179], v[122:125]
	v_mfma_f32_16x16x32_bf16 v[114:117], v[152:155], v[176:179], v[114:117]
	s_waitcnt lgkmcnt(5)
	v_mfma_f32_16x16x32_bf16 v[106:109], v[136:139], v[184:187], v[106:109]
	v_mfma_f32_16x16x32_bf16 v[98:101], v[152:155], v[184:187], v[98:101]
	s_waitcnt lgkmcnt(3)
	v_mfma_f32_16x16x32_bf16 v[90:93], v[136:139], v[192:195], v[90:93]
	v_mfma_f32_16x16x32_bf16 v[82:85], v[152:155], v[192:195], v[82:85]
	s_waitcnt lgkmcnt(1)
	v_mfma_f32_16x16x32_bf16 v[74:77], v[136:139], v[200:203], v[74:77]
	v_mfma_f32_16x16x32_bf16 v[66:69], v[152:155], v[200:203], v[66:69]
	v_mfma_f32_16x16x32_bf16 v[122:125], v[148:151], v[180:183], v[122:125]
	v_mfma_f32_16x16x32_bf16 v[114:117], v[156:159], v[180:183], v[114:117]
	v_mfma_f32_16x16x32_bf16 v[106:109], v[148:151], v[188:191], v[106:109]
	v_mfma_f32_16x16x32_bf16 v[98:101], v[156:159], v[188:191], v[98:101]
	v_mfma_f32_16x16x32_bf16 v[90:93], v[148:151], v[196:199], v[90:93]
	v_mfma_f32_16x16x32_bf16 v[82:85], v[156:159], v[196:199], v[82:85]
	s_waitcnt lgkmcnt(0)
	v_mfma_f32_16x16x32_bf16 v[74:77], v[148:151], v[204:207], v[74:77]
	v_mfma_f32_16x16x32_bf16 v[66:69], v[156:159], v[204:207], v[66:69]
	v_mfma_f32_16x16x32_bf16 v[126:129], v[160:163], v[176:179], v[126:129]
	v_mfma_f32_16x16x32_bf16 v[118:121], v[168:171], v[176:179], v[118:121]
	v_mfma_f32_16x16x32_bf16 v[110:113], v[160:163], v[184:187], v[110:113]
	v_mfma_f32_16x16x32_bf16 v[102:105], v[168:171], v[184:187], v[102:105]
	v_mfma_f32_16x16x32_bf16 v[94:97], v[160:163], v[192:195], v[94:97]
	v_mfma_f32_16x16x32_bf16 v[86:89], v[168:171], v[192:195], v[86:89]
	v_mfma_f32_16x16x32_bf16 v[78:81], v[160:163], v[200:203], v[78:81]
	v_mfma_f32_16x16x32_bf16 v[70:73], v[168:171], v[200:203], v[70:73]
	v_mfma_f32_16x16x32_bf16 v[126:129], v[164:167], v[180:183], v[126:129]
	v_mfma_f32_16x16x32_bf16 v[118:121], v[172:175], v[180:183], v[118:121]
	v_mfma_f32_16x16x32_bf16 v[110:113], v[164:167], v[188:191], v[110:113]
	v_mfma_f32_16x16x32_bf16 v[102:105], v[172:175], v[188:191], v[102:105]
	v_mfma_f32_16x16x32_bf16 v[94:97], v[164:167], v[196:199], v[94:97]
	v_mfma_f32_16x16x32_bf16 v[86:89], v[172:175], v[196:199], v[86:89]
	v_mfma_f32_16x16x32_bf16 v[78:81], v[164:167], v[204:207], v[78:81]
	v_mfma_f32_16x16x32_bf16 v[70:73], v[172:175], v[204:207], v[70:73]
	s_barrier
	s_add_u32 s50, s54, 0x80
	s_addc_u32 s51, s55, 0
	ds_read_b128 v[176:179], v146 offset:49152
	ds_read_b128 v[180:183], v146 offset:50176
	ds_read_b128 v[184:187], v146 offset:51200
	ds_read_b128 v[188:191], v146 offset:52224
	ds_read_b128 v[192:195], v146 offset:53248
	ds_read_b128 v[196:199], v146 offset:54272
	ds_read_b128 v[200:203], v146 offset:55296
	ds_read_b128 v[204:207], v146 offset:56320
	s_mov_b32 s2, m0
	s_mov_b32 m0, s65
	s_nop 4
	global_load_lds_dwordx4 v142, s[50:51]
	s_mov_b32 m0, s2
	s_add_u32 s50, s54, 0x20080
	s_addc_u32 s51, s55, 0
	s_mov_b32 s2, m0
	s_mov_b32 m0, s66
	s_nop 4
	global_load_lds_dwordx4 v142, s[50:51]
	s_mov_b32 m0, s2
	s_add_u32 s50, s54, 0x40080
	s_addc_u32 s51, s55, 0
	s_mov_b32 s2, m0
	s_mov_b32 m0, s74
	s_nop 4
	global_load_lds_dwordx4 v142, s[50:51]
	s_mov_b32 m0, s2
	s_add_u32 s50, s54, 0x60080
	s_addc_u32 s51, s55, 0
	s_mov_b32 s2, m0
	s_mov_b32 m0, s75
	s_nop 4
	global_load_lds_dwordx4 v142, s[50:51]
	s_mov_b32 m0, s2
	s_add_u32 s34, s34, 0x20080
	s_mov_b32 s2, m0
	s_mov_b32 m0, s67
	s_nop 4
	global_load_lds_dwordx4 v1, s[52:53]
	s_mov_b32 m0, s2
	s_addc_u32 s35, s35, 0
	s_mov_b32 s2, m0
	s_mov_b32 m0, s73
	s_nop 4
	global_load_lds_dwordx4 v1, s[34:35]
	s_mov_b32 m0, s2
	s_waitcnt vmcnt(8)
	s_waitcnt lgkmcnt(0)
	s_barrier
	s_waitcnt lgkmcnt(7)
	v_mfma_f32_16x16x32_bf16 v[58:61], v[136:139], v[176:179], v[58:61]
	v_mfma_f32_16x16x32_bf16 v[50:53], v[152:155], v[176:179], v[50:53]
	s_waitcnt lgkmcnt(5)
	v_mfma_f32_16x16x32_bf16 v[42:45], v[136:139], v[184:187], v[42:45]
	v_mfma_f32_16x16x32_bf16 v[34:37], v[152:155], v[184:187], v[34:37]
	s_waitcnt lgkmcnt(3)
	v_mfma_f32_16x16x32_bf16 v[26:29], v[136:139], v[192:195], v[26:29]
	v_mfma_f32_16x16x32_bf16 v[18:21], v[152:155], v[192:195], v[18:21]
	s_waitcnt lgkmcnt(1)
	v_mfma_f32_16x16x32_bf16 v[10:13], v[136:139], v[200:203], v[10:13]
	v_mfma_f32_16x16x32_bf16 v[2:5], v[152:155], v[200:203], v[2:5]
	v_mfma_f32_16x16x32_bf16 v[58:61], v[148:151], v[180:183], v[58:61]
	v_mfma_f32_16x16x32_bf16 v[50:53], v[156:159], v[180:183], v[50:53]
	v_mfma_f32_16x16x32_bf16 v[42:45], v[148:151], v[188:191], v[42:45]
	v_mfma_f32_16x16x32_bf16 v[34:37], v[156:159], v[188:191], v[34:37]
	v_mfma_f32_16x16x32_bf16 v[26:29], v[148:151], v[196:199], v[26:29]
	v_mfma_f32_16x16x32_bf16 v[18:21], v[156:159], v[196:199], v[18:21]
	s_waitcnt lgkmcnt(0)
	v_mfma_f32_16x16x32_bf16 v[10:13], v[148:151], v[204:207], v[10:13]
	v_mfma_f32_16x16x32_bf16 v[2:5], v[156:159], v[204:207], v[2:5]
	v_mfma_f32_16x16x32_bf16 v[62:65], v[160:163], v[176:179], v[62:65]
	v_mfma_f32_16x16x32_bf16 v[54:57], v[168:171], v[176:179], v[54:57]
	v_mfma_f32_16x16x32_bf16 v[46:49], v[160:163], v[184:187], v[46:49]
	v_mfma_f32_16x16x32_bf16 v[38:41], v[168:171], v[184:187], v[38:41]
	v_mfma_f32_16x16x32_bf16 v[30:33], v[160:163], v[192:195], v[30:33]
	v_mfma_f32_16x16x32_bf16 v[22:25], v[168:171], v[192:195], v[22:25]
	v_mfma_f32_16x16x32_bf16 v[14:17], v[160:163], v[200:203], v[14:17]
	v_mfma_f32_16x16x32_bf16 v[6:9], v[168:171], v[200:203], v[6:9]
	v_mfma_f32_16x16x32_bf16 v[62:65], v[164:167], v[180:183], v[62:65]
	v_mfma_f32_16x16x32_bf16 v[54:57], v[172:175], v[180:183], v[54:57]
	v_mfma_f32_16x16x32_bf16 v[46:49], v[164:167], v[188:191], v[46:49]
	v_mfma_f32_16x16x32_bf16 v[38:41], v[172:175], v[188:191], v[38:41]
	v_mfma_f32_16x16x32_bf16 v[30:33], v[164:167], v[196:199], v[30:33]
	v_mfma_f32_16x16x32_bf16 v[22:25], v[172:175], v[196:199], v[22:25]
	v_mfma_f32_16x16x32_bf16 v[14:17], v[164:167], v[204:207], v[14:17]
	v_mfma_f32_16x16x32_bf16 v[6:9], v[172:175], v[204:207], v[6:9]
	s_barrier
	s_add_i32 s81, s81, 2
	s_add_u32 s79, s79, 0x100
	s_addc_u32 s80, s80, 0
	s_cmp_gt_u32 s81, 13
	s_mov_b64 s[50:51], s[0:1]
	s_cbranch_scc0 .LBB0_419
	s_and_b64 vcc, exec, s[24:25]
	s_cbranch_vccz .LBB0_422
	s_barrier

.LBB0_557:
	v_add_u32_e32 v134, 0x10000, v139
	ds_read_b128 v[142:145], v134
	ds_read_b128 v[146:149], v134 offset:1024
	ds_read_b128 v[150:153], v134 offset:2048
	ds_read_b128 v[154:157], v134 offset:3072
	v_add_u32_e32 v134, 0x14000, v139
	ds_read_b128 v[158:161], v134
	ds_read_b128 v[162:165], v134 offset:1024
	ds_read_b128 v[166:169], v134 offset:2048
	ds_read_b128 v[170:173], v134 offset:3072
	s_add_u32 s0, s44, 0x100
	s_addc_u32 s1, s45, 0
	s_cmp_eq_u32 s81, 12
	s_cselect_b32 s34, s15, s0
	s_cselect_b32 s35, s14, s1
	s_cselect_b32 s52, s27, s79
	s_cselect_b32 s53, s25, s80
	s_add_u32 s50, s34, 0x80
	s_addc_u32 s51, s35, 0
	ds_read_b128 v[174:177], v140
	ds_read_b128 v[178:181], v140 offset:1024
	ds_read_b128 v[182:185], v140 offset:2048
	ds_read_b128 v[186:189], v140 offset:3072
	ds_read_b128 v[190:193], v140 offset:4096
	ds_read_b128 v[194:197], v140 offset:5120
	ds_read_b128 v[198:201], v140 offset:6144
	ds_read_b128 v[202:205], v140 offset:7168
	s_add_u32 s84, s44, 0x40080
	s_addc_u32 s85, s45, 0
	s_mov_b32 s2, m0
	s_mov_b32 m0, s74
	s_nop 4
	global_load_lds_dwordx4 v1, s[84:85]
	s_mov_b32 m0, s2
	s_add_u32 s44, s44, 0x60080
	s_addc_u32 s45, s45, 0
	s_add_i32 s2, s43, 0xe000
	s_mov_b32 s3, m0
	s_mov_b32 m0, s2
	s_nop 4
	global_load_lds_dwordx4 v1, s[44:45]
	s_mov_b32 m0, s3
	s_waitcnt vmcnt(8)
	s_waitcnt lgkmcnt(0)
	s_barrier
	s_waitcnt lgkmcnt(7)
	v_mfma_f32_16x16x32_bf16 v[122:125], v[142:145], v[174:177], v[122:125]
	v_mfma_f32_16x16x32_bf16 v[114:117], v[150:153], v[174:177], v[114:117]
	s_waitcnt lgkmcnt(5)
	v_mfma_f32_16x16x32_bf16 v[106:109], v[142:145], v[182:185], v[106:109]
	v_mfma_f32_16x16x32_bf16 v[98:101], v[150:153], v[182:185], v[98:101]
	s_waitcnt lgkmcnt(3)
	v_mfma_f32_16x16x32_bf16 v[90:93], v[142:145], v[190:193], v[90:93]
	v_mfma_f32_16x16x32_bf16 v[82:85], v[150:153], v[190:193], v[82:85]
	s_waitcnt lgkmcnt(1)
	v_mfma_f32_16x16x32_bf16 v[74:77], v[142:145], v[198:201], v[74:77]
	v_mfma_f32_16x16x32_bf16 v[66:69], v[150:153], v[198:201], v[66:69]
	v_mfma_f32_16x16x32_bf16 v[122:125], v[146:149], v[178:181], v[122:125]
	v_mfma_f32_16x16x32_bf16 v[114:117], v[154:157], v[178:181], v[114:117]
	v_mfma_f32_16x16x32_bf16 v[106:109], v[146:149], v[186:189], v[106:109]
	v_mfma_f32_16x16x32_bf16 v[98:101], v[154:157], v[186:189], v[98:101]
	v_mfma_f32_16x16x32_bf16 v[90:93], v[146:149], v[194:197], v[90:93]
	v_mfma_f32_16x16x32_bf16 v[82:85], v[154:157], v[194:197], v[82:85]
	s_waitcnt lgkmcnt(0)
	v_mfma_f32_16x16x32_bf16 v[74:77], v[146:149], v[202:205], v[74:77]
	v_mfma_f32_16x16x32_bf16 v[66:69], v[154:157], v[202:205], v[66:69]
	v_mfma_f32_16x16x32_bf16 v[126:129], v[158:161], v[174:177], v[126:129]
	v_mfma_f32_16x16x32_bf16 v[118:121], v[166:169], v[174:177], v[118:121]
	v_mfma_f32_16x16x32_bf16 v[110:113], v[158:161], v[182:185], v[110:113]
	v_mfma_f32_16x16x32_bf16 v[102:105], v[166:169], v[182:185], v[102:105]
	v_mfma_f32_16x16x32_bf16 v[94:97], v[158:161], v[190:193], v[94:97]
	v_mfma_f32_16x16x32_bf16 v[86:89], v[166:169], v[190:193], v[86:89]
	v_mfma_f32_16x16x32_bf16 v[78:81], v[158:161], v[198:201], v[78:81]
	v_mfma_f32_16x16x32_bf16 v[70:73], v[166:169], v[198:201], v[70:73]
	v_mfma_f32_16x16x32_bf16 v[126:129], v[162:165], v[178:181], v[126:129]
	v_mfma_f32_16x16x32_bf16 v[118:121], v[170:173], v[178:181], v[118:121]
	v_mfma_f32_16x16x32_bf16 v[110:113], v[162:165], v[186:189], v[110:113]
	v_mfma_f32_16x16x32_bf16 v[102:105], v[170:173], v[186:189], v[102:105]
	v_mfma_f32_16x16x32_bf16 v[94:97], v[162:165], v[194:197], v[94:97]
	v_mfma_f32_16x16x32_bf16 v[86:89], v[170:173], v[194:197], v[86:89]
	v_mfma_f32_16x16x32_bf16 v[78:81], v[162:165], v[202:205], v[78:81]
	v_mfma_f32_16x16x32_bf16 v[70:73], v[170:173], v[202:205], v[70:73]
	s_barrier
	s_add_u32 s44, s52, 0x20000
	ds_read_b128 v[174:177], v140 offset:16384
	ds_read_b128 v[178:181], v140 offset:17408
	ds_read_b128 v[182:185], v140 offset:18432
	ds_read_b128 v[186:189], v140 offset:19456
	ds_read_b128 v[190:193], v140 offset:20480
	ds_read_b128 v[194:197], v140 offset:21504
	ds_read_b128 v[198:201], v140 offset:22528
	ds_read_b128 v[202:205], v140 offset:23552
	s_mov_b32 s2, m0
	s_mov_b32 m0, s56
	s_nop 4
	global_load_lds_dwordx4 v136, s[52:53]
	s_mov_b32 m0, s2
	s_addc_u32 s45, s53, 0
	s_mov_b32 s2, m0
	s_mov_b32 m0, s57
	s_nop 4
	global_load_lds_dwordx4 v136, s[44:45]
	s_mov_b32 m0, s2
	s_add_u32 s44, s52, 0x40000
	s_addc_u32 s45, s53, 0
	s_mov_b32 s2, m0
	s_mov_b32 m0, s58
	s_nop 4
	global_load_lds_dwordx4 v136, s[44:45]
	s_mov_b32 m0, s2
	s_add_u32 s44, s52, 0x60000
	s_addc_u32 s45, s53, 0
	s_mov_b32 s2, m0
	s_mov_b32 m0, s59
	s_nop 4
	global_load_lds_dwordx4 v136, s[44:45]
	s_mov_b32 m0, s2
	s_add_u32 s44, s34, 0x20000
	s_mov_b32 s2, m0
	s_mov_b32 m0, s43
	s_nop 4
	global_load_lds_dwordx4 v1, s[34:35]
	s_mov_b32 m0, s2
	s_addc_u32 s45, s35, 0
	s_mov_b32 s2, m0
	s_mov_b32 m0, s60
	s_nop 4
	global_load_lds_dwordx4 v1, s[44:45]
	s_mov_b32 m0, s2
	s_waitcnt vmcnt(8)
	s_waitcnt lgkmcnt(0)
	s_barrier
	s_waitcnt lgkmcnt(7)
	v_mfma_f32_16x16x32_bf16 v[58:61], v[142:145], v[174:177], v[58:61]
	v_mfma_f32_16x16x32_bf16 v[50:53], v[150:153], v[174:177], v[50:53]
	s_waitcnt lgkmcnt(5)
	v_mfma_f32_16x16x32_bf16 v[42:45], v[142:145], v[182:185], v[42:45]
	v_mfma_f32_16x16x32_bf16 v[34:37], v[150:153], v[182:185], v[34:37]
	s_waitcnt lgkmcnt(3)
	v_mfma_f32_16x16x32_bf16 v[26:29], v[142:145], v[190:193], v[26:29]
	v_mfma_f32_16x16x32_bf16 v[18:21], v[150:153], v[190:193], v[18:21]
	s_waitcnt lgkmcnt(1)
	v_mfma_f32_16x16x32_bf16 v[10:13], v[142:145], v[198:201], v[10:13]
	v_mfma_f32_16x16x32_bf16 v[6:9], v[150:153], v[198:201], v[6:9]
	v_mfma_f32_16x16x32_bf16 v[58:61], v[146:149], v[178:181], v[58:61]
	v_mfma_f32_16x16x32_bf16 v[50:53], v[154:157], v[178:181], v[50:53]
	v_mfma_f32_16x16x32_bf16 v[42:45], v[146:149], v[186:189], v[42:45]
	v_mfma_f32_16x16x32_bf16 v[34:37], v[154:157], v[186:189], v[34:37]
	v_mfma_f32_16x16x32_bf16 v[26:29], v[146:149], v[194:197], v[26:29]
	v_mfma_f32_16x16x32_bf16 v[18:21], v[154:157], v[194:197], v[18:21]
	s_waitcnt lgkmcnt(0)
	v_mfma_f32_16x16x32_bf16 v[10:13], v[146:149], v[202:205], v[10:13]
	v_mfma_f32_16x16x32_bf16 v[6:9], v[154:157], v[202:205], v[6:9]
	v_mfma_f32_16x16x32_bf16 v[62:65], v[158:161], v[174:177], v[62:65]
	v_mfma_f32_16x16x32_bf16 v[54:57], v[166:169], v[174:177], v[54:57]
	v_mfma_f32_16x16x32_bf16 v[46:49], v[158:161], v[182:185], v[46:49]
	v_mfma_f32_16x16x32_bf16 v[38:41], v[166:169], v[182:185], v[38:41]
	v_mfma_f32_16x16x32_bf16 v[30:33], v[158:161], v[190:193], v[30:33]
	v_mfma_f32_16x16x32_bf16 v[22:25], v[166:169], v[190:193], v[22:25]
	v_mfma_f32_16x16x32_bf16 v[14:17], v[158:161], v[198:201], v[14:17]
	v_mfma_f32_16x16x32_bf16 v[2:5], v[166:169], v[198:201], v[2:5]
	v_mfma_f32_16x16x32_bf16 v[62:65], v[162:165], v[178:181], v[62:65]
	v_mfma_f32_16x16x32_bf16 v[54:57], v[170:173], v[178:181], v[54:57]
	v_mfma_f32_16x16x32_bf16 v[46:49], v[162:165], v[186:189], v[46:49]
	v_mfma_f32_16x16x32_bf16 v[38:41], v[170:173], v[186:189], v[38:41]
	v_mfma_f32_16x16x32_bf16 v[30:33], v[162:165], v[194:197], v[30:33]
	v_mfma_f32_16x16x32_bf16 v[22:25], v[170:173], v[194:197], v[22:25]
	v_mfma_f32_16x16x32_bf16 v[14:17], v[162:165], v[202:205], v[14:17]
	v_mfma_f32_16x16x32_bf16 v[2:5], v[170:173], v[202:205], v[2:5]
	s_barrier
	v_add_u32_e32 v134, 0x18000, v139
	ds_read_b128 v[142:145], v134
	ds_read_b128 v[146:149], v134 offset:1024
	ds_read_b128 v[150:153], v134 offset:2048
	ds_read_b128 v[154:157], v134 offset:3072
	v_add_u32_e32 v134, 0x1c000, v139
	ds_read_b128 v[158:161], v134
	ds_read_b128 v[162:165], v134 offset:1024
	ds_read_b128 v[166:169], v134 offset:2048
	ds_read_b128 v[170:173], v134 offset:3072
	ds_read_b128 v[174:177], v140 offset:32768
	ds_read_b128 v[178:181], v140 offset:33792
	ds_read_b128 v[182:185], v140 offset:34816
	ds_read_b128 v[186:189], v140 offset:35840
	ds_read_b128 v[190:193], v140 offset:36864
	ds_read_b128 v[194:197], v140 offset:37888
	ds_read_b128 v[198:201], v140 offset:38912
	ds_read_b128 v[202:205], v140 offset:39936
	s_add_u32 s44, s34, 0x40000
	s_addc_u32 s45, s35, 0
	s_mov_b32 s2, m0
	s_mov_b32 m0, s61
	s_nop 4
	global_load_lds_dwordx4 v1, s[44:45]
	s_mov_b32 m0, s2
	s_add_u32 s44, s34, 0x60000
	s_addc_u32 s45, s35, 0
	s_mov_b32 s2, m0
	s_mov_b32 m0, s62
	s_nop 4
	global_load_lds_dwordx4 v1, s[44:45]
	s_mov_b32 m0, s2
	s_waitcnt vmcnt(8)
	s_waitcnt lgkmcnt(0)
	s_barrier
	s_waitcnt lgkmcnt(7)
	v_mfma_f32_16x16x32_bf16 v[122:125], v[142:145], v[174:177], v[122:125]
	v_mfma_f32_16x16x32_bf16 v[114:117], v[150:153], v[174:177], v[114:117]
	s_waitcnt lgkmcnt(5)
	v_mfma_f32_16x16x32_bf16 v[106:109], v[142:145], v[182:185], v[106:109]
	v_mfma_f32_16x16x32_bf16 v[98:101], v[150:153], v[182:185], v[98:101]
	s_waitcnt lgkmcnt(3)
	v_mfma_f32_16x16x32_bf16 v[90:93], v[142:145], v[190:193], v[90:93]
	v_mfma_f32_16x16x32_bf16 v[82:85], v[150:153], v[190:193], v[82:85]
	s_waitcnt lgkmcnt(1)
	v_mfma_f32_16x16x32_bf16 v[74:77], v[142:145], v[198:201], v[74:77]
	v_mfma_f32_16x16x32_bf16 v[66:69], v[150:153], v[198:201], v[66:69]
	v_mfma_f32_16x16x32_bf16 v[122:125], v[146:149], v[178:181], v[122:125]
	v_mfma_f32_16x16x32_bf16 v[114:117], v[154:157], v[178:181], v[114:117]
	v_mfma_f32_16x16x32_bf16 v[106:109], v[146:149], v[186:189], v[106:109]
	v_mfma_f32_16x16x32_bf16 v[98:101], v[154:157], v[186:189], v[98:101]
	v_mfma_f32_16x16x32_bf16 v[90:93], v[146:149], v[194:197], v[90:93]
	v_mfma_f32_16x16x32_bf16 v[82:85], v[154:157], v[194:197], v[82:85]
	s_waitcnt lgkmcnt(0)
	v_mfma_f32_16x16x32_bf16 v[74:77], v[146:149], v[202:205], v[74:77]
	v_mfma_f32_16x16x32_bf16 v[66:69], v[154:157], v[202:205], v[66:69]
	v_mfma_f32_16x16x32_bf16 v[126:129], v[158:161], v[174:177], v[126:129]
	v_mfma_f32_16x16x32_bf16 v[118:121], v[166:169], v[174:177], v[118:121]
	v_mfma_f32_16x16x32_bf16 v[110:113], v[158:161], v[182:185], v[110:113]
	v_mfma_f32_16x16x32_bf16 v[102:105], v[166:169], v[182:185], v[102:105]
	v_mfma_f32_16x16x32_bf16 v[94:97], v[158:161], v[190:193], v[94:97]
	v_mfma_f32_16x16x32_bf16 v[86:89], v[166:169], v[190:193], v[86:89]
	v_mfma_f32_16x16x32_bf16 v[78:81], v[158:161], v[198:201], v[78:81]
	v_mfma_f32_16x16x32_bf16 v[70:73], v[166:169], v[198:201], v[70:73]
	v_mfma_f32_16x16x32_bf16 v[126:129], v[162:165], v[178:181], v[126:129]
	v_mfma_f32_16x16x32_bf16 v[118:121], v[170:173], v[178:181], v[118:121]
	v_mfma_f32_16x16x32_bf16 v[110:113], v[162:165], v[186:189], v[110:113]
	v_mfma_f32_16x16x32_bf16 v[102:105], v[170:173], v[186:189], v[102:105]
	v_mfma_f32_16x16x32_bf16 v[94:97], v[162:165], v[194:197], v[94:97]
	v_mfma_f32_16x16x32_bf16 v[86:89], v[170:173], v[194:197], v[86:89]
	v_mfma_f32_16x16x32_bf16 v[78:81], v[162:165], v[202:205], v[78:81]
	v_mfma_f32_16x16x32_bf16 v[70:73], v[170:173], v[202:205], v[70:73]
	s_barrier
	s_add_u32 s44, s52, 0x80
	s_addc_u32 s45, s53, 0
	ds_read_b128 v[174:177], v140 offset:49152
	ds_read_b128 v[178:181], v140 offset:50176
	ds_read_b128 v[182:185], v140 offset:51200
	ds_read_b128 v[186:189], v140 offset:52224
	ds_read_b128 v[190:193], v140 offset:53248
	ds_read_b128 v[194:197], v140 offset:54272
	ds_read_b128 v[198:201], v140 offset:55296
	ds_read_b128 v[202:205], v140 offset:56320
	s_mov_b32 s2, m0
	s_mov_b32 m0, s63
	s_nop 4
	global_load_lds_dwordx4 v136, s[44:45]
	s_mov_b32 m0, s2
	s_add_u32 s44, s52, 0x20080
	s_addc_u32 s45, s53, 0
	s_mov_b32 s2, m0
	s_mov_b32 m0, s64
	s_nop 4
	global_load_lds_dwordx4 v136, s[44:45]
	s_mov_b32 m0, s2
	s_add_u32 s44, s52, 0x40080
	s_addc_u32 s45, s53, 0
	s_mov_b32 s2, m0
	s_mov_b32 m0, s67
	s_nop 4
	global_load_lds_dwordx4 v136, s[44:45]
	s_mov_b32 m0, s2
	s_add_u32 s44, s52, 0x60080
	s_addc_u32 s45, s53, 0
	s_mov_b32 s2, m0
	s_mov_b32 m0, s73
	s_nop 4
	global_load_lds_dwordx4 v136, s[44:45]
	s_mov_b32 m0, s2
	s_add_u32 s34, s34, 0x20080
	s_mov_b32 s2, m0
	s_mov_b32 m0, s65
	s_nop 4
	global_load_lds_dwordx4 v1, s[50:51]
	s_mov_b32 m0, s2
	s_addc_u32 s35, s35, 0
	s_mov_b32 s2, m0
	s_mov_b32 m0, s66
	s_nop 4
	global_load_lds_dwordx4 v1, s[34:35]
	s_mov_b32 m0, s2
	s_waitcnt vmcnt(8)
	s_waitcnt lgkmcnt(0)
	s_barrier
	s_waitcnt lgkmcnt(7)
	v_mfma_f32_16x16x32_bf16 v[58:61], v[142:145], v[174:177], v[58:61]
	v_mfma_f32_16x16x32_bf16 v[50:53], v[150:153], v[174:177], v[50:53]
	s_waitcnt lgkmcnt(5)
	v_mfma_f32_16x16x32_bf16 v[42:45], v[142:145], v[182:185], v[42:45]
	v_mfma_f32_16x16x32_bf16 v[34:37], v[150:153], v[182:185], v[34:37]
	s_waitcnt lgkmcnt(3)
	v_mfma_f32_16x16x32_bf16 v[26:29], v[142:145], v[190:193], v[26:29]
	v_mfma_f32_16x16x32_bf16 v[18:21], v[150:153], v[190:193], v[18:21]
	s_waitcnt lgkmcnt(1)
	v_mfma_f32_16x16x32_bf16 v[10:13], v[142:145], v[198:201], v[10:13]
	v_mfma_f32_16x16x32_bf16 v[6:9], v[150:153], v[198:201], v[6:9]
	v_mfma_f32_16x16x32_bf16 v[58:61], v[146:149], v[178:181], v[58:61]
	v_mfma_f32_16x16x32_bf16 v[50:53], v[154:157], v[178:181], v[50:53]
	v_mfma_f32_16x16x32_bf16 v[42:45], v[146:149], v[186:189], v[42:45]
	v_mfma_f32_16x16x32_bf16 v[34:37], v[154:157], v[186:189], v[34:37]
	v_mfma_f32_16x16x32_bf16 v[26:29], v[146:149], v[194:197], v[26:29]
	v_mfma_f32_16x16x32_bf16 v[18:21], v[154:157], v[194:197], v[18:21]
	s_waitcnt lgkmcnt(0)
	v_mfma_f32_16x16x32_bf16 v[10:13], v[146:149], v[202:205], v[10:13]
	v_mfma_f32_16x16x32_bf16 v[6:9], v[154:157], v[202:205], v[6:9]
	v_mfma_f32_16x16x32_bf16 v[62:65], v[158:161], v[174:177], v[62:65]
	v_mfma_f32_16x16x32_bf16 v[54:57], v[166:169], v[174:177], v[54:57]
	v_mfma_f32_16x16x32_bf16 v[46:49], v[158:161], v[182:185], v[46:49]
	v_mfma_f32_16x16x32_bf16 v[38:41], v[166:169], v[182:185], v[38:41]
	v_mfma_f32_16x16x32_bf16 v[30:33], v[158:161], v[190:193], v[30:33]
	v_mfma_f32_16x16x32_bf16 v[22:25], v[166:169], v[190:193], v[22:25]
	v_mfma_f32_16x16x32_bf16 v[14:17], v[158:161], v[198:201], v[14:17]
	v_mfma_f32_16x16x32_bf16 v[2:5], v[166:169], v[198:201], v[2:5]
	v_mfma_f32_16x16x32_bf16 v[62:65], v[162:165], v[178:181], v[62:65]
	v_mfma_f32_16x16x32_bf16 v[54:57], v[170:173], v[178:181], v[54:57]
	v_mfma_f32_16x16x32_bf16 v[46:49], v[162:165], v[186:189], v[46:49]
	v_mfma_f32_16x16x32_bf16 v[38:41], v[170:173], v[186:189], v[38:41]
	v_mfma_f32_16x16x32_bf16 v[30:33], v[162:165], v[194:197], v[30:33]
	v_mfma_f32_16x16x32_bf16 v[22:25], v[170:173], v[194:197], v[22:25]
	v_mfma_f32_16x16x32_bf16 v[14:17], v[162:165], v[202:205], v[14:17]
	v_mfma_f32_16x16x32_bf16 v[2:5], v[170:173], v[202:205], v[2:5]
	s_barrier
	s_add_i32 s81, s81, 2
	s_add_u32 s79, s79, 0x100
	s_addc_u32 s80, s80, 0
	s_cmp_gt_u32 s81, 13
	s_mov_b64 s[44:45], s[0:1]
	s_cbranch_scc0 .LBB0_557
	s_and_b64 vcc, exec, s[10:11]
	s_cbranch_vccz .LBB0_560
	s_barrier

.LBB0_637:
	ds_read_b128 v[138:141], v132
	ds_read_b128 v[142:145], v132 offset:1024
	ds_read_b128 v[146:149], v132 offset:2048
	ds_read_b128 v[150:153], v132 offset:3072
	ds_read_b128 v[154:157], v134
	ds_read_b128 v[158:161], v134 offset:1024
	ds_read_b128 v[182:185], v134 offset:2048
	ds_read_b128 v[186:189], v134 offset:3072
	s_add_u32 s0, s34, 0x100
	s_addc_u32 s1, s35, 0
	s_cmp_eq_u32 s91, 18
	s_cselect_b32 s52, s10, s0
	s_cselect_b32 s53, s11, s1
	s_cselect_b32 s50, s6, s89
	s_cselect_b32 s51, s7, s90
	s_add_u32 s54, s52, 0x80
	s_addc_u32 s55, s53, 0
	s_add_u32 s92, s34, 0x58080
	s_addc_u32 s93, s35, 0
	s_mov_b32 m0, s88
	s_nop 4
	global_load_lds_dwordx4 v130, s[92:93]
	s_add_u32 s34, s34, 0x84080
	s_addc_u32 s35, s35, 0
	s_add_i32 s2, s73, 0xe000
	s_mov_b32 m0, s2
	s_nop 4
	global_load_lds_dwordx4 v130, s[34:35]
	ds_read_b128 v[190:193], v133
	ds_read_b128 v[194:197], v133 offset:1024
	ds_read_b128 v[198:201], v133 offset:2048
	ds_read_b128 v[202:205], v133 offset:3072
	ds_read_b128 v[206:209], v133 offset:4096
	ds_read_b128 v[210:213], v133 offset:5120
	ds_read_b128 v[214:217], v133 offset:6144
	ds_read_b128 v[218:221], v133 offset:7168
	s_waitcnt vmcnt(8)
	s_waitcnt lgkmcnt(0)
	s_barrier
	v_mfma_f32_16x16x128_f8f6f4 v[14:17], v[138:145], v[190:197], v[14:17]
	v_mfma_f32_16x16x128_f8f6f4 v[30:33], v[138:145], v[198:205], v[30:33]
	v_mfma_f32_16x16x128_f8f6f4 v[50:53], v[138:145], v[206:213], v[50:53]
	v_mfma_f32_16x16x128_f8f6f4 v[62:65], v[138:145], v[214:221], v[62:65]
	v_mfma_f32_16x16x128_f8f6f4 v[10:13], v[146:153], v[190:197], v[10:13]
	v_mfma_f32_16x16x128_f8f6f4 v[26:29], v[146:153], v[198:205], v[26:29]
	v_mfma_f32_16x16x128_f8f6f4 v[42:45], v[146:153], v[206:213], v[42:45]
	v_mfma_f32_16x16x128_f8f6f4 v[58:61], v[146:153], v[214:221], v[58:61]
	v_mfma_f32_16x16x128_f8f6f4 v[6:9], v[154:161], v[190:197], v[6:9]
	v_mfma_f32_16x16x128_f8f6f4 v[22:25], v[154:161], v[198:205], v[22:25]
	v_mfma_f32_16x16x128_f8f6f4 v[38:41], v[154:161], v[206:213], v[38:41]
	v_mfma_f32_16x16x128_f8f6f4 v[54:57], v[154:161], v[214:221], v[54:57]
	v_mfma_f32_16x16x128_f8f6f4 v[2:5], v[182:189], v[190:197], v[2:5]
	v_mfma_f32_16x16x128_f8f6f4 v[18:21], v[182:189], v[198:205], v[18:21]
	v_mfma_f32_16x16x128_f8f6f4 v[34:37], v[182:189], v[206:213], v[34:37]
	v_mfma_f32_16x16x128_f8f6f4 v[46:49], v[182:189], v[214:221], v[46:49]
	s_barrier
	ds_read_b128 v[190:193], v133 offset:16384
	ds_read_b128 v[194:197], v133 offset:17408
	ds_read_b128 v[198:201], v133 offset:18432
	ds_read_b128 v[202:205], v133 offset:19456
	ds_read_b128 v[206:209], v133 offset:20480
	ds_read_b128 v[210:213], v133 offset:21504
	ds_read_b128 v[214:217], v133 offset:22528
	ds_read_b128 v[218:221], v133 offset:23552
	s_mov_b32 m0, s74
	s_nop 4
	global_load_lds_dwordx4 v131, s[50:51]
	s_add_u32 s34, s50, 0x2c000
	s_addc_u32 s35, s51, 0
	s_mov_b32 m0, s75
	s_nop 4
	global_load_lds_dwordx4 v131, s[34:35]
	s_add_u32 s34, s50, 0x58000
	s_addc_u32 s35, s51, 0
	s_mov_b32 m0, s77
	s_nop 4
	global_load_lds_dwordx4 v131, s[34:35]
	s_add_u32 s34, s50, 0x84000
	s_addc_u32 s35, s51, 0
	s_mov_b32 m0, s78
	s_nop 4
	global_load_lds_dwordx4 v131, s[34:35]
	s_mov_b32 m0, s73
	s_nop 4
	global_load_lds_dwordx4 v130, s[52:53]
	s_add_u32 s34, s52, 0x2c000
	s_addc_u32 s35, s53, 0
	s_mov_b32 m0, s76
	s_nop 4
	global_load_lds_dwordx4 v130, s[34:35]
	s_waitcnt vmcnt(8)
	s_waitcnt lgkmcnt(0)
	s_barrier
	v_mfma_f32_16x16x128_f8f6f4 v[78:81], v[138:145], v[190:197], v[78:81]
	v_mfma_f32_16x16x128_f8f6f4 v[94:97], v[138:145], v[198:205], v[94:97]
	v_mfma_f32_16x16x128_f8f6f4 v[126:129], v[138:145], v[206:213], v[126:129]
	v_mfma_f32_16x16x128_f8f6f4 v[98:101], v[138:145], v[214:221], v[98:101]
	v_mfma_f32_16x16x128_f8f6f4 v[74:77], v[146:153], v[190:197], v[74:77]
	v_mfma_f32_16x16x128_f8f6f4 v[90:93], v[146:153], v[198:205], v[90:93]
	v_mfma_f32_16x16x128_f8f6f4 v[114:117], v[146:153], v[206:213], v[114:117]
	v_mfma_f32_16x16x128_f8f6f4 v[122:125], v[146:153], v[214:221], v[122:125]
	v_mfma_f32_16x16x128_f8f6f4 v[70:73], v[154:161], v[190:197], v[70:73]
	v_mfma_f32_16x16x128_f8f6f4 v[86:89], v[154:161], v[198:205], v[86:89]
	v_mfma_f32_16x16x128_f8f6f4 v[106:109], v[154:161], v[206:213], v[106:109]
	v_mfma_f32_16x16x128_f8f6f4 v[118:121], v[154:161], v[214:221], v[118:121]
	v_mfma_f32_16x16x128_f8f6f4 v[66:69], v[182:189], v[190:197], v[66:69]
	v_mfma_f32_16x16x128_f8f6f4 v[82:85], v[182:189], v[198:205], v[82:85]
	v_mfma_f32_16x16x128_f8f6f4 v[102:105], v[182:189], v[206:213], v[102:105]
	v_mfma_f32_16x16x128_f8f6f4 v[110:113], v[182:189], v[214:221], v[110:113]
	s_barrier
	ds_read_b128 v[138:141], v135
	ds_read_b128 v[142:145], v135 offset:1024
	ds_read_b128 v[146:149], v135 offset:2048
	ds_read_b128 v[150:153], v135 offset:3072
	ds_read_b128 v[154:157], v136
	ds_read_b128 v[158:161], v136 offset:1024
	ds_read_b128 v[182:185], v136 offset:2048
	ds_read_b128 v[186:189], v136 offset:3072
	s_add_u32 s34, s52, 0x58000
	s_addc_u32 s35, s53, 0
	s_mov_b32 m0, s79
	s_nop 4
	global_load_lds_dwordx4 v130, s[34:35]
	s_add_u32 s34, s52, 0x84000
	s_addc_u32 s35, s53, 0
	s_mov_b32 m0, s80
	s_nop 4
	global_load_lds_dwordx4 v130, s[34:35]
	ds_read_b128 v[190:193], v133 offset:32768
	ds_read_b128 v[194:197], v133 offset:33792
	ds_read_b128 v[198:201], v133 offset:34816
	ds_read_b128 v[202:205], v133 offset:35840
	ds_read_b128 v[206:209], v133 offset:36864
	ds_read_b128 v[210:213], v133 offset:37888
	ds_read_b128 v[214:217], v133 offset:38912
	ds_read_b128 v[218:221], v133 offset:39936
	s_waitcnt vmcnt(8)
	s_waitcnt lgkmcnt(0)
	s_barrier
	v_mfma_f32_16x16x128_f8f6f4 v[14:17], v[138:145], v[190:197], v[14:17]
	v_mfma_f32_16x16x128_f8f6f4 v[30:33], v[138:145], v[198:205], v[30:33]
	v_mfma_f32_16x16x128_f8f6f4 v[50:53], v[138:145], v[206:213], v[50:53]
	v_mfma_f32_16x16x128_f8f6f4 v[62:65], v[138:145], v[214:221], v[62:65]
	v_mfma_f32_16x16x128_f8f6f4 v[10:13], v[146:153], v[190:197], v[10:13]
	v_mfma_f32_16x16x128_f8f6f4 v[26:29], v[146:153], v[198:205], v[26:29]
	v_mfma_f32_16x16x128_f8f6f4 v[42:45], v[146:153], v[206:213], v[42:45]
	v_mfma_f32_16x16x128_f8f6f4 v[58:61], v[146:153], v[214:221], v[58:61]
	v_mfma_f32_16x16x128_f8f6f4 v[6:9], v[154:161], v[190:197], v[6:9]
	v_mfma_f32_16x16x128_f8f6f4 v[22:25], v[154:161], v[198:205], v[22:25]
	v_mfma_f32_16x16x128_f8f6f4 v[38:41], v[154:161], v[206:213], v[38:41]
	v_mfma_f32_16x16x128_f8f6f4 v[54:57], v[154:161], v[214:221], v[54:57]
	v_mfma_f32_16x16x128_f8f6f4 v[2:5], v[182:189], v[190:197], v[2:5]
	v_mfma_f32_16x16x128_f8f6f4 v[18:21], v[182:189], v[198:205], v[18:21]
	v_mfma_f32_16x16x128_f8f6f4 v[34:37], v[182:189], v[206:213], v[34:37]
	v_mfma_f32_16x16x128_f8f6f4 v[46:49], v[182:189], v[214:221], v[46:49]
	s_barrier
	ds_read_b128 v[190:193], v133 offset:49152
	ds_read_b128 v[194:197], v133 offset:50176
	ds_read_b128 v[198:201], v133 offset:51200
	ds_read_b128 v[202:205], v133 offset:52224
	ds_read_b128 v[206:209], v133 offset:53248
	ds_read_b128 v[210:213], v133 offset:54272
	ds_read_b128 v[214:217], v133 offset:55296
	ds_read_b128 v[218:221], v133 offset:56320
	s_add_u32 s34, s50, 0x80
	s_addc_u32 s35, s51, 0
	s_mov_b32 m0, s81
	s_nop 4
	global_load_lds_dwordx4 v131, s[34:35]
	s_add_u32 s34, s50, 0x2c080
	s_addc_u32 s35, s51, 0
	s_mov_b32 m0, s82
	s_nop 4
	global_load_lds_dwordx4 v131, s[34:35]
	s_add_u32 s34, s50, 0x58080
	s_addc_u32 s35, s51, 0
	s_mov_b32 m0, s86
	s_nop 4
	global_load_lds_dwordx4 v131, s[34:35]
	s_add_u32 s34, s50, 0x84080
	s_addc_u32 s35, s51, 0
	s_mov_b32 m0, s87
	s_nop 4
	global_load_lds_dwordx4 v131, s[34:35]
	s_mov_b32 m0, s84
	s_nop 4
	global_load_lds_dwordx4 v130, s[54:55]
	s_add_u32 s34, s52, 0x2c080
	s_addc_u32 s35, s53, 0
	s_mov_b32 m0, s85
	s_nop 4
	global_load_lds_dwordx4 v130, s[34:35]
	s_waitcnt vmcnt(8)
	s_waitcnt lgkmcnt(0)
	s_barrier
	v_mfma_f32_16x16x128_f8f6f4 v[78:81], v[138:145], v[190:197], v[78:81]
	v_mfma_f32_16x16x128_f8f6f4 v[94:97], v[138:145], v[198:205], v[94:97]
	v_mfma_f32_16x16x128_f8f6f4 v[126:129], v[138:145], v[206:213], v[126:129]
	v_mfma_f32_16x16x128_f8f6f4 v[98:101], v[138:145], v[214:221], v[98:101]
	v_mfma_f32_16x16x128_f8f6f4 v[74:77], v[146:153], v[190:197], v[74:77]
	v_mfma_f32_16x16x128_f8f6f4 v[90:93], v[146:153], v[198:205], v[90:93]
	v_mfma_f32_16x16x128_f8f6f4 v[114:117], v[146:153], v[206:213], v[114:117]
	v_mfma_f32_16x16x128_f8f6f4 v[122:125], v[146:153], v[214:221], v[122:125]
	v_mfma_f32_16x16x128_f8f6f4 v[70:73], v[154:161], v[190:197], v[70:73]
	v_mfma_f32_16x16x128_f8f6f4 v[86:89], v[154:161], v[198:205], v[86:89]
	v_mfma_f32_16x16x128_f8f6f4 v[106:109], v[154:161], v[206:213], v[106:109]
	v_mfma_f32_16x16x128_f8f6f4 v[118:121], v[154:161], v[214:221], v[118:121]
	v_mfma_f32_16x16x128_f8f6f4 v[66:69], v[182:189], v[190:197], v[66:69]
	v_mfma_f32_16x16x128_f8f6f4 v[82:85], v[182:189], v[198:205], v[82:85]
	v_mfma_f32_16x16x128_f8f6f4 v[102:105], v[182:189], v[206:213], v[102:105]
	v_mfma_f32_16x16x128_f8f6f4 v[110:113], v[182:189], v[214:221], v[110:113]
	s_add_i32 s91, s91, 2
	s_add_u32 s89, s89, 0x100
	s_addc_u32 s90, s90, 0
	s_cmp_lt_u32 s91, 20
	s_mov_b64 s[34:35], s[0:1]
	s_barrier
	s_cbranch_scc1 .LBB0_637
	s_waitcnt vmcnt(0)
	s_cmpk_gt_u32 s66, 0xff
	s_cbranch_scc1 .LBB0_640
	s_barrier

.LBB0_752:
	v_add_u32_e32 v138, 0x10000, v143
	ds_read_b128 v[130:133], v138
	ds_read_b128 v[154:157], v138 offset:1024
	ds_read_b128 v[158:161], v138 offset:2048
	ds_read_b128 v[162:165], v138 offset:3072
	v_add_u32_e32 v138, 0x14000, v143
	ds_read_b128 v[166:169], v138
	ds_read_b128 v[170:173], v138 offset:1024
	ds_read_b128 v[174:177], v138 offset:2048
	ds_read_b128 v[178:181], v138 offset:3072
	s_add_u32 s0, s44, 0x100
	s_addc_u32 s1, s45, 0
	s_cmp_eq_u32 vcc_lo, 12
	s_cselect_b32 s34, s9, s0
	s_cselect_b32 s35, s7, s1
	s_cselect_b32 s52, s15, s27
	s_cselect_b32 s53, s14, s37
	s_add_u32 s50, s34, 0x80
	s_addc_u32 s51, s35, 0
	ds_read_b128 v[182:185], v145
	ds_read_b128 v[186:189], v145 offset:1024
	ds_read_b128 v[190:193], v145 offset:2048
	ds_read_b128 v[194:197], v145 offset:3072
	ds_read_b128 v[198:201], v145 offset:4096
	ds_read_b128 v[202:205], v145 offset:5120
	ds_read_b128 v[206:209], v145 offset:6144
	ds_read_b128 v[210:213], v145 offset:7168
	s_add_u32 s2, s44, 0x40080
	s_addc_u32 s3, s45, 0
	s_mov_b32 s12, m0
	s_mov_b32 m0, s96
	s_nop 4
	global_load_lds_dwordx4 v1, s[2:3]
	s_mov_b32 m0, s12
	s_add_u32 s2, s44, 0x60080
	s_addc_u32 s3, s45, 0
	s_add_i32 s12, s58, 0xe000
	s_mov_b32 s13, m0
	s_mov_b32 m0, s12
	s_nop 4
	global_load_lds_dwordx4 v1, s[2:3]
	s_mov_b32 m0, s13
	s_waitcnt vmcnt(8)
	s_waitcnt lgkmcnt(0)
	s_barrier
	s_waitcnt lgkmcnt(7)
	v_mfma_f32_16x16x32_bf16 v[118:121], v[130:133], v[182:185], v[118:121]
	v_mfma_f32_16x16x32_bf16 v[114:117], v[158:161], v[182:185], v[114:117]
	s_waitcnt lgkmcnt(5)
	v_mfma_f32_16x16x32_bf16 v[102:105], v[130:133], v[190:193], v[102:105]
	v_mfma_f32_16x16x32_bf16 v[98:101], v[158:161], v[190:193], v[98:101]
	s_waitcnt lgkmcnt(3)
	v_mfma_f32_16x16x32_bf16 v[86:89], v[130:133], v[198:201], v[86:89]
	v_mfma_f32_16x16x32_bf16 v[82:85], v[158:161], v[198:201], v[82:85]
	s_waitcnt lgkmcnt(1)
	v_mfma_f32_16x16x32_bf16 v[70:73], v[130:133], v[206:209], v[70:73]
	v_mfma_f32_16x16x32_bf16 v[66:69], v[158:161], v[206:209], v[66:69]
	v_mfma_f32_16x16x32_bf16 v[118:121], v[154:157], v[186:189], v[118:121]
	v_mfma_f32_16x16x32_bf16 v[114:117], v[162:165], v[186:189], v[114:117]
	v_mfma_f32_16x16x32_bf16 v[102:105], v[154:157], v[194:197], v[102:105]
	v_mfma_f32_16x16x32_bf16 v[98:101], v[162:165], v[194:197], v[98:101]
	v_mfma_f32_16x16x32_bf16 v[86:89], v[154:157], v[202:205], v[86:89]
	v_mfma_f32_16x16x32_bf16 v[82:85], v[162:165], v[202:205], v[82:85]
	s_waitcnt lgkmcnt(0)
	v_mfma_f32_16x16x32_bf16 v[70:73], v[154:157], v[210:213], v[70:73]
	v_mfma_f32_16x16x32_bf16 v[66:69], v[162:165], v[210:213], v[66:69]
	v_mfma_f32_16x16x32_bf16 v[126:129], v[166:169], v[182:185], v[126:129]
	v_mfma_f32_16x16x32_bf16 v[122:125], v[174:177], v[182:185], v[122:125]
	v_mfma_f32_16x16x32_bf16 v[110:113], v[166:169], v[190:193], v[110:113]
	v_mfma_f32_16x16x32_bf16 v[106:109], v[174:177], v[190:193], v[106:109]
	v_mfma_f32_16x16x32_bf16 v[94:97], v[166:169], v[198:201], v[94:97]
	v_mfma_f32_16x16x32_bf16 v[90:93], v[174:177], v[198:201], v[90:93]
	v_mfma_f32_16x16x32_bf16 v[78:81], v[166:169], v[206:209], v[78:81]
	v_mfma_f32_16x16x32_bf16 v[74:77], v[174:177], v[206:209], v[74:77]
	v_mfma_f32_16x16x32_bf16 v[126:129], v[170:173], v[186:189], v[126:129]
	v_mfma_f32_16x16x32_bf16 v[122:125], v[178:181], v[186:189], v[122:125]
	v_mfma_f32_16x16x32_bf16 v[110:113], v[170:173], v[194:197], v[110:113]
	v_mfma_f32_16x16x32_bf16 v[106:109], v[178:181], v[194:197], v[106:109]
	v_mfma_f32_16x16x32_bf16 v[94:97], v[170:173], v[202:205], v[94:97]
	v_mfma_f32_16x16x32_bf16 v[90:93], v[178:181], v[202:205], v[90:93]
	v_mfma_f32_16x16x32_bf16 v[78:81], v[170:173], v[210:213], v[78:81]
	v_mfma_f32_16x16x32_bf16 v[74:77], v[178:181], v[210:213], v[74:77]
	s_barrier
	ds_read_b128 v[182:185], v145 offset:16384
	ds_read_b128 v[186:189], v145 offset:17408
	ds_read_b128 v[190:193], v145 offset:18432
	ds_read_b128 v[194:197], v145 offset:19456
	ds_read_b128 v[198:201], v145 offset:20480
	ds_read_b128 v[202:205], v145 offset:21504
	ds_read_b128 v[206:209], v145 offset:22528
	ds_read_b128 v[210:213], v145 offset:23552
	s_mov_b32 s2, m0
	s_mov_b32 m0, s60
	s_nop 4
	global_load_lds_dwordx4 v135, s[52:53]
	s_mov_b32 m0, s2
	s_add_u32 s2, s52, 0x20000
	s_addc_u32 s3, s53, 0
	s_mov_b32 s12, m0
	s_mov_b32 m0, s61
	s_nop 4
	global_load_lds_dwordx4 v135, s[2:3]
	s_mov_b32 m0, s12
	s_add_u32 s2, s52, 0x40000
	s_addc_u32 s3, s53, 0
	s_mov_b32 s12, m0
	s_mov_b32 m0, s62
	s_nop 4
	global_load_lds_dwordx4 v135, s[2:3]
	s_mov_b32 m0, s12
	s_add_u32 s2, s52, 0x60000
	s_addc_u32 s3, s53, 0
	s_mov_b32 s12, m0
	s_mov_b32 m0, s63
	s_nop 4
	global_load_lds_dwordx4 v135, s[2:3]
	s_mov_b32 m0, s12
	s_mov_b32 s2, m0
	s_mov_b32 m0, s58
	s_nop 4
	global_load_lds_dwordx4 v1, s[34:35]
	s_mov_b32 m0, s2
	s_add_u32 s2, s34, 0x20000
	s_addc_u32 s3, s35, 0
	s_mov_b32 s12, m0
	s_mov_b32 m0, s64
	s_nop 4
	global_load_lds_dwordx4 v1, s[2:3]
	s_mov_b32 m0, s12
	s_waitcnt vmcnt(8)
	s_waitcnt lgkmcnt(0)
	s_barrier
	s_waitcnt lgkmcnt(7)
	v_mfma_f32_16x16x32_bf16 v[54:57], v[130:133], v[182:185], v[54:57]
	v_mfma_f32_16x16x32_bf16 v[50:53], v[158:161], v[182:185], v[50:53]
	s_waitcnt lgkmcnt(5)
	v_mfma_f32_16x16x32_bf16 v[38:41], v[130:133], v[190:193], v[38:41]
	v_mfma_f32_16x16x32_bf16 v[34:37], v[158:161], v[190:193], v[34:37]
	s_waitcnt lgkmcnt(3)
	v_mfma_f32_16x16x32_bf16 v[22:25], v[130:133], v[198:201], v[22:25]
	v_mfma_f32_16x16x32_bf16 v[18:21], v[158:161], v[198:201], v[18:21]
	s_waitcnt lgkmcnt(1)
	v_mfma_f32_16x16x32_bf16 v[10:13], v[130:133], v[206:209], v[10:13]
	v_mfma_f32_16x16x32_bf16 v[6:9], v[158:161], v[206:209], v[6:9]
	v_mfma_f32_16x16x32_bf16 v[54:57], v[154:157], v[186:189], v[54:57]
	v_mfma_f32_16x16x32_bf16 v[50:53], v[162:165], v[186:189], v[50:53]
	v_mfma_f32_16x16x32_bf16 v[38:41], v[154:157], v[194:197], v[38:41]
	v_mfma_f32_16x16x32_bf16 v[34:37], v[162:165], v[194:197], v[34:37]
	v_mfma_f32_16x16x32_bf16 v[22:25], v[154:157], v[202:205], v[22:25]
	v_mfma_f32_16x16x32_bf16 v[18:21], v[162:165], v[202:205], v[18:21]
	s_waitcnt lgkmcnt(0)
	v_mfma_f32_16x16x32_bf16 v[10:13], v[154:157], v[210:213], v[10:13]
	v_mfma_f32_16x16x32_bf16 v[6:9], v[162:165], v[210:213], v[6:9]
	v_mfma_f32_16x16x32_bf16 v[62:65], v[166:169], v[182:185], v[62:65]
	v_mfma_f32_16x16x32_bf16 v[58:61], v[174:177], v[182:185], v[58:61]
	v_mfma_f32_16x16x32_bf16 v[46:49], v[166:169], v[190:193], v[46:49]
	v_mfma_f32_16x16x32_bf16 v[42:45], v[174:177], v[190:193], v[42:45]
	v_mfma_f32_16x16x32_bf16 v[30:33], v[166:169], v[198:201], v[30:33]
	v_mfma_f32_16x16x32_bf16 v[26:29], v[174:177], v[198:201], v[26:29]
	v_mfma_f32_16x16x32_bf16 v[14:17], v[166:169], v[206:209], v[14:17]
	v_mfma_f32_16x16x32_bf16 v[2:5], v[174:177], v[206:209], v[2:5]
	v_mfma_f32_16x16x32_bf16 v[62:65], v[170:173], v[186:189], v[62:65]
	v_mfma_f32_16x16x32_bf16 v[58:61], v[178:181], v[186:189], v[58:61]
	v_mfma_f32_16x16x32_bf16 v[46:49], v[170:173], v[194:197], v[46:49]
	v_mfma_f32_16x16x32_bf16 v[42:45], v[178:181], v[194:197], v[42:45]
	v_mfma_f32_16x16x32_bf16 v[30:33], v[170:173], v[202:205], v[30:33]
	v_mfma_f32_16x16x32_bf16 v[26:29], v[178:181], v[202:205], v[26:29]
	v_mfma_f32_16x16x32_bf16 v[14:17], v[170:173], v[210:213], v[14:17]
	v_mfma_f32_16x16x32_bf16 v[2:5], v[178:181], v[210:213], v[2:5]
	s_barrier
	v_add_u32_e32 v138, 0x18000, v143
	ds_read_b128 v[130:133], v138
	ds_read_b128 v[154:157], v138 offset:1024
	ds_read_b128 v[158:161], v138 offset:2048
	ds_read_b128 v[162:165], v138 offset:3072
	v_add_u32_e32 v138, 0x1c000, v143
	ds_read_b128 v[166:169], v138
	ds_read_b128 v[170:173], v138 offset:1024
	ds_read_b128 v[174:177], v138 offset:2048
	ds_read_b128 v[178:181], v138 offset:3072
	ds_read_b128 v[182:185], v145 offset:32768
	ds_read_b128 v[186:189], v145 offset:33792
	ds_read_b128 v[190:193], v145 offset:34816
	ds_read_b128 v[194:197], v145 offset:35840
	ds_read_b128 v[198:201], v145 offset:36864
	ds_read_b128 v[202:205], v145 offset:37888
	ds_read_b128 v[206:209], v145 offset:38912
	ds_read_b128 v[210:213], v145 offset:39936
	s_add_u32 s2, s34, 0x40000
	s_addc_u32 s3, s35, 0
	s_mov_b32 s12, m0
	s_mov_b32 m0, s65
	s_nop 4
	global_load_lds_dwordx4 v1, s[2:3]
	s_mov_b32 m0, s12
	s_add_u32 s2, s34, 0x60000
	s_addc_u32 s3, s35, 0
	s_mov_b32 s12, m0
	s_mov_b32 m0, s66
	s_nop 4
	global_load_lds_dwordx4 v1, s[2:3]
	s_mov_b32 m0, s12
	s_waitcnt vmcnt(8)
	s_waitcnt lgkmcnt(0)
	s_barrier
	s_waitcnt lgkmcnt(7)
	v_mfma_f32_16x16x32_bf16 v[118:121], v[130:133], v[182:185], v[118:121]
	v_mfma_f32_16x16x32_bf16 v[114:117], v[158:161], v[182:185], v[114:117]
	s_waitcnt lgkmcnt(5)
	v_mfma_f32_16x16x32_bf16 v[102:105], v[130:133], v[190:193], v[102:105]
	v_mfma_f32_16x16x32_bf16 v[98:101], v[158:161], v[190:193], v[98:101]
	s_waitcnt lgkmcnt(3)
	v_mfma_f32_16x16x32_bf16 v[86:89], v[130:133], v[198:201], v[86:89]
	v_mfma_f32_16x16x32_bf16 v[82:85], v[158:161], v[198:201], v[82:85]
	s_waitcnt lgkmcnt(1)
	v_mfma_f32_16x16x32_bf16 v[70:73], v[130:133], v[206:209], v[70:73]
	v_mfma_f32_16x16x32_bf16 v[66:69], v[158:161], v[206:209], v[66:69]
	v_mfma_f32_16x16x32_bf16 v[118:121], v[154:157], v[186:189], v[118:121]
	v_mfma_f32_16x16x32_bf16 v[114:117], v[162:165], v[186:189], v[114:117]
	v_mfma_f32_16x16x32_bf16 v[102:105], v[154:157], v[194:197], v[102:105]
	v_mfma_f32_16x16x32_bf16 v[98:101], v[162:165], v[194:197], v[98:101]
	v_mfma_f32_16x16x32_bf16 v[86:89], v[154:157], v[202:205], v[86:89]
	v_mfma_f32_16x16x32_bf16 v[82:85], v[162:165], v[202:205], v[82:85]
	s_waitcnt lgkmcnt(0)
	v_mfma_f32_16x16x32_bf16 v[70:73], v[154:157], v[210:213], v[70:73]
	v_mfma_f32_16x16x32_bf16 v[66:69], v[162:165], v[210:213], v[66:69]
	v_mfma_f32_16x16x32_bf16 v[126:129], v[166:169], v[182:185], v[126:129]
	v_mfma_f32_16x16x32_bf16 v[122:125], v[174:177], v[182:185], v[122:125]
	v_mfma_f32_16x16x32_bf16 v[110:113], v[166:169], v[190:193], v[110:113]
	v_mfma_f32_16x16x32_bf16 v[106:109], v[174:177], v[190:193], v[106:109]
	v_mfma_f32_16x16x32_bf16 v[94:97], v[166:169], v[198:201], v[94:97]
	v_mfma_f32_16x16x32_bf16 v[90:93], v[174:177], v[198:201], v[90:93]
	v_mfma_f32_16x16x32_bf16 v[78:81], v[166:169], v[206:209], v[78:81]
	v_mfma_f32_16x16x32_bf16 v[74:77], v[174:177], v[206:209], v[74:77]
	v_mfma_f32_16x16x32_bf16 v[126:129], v[170:173], v[186:189], v[126:129]
	v_mfma_f32_16x16x32_bf16 v[122:125], v[178:181], v[186:189], v[122:125]
	v_mfma_f32_16x16x32_bf16 v[110:113], v[170:173], v[194:197], v[110:113]
	v_mfma_f32_16x16x32_bf16 v[106:109], v[178:181], v[194:197], v[106:109]
	v_mfma_f32_16x16x32_bf16 v[94:97], v[170:173], v[202:205], v[94:97]
	v_mfma_f32_16x16x32_bf16 v[90:93], v[178:181], v[202:205], v[90:93]
	v_mfma_f32_16x16x32_bf16 v[78:81], v[170:173], v[210:213], v[78:81]
	v_mfma_f32_16x16x32_bf16 v[74:77], v[178:181], v[210:213], v[74:77]
	s_barrier
	s_add_u32 s2, s52, 0x80
	s_addc_u32 s3, s53, 0
	ds_read_b128 v[182:185], v145 offset:49152
	ds_read_b128 v[186:189], v145 offset:50176
	ds_read_b128 v[190:193], v145 offset:51200
	ds_read_b128 v[194:197], v145 offset:52224
	ds_read_b128 v[198:201], v145 offset:53248
	ds_read_b128 v[202:205], v145 offset:54272
	ds_read_b128 v[206:209], v145 offset:55296
	ds_read_b128 v[210:213], v145 offset:56320
	s_mov_b32 s12, m0
	s_mov_b32 m0, s90
	s_nop 4
	global_load_lds_dwordx4 v135, s[2:3]
	s_mov_b32 m0, s12
	s_add_u32 s2, s52, 0x20080
	s_addc_u32 s3, s53, 0
	s_mov_b32 s12, m0
	s_mov_b32 m0, s91
	s_nop 4
	global_load_lds_dwordx4 v135, s[2:3]
	s_mov_b32 m0, s12
	s_add_u32 s2, s52, 0x40080
	s_addc_u32 s3, s53, 0
	s_mov_b32 s12, m0
	s_mov_b32 m0, s94
	s_nop 4
	global_load_lds_dwordx4 v135, s[2:3]
	s_mov_b32 m0, s12
	s_add_u32 s2, s52, 0x60080
	s_addc_u32 s3, s53, 0
	s_mov_b32 s12, m0
	s_mov_b32 m0, s95
	s_nop 4
	global_load_lds_dwordx4 v135, s[2:3]
	s_mov_b32 m0, s12
	s_mov_b32 s2, m0
	s_mov_b32 m0, s92
	s_nop 4
	global_load_lds_dwordx4 v1, s[50:51]
	s_mov_b32 m0, s2
	s_add_u32 s2, s34, 0x20080
	s_addc_u32 s3, s35, 0
	s_mov_b32 s12, m0
	s_mov_b32 m0, s93
	s_nop 4
	global_load_lds_dwordx4 v1, s[2:3]
	s_mov_b32 m0, s12
	s_waitcnt vmcnt(8)
	s_waitcnt lgkmcnt(0)
	s_barrier
	s_waitcnt lgkmcnt(7)
	v_mfma_f32_16x16x32_bf16 v[54:57], v[130:133], v[182:185], v[54:57]
	v_mfma_f32_16x16x32_bf16 v[50:53], v[158:161], v[182:185], v[50:53]
	s_waitcnt lgkmcnt(5)
	v_mfma_f32_16x16x32_bf16 v[38:41], v[130:133], v[190:193], v[38:41]
	v_mfma_f32_16x16x32_bf16 v[34:37], v[158:161], v[190:193], v[34:37]
	s_waitcnt lgkmcnt(3)
	v_mfma_f32_16x16x32_bf16 v[22:25], v[130:133], v[198:201], v[22:25]
	v_mfma_f32_16x16x32_bf16 v[18:21], v[158:161], v[198:201], v[18:21]
	s_waitcnt lgkmcnt(1)
	v_mfma_f32_16x16x32_bf16 v[10:13], v[130:133], v[206:209], v[10:13]
	v_mfma_f32_16x16x32_bf16 v[6:9], v[158:161], v[206:209], v[6:9]
	v_mfma_f32_16x16x32_bf16 v[54:57], v[154:157], v[186:189], v[54:57]
	v_mfma_f32_16x16x32_bf16 v[50:53], v[162:165], v[186:189], v[50:53]
	v_mfma_f32_16x16x32_bf16 v[38:41], v[154:157], v[194:197], v[38:41]
	v_mfma_f32_16x16x32_bf16 v[34:37], v[162:165], v[194:197], v[34:37]
	v_mfma_f32_16x16x32_bf16 v[22:25], v[154:157], v[202:205], v[22:25]
	v_mfma_f32_16x16x32_bf16 v[18:21], v[162:165], v[202:205], v[18:21]
	s_waitcnt lgkmcnt(0)
	v_mfma_f32_16x16x32_bf16 v[10:13], v[154:157], v[210:213], v[10:13]
	v_mfma_f32_16x16x32_bf16 v[6:9], v[162:165], v[210:213], v[6:9]
	v_mfma_f32_16x16x32_bf16 v[62:65], v[166:169], v[182:185], v[62:65]
	v_mfma_f32_16x16x32_bf16 v[58:61], v[174:177], v[182:185], v[58:61]
	v_mfma_f32_16x16x32_bf16 v[46:49], v[166:169], v[190:193], v[46:49]
	v_mfma_f32_16x16x32_bf16 v[42:45], v[174:177], v[190:193], v[42:45]
	v_mfma_f32_16x16x32_bf16 v[30:33], v[166:169], v[198:201], v[30:33]
	v_mfma_f32_16x16x32_bf16 v[26:29], v[174:177], v[198:201], v[26:29]
	v_mfma_f32_16x16x32_bf16 v[14:17], v[166:169], v[206:209], v[14:17]
	v_mfma_f32_16x16x32_bf16 v[2:5], v[174:177], v[206:209], v[2:5]
	v_mfma_f32_16x16x32_bf16 v[62:65], v[170:173], v[186:189], v[62:65]
	v_mfma_f32_16x16x32_bf16 v[58:61], v[178:181], v[186:189], v[58:61]
	v_mfma_f32_16x16x32_bf16 v[46:49], v[170:173], v[194:197], v[46:49]
	v_mfma_f32_16x16x32_bf16 v[42:45], v[178:181], v[194:197], v[42:45]
	v_mfma_f32_16x16x32_bf16 v[30:33], v[170:173], v[202:205], v[30:33]
	v_mfma_f32_16x16x32_bf16 v[26:29], v[178:181], v[202:205], v[26:29]
	v_mfma_f32_16x16x32_bf16 v[14:17], v[170:173], v[210:213], v[14:17]
	v_mfma_f32_16x16x32_bf16 v[2:5], v[178:181], v[210:213], v[2:5]
	s_barrier
	s_add_i32 vcc_lo, vcc_lo, 2
	s_add_u32 s27, s27, 0x100
	s_addc_u32 s37, s37, 0
	s_cmp_gt_u32 vcc_lo, 13
	s_mov_b64 s[44:45], s[0:1]
	s_cbranch_scc0 .LBB0_752
	s_and_b64 vcc, exec, s[24:25]
	s_cbranch_vccz .LBB0_755
	s_barrier

.LBB0_800:
	v_add_u32_e32 v134, 0x10000, v139
	ds_read_b128 v[142:145], v134
	ds_read_b128 v[146:149], v134 offset:1024
	ds_read_b128 v[150:153], v134 offset:2048
	ds_read_b128 v[154:157], v134 offset:3072
	v_add_u32_e32 v134, 0x14000, v139
	ds_read_b128 v[158:161], v134
	ds_read_b128 v[162:165], v134 offset:1024
	ds_read_b128 v[166:169], v134 offset:2048
	ds_read_b128 v[170:173], v134 offset:3072
	s_add_u32 s0, s42, 0x100
	s_addc_u32 s1, s43, 0
	s_cmp_eq_u32 s88, 12
	s_cselect_b32 s34, s15, s0
	s_cselect_b32 s35, s14, s1
	s_cselect_b32 s50, s25, s86
	s_cselect_b32 s51, s11, s87
	s_add_u32 s44, s34, 0x80
	s_addc_u32 s45, s35, 0
	ds_read_b128 v[174:177], v140
	ds_read_b128 v[178:181], v140 offset:1024
	ds_read_b128 v[182:185], v140 offset:2048
	ds_read_b128 v[186:189], v140 offset:3072
	ds_read_b128 v[190:193], v140 offset:4096
	ds_read_b128 v[194:197], v140 offset:5120
	ds_read_b128 v[198:201], v140 offset:6144
	ds_read_b128 v[202:205], v140 offset:7168
	s_add_u32 s2, s42, 0x40080
	s_addc_u32 s3, s43, 0
	s_mov_b32 s12, m0
	s_mov_b32 m0, s67
	s_nop 4
	global_load_lds_dwordx4 v1, s[2:3]
	s_mov_b32 m0, s12
	s_add_u32 s2, s42, 0x60080
	s_addc_u32 s3, s43, 0
	s_add_i32 s12, s39, 0xe000
	s_mov_b32 s13, m0
	s_mov_b32 m0, s12
	s_nop 4
	global_load_lds_dwordx4 v1, s[2:3]
	s_mov_b32 m0, s13
	s_waitcnt vmcnt(8)
	s_waitcnt lgkmcnt(0)
	s_barrier
	s_waitcnt lgkmcnt(7)
	v_mfma_f32_16x16x32_bf16 v[122:125], v[142:145], v[174:177], v[122:125]
	v_mfma_f32_16x16x32_bf16 v[114:117], v[150:153], v[174:177], v[114:117]
	s_waitcnt lgkmcnt(5)
	v_mfma_f32_16x16x32_bf16 v[106:109], v[142:145], v[182:185], v[106:109]
	v_mfma_f32_16x16x32_bf16 v[98:101], v[150:153], v[182:185], v[98:101]
	s_waitcnt lgkmcnt(3)
	v_mfma_f32_16x16x32_bf16 v[90:93], v[142:145], v[190:193], v[90:93]
	v_mfma_f32_16x16x32_bf16 v[82:85], v[150:153], v[190:193], v[82:85]
	s_waitcnt lgkmcnt(1)
	v_mfma_f32_16x16x32_bf16 v[74:77], v[142:145], v[198:201], v[74:77]
	v_mfma_f32_16x16x32_bf16 v[66:69], v[150:153], v[198:201], v[66:69]
	v_mfma_f32_16x16x32_bf16 v[122:125], v[146:149], v[178:181], v[122:125]
	v_mfma_f32_16x16x32_bf16 v[114:117], v[154:157], v[178:181], v[114:117]
	v_mfma_f32_16x16x32_bf16 v[106:109], v[146:149], v[186:189], v[106:109]
	v_mfma_f32_16x16x32_bf16 v[98:101], v[154:157], v[186:189], v[98:101]
	v_mfma_f32_16x16x32_bf16 v[90:93], v[146:149], v[194:197], v[90:93]
	v_mfma_f32_16x16x32_bf16 v[82:85], v[154:157], v[194:197], v[82:85]
	s_waitcnt lgkmcnt(0)
	v_mfma_f32_16x16x32_bf16 v[74:77], v[146:149], v[202:205], v[74:77]
	v_mfma_f32_16x16x32_bf16 v[66:69], v[154:157], v[202:205], v[66:69]
	v_mfma_f32_16x16x32_bf16 v[126:129], v[158:161], v[174:177], v[126:129]
	v_mfma_f32_16x16x32_bf16 v[118:121], v[166:169], v[174:177], v[118:121]
	v_mfma_f32_16x16x32_bf16 v[110:113], v[158:161], v[182:185], v[110:113]
	v_mfma_f32_16x16x32_bf16 v[102:105], v[166:169], v[182:185], v[102:105]
	v_mfma_f32_16x16x32_bf16 v[94:97], v[158:161], v[190:193], v[94:97]
	v_mfma_f32_16x16x32_bf16 v[86:89], v[166:169], v[190:193], v[86:89]
	v_mfma_f32_16x16x32_bf16 v[78:81], v[158:161], v[198:201], v[78:81]
	v_mfma_f32_16x16x32_bf16 v[70:73], v[166:169], v[198:201], v[70:73]
	v_mfma_f32_16x16x32_bf16 v[126:129], v[162:165], v[178:181], v[126:129]
	v_mfma_f32_16x16x32_bf16 v[118:121], v[170:173], v[178:181], v[118:121]
	v_mfma_f32_16x16x32_bf16 v[110:113], v[162:165], v[186:189], v[110:113]
	v_mfma_f32_16x16x32_bf16 v[102:105], v[170:173], v[186:189], v[102:105]
	v_mfma_f32_16x16x32_bf16 v[94:97], v[162:165], v[194:197], v[94:97]
	v_mfma_f32_16x16x32_bf16 v[86:89], v[170:173], v[194:197], v[86:89]
	v_mfma_f32_16x16x32_bf16 v[78:81], v[162:165], v[202:205], v[78:81]
	v_mfma_f32_16x16x32_bf16 v[70:73], v[170:173], v[202:205], v[70:73]
	s_barrier
	ds_read_b128 v[174:177], v140 offset:16384
	ds_read_b128 v[178:181], v140 offset:17408
	ds_read_b128 v[182:185], v140 offset:18432
	ds_read_b128 v[186:189], v140 offset:19456
	ds_read_b128 v[190:193], v140 offset:20480
	ds_read_b128 v[194:197], v140 offset:21504
	ds_read_b128 v[198:201], v140 offset:22528
	ds_read_b128 v[202:205], v140 offset:23552
	s_mov_b32 s2, m0
	s_mov_b32 m0, s54
	s_nop 4
	global_load_lds_dwordx4 v136, s[50:51]
	s_mov_b32 m0, s2
	s_add_u32 s2, s50, 0x20000
	s_addc_u32 s3, s51, 0
	s_mov_b32 s12, m0
	s_mov_b32 m0, s55
	s_nop 4
	global_load_lds_dwordx4 v136, s[2:3]
	s_mov_b32 m0, s12
	s_add_u32 s2, s50, 0x40000
	s_addc_u32 s3, s51, 0
	s_mov_b32 s12, m0
	s_mov_b32 m0, s56
	s_nop 4
	global_load_lds_dwordx4 v136, s[2:3]
	s_mov_b32 m0, s12
	s_add_u32 s2, s50, 0x60000
	s_addc_u32 s3, s51, 0
	s_mov_b32 s12, m0
	s_mov_b32 m0, s57
	s_nop 4
	global_load_lds_dwordx4 v136, s[2:3]
	s_mov_b32 m0, s12
	s_mov_b32 s2, m0
	s_mov_b32 m0, s39
	s_nop 4
	global_load_lds_dwordx4 v1, s[34:35]
	s_mov_b32 m0, s2
	s_add_u32 s2, s34, 0x20000
	s_addc_u32 s3, s35, 0
	s_mov_b32 s12, m0
	s_mov_b32 m0, s58
	s_nop 4
	global_load_lds_dwordx4 v1, s[2:3]
	s_mov_b32 m0, s12
	s_waitcnt vmcnt(8)
	s_waitcnt lgkmcnt(0)
	s_barrier
	s_waitcnt lgkmcnt(7)
	v_mfma_f32_16x16x32_bf16 v[58:61], v[142:145], v[174:177], v[58:61]
	v_mfma_f32_16x16x32_bf16 v[50:53], v[150:153], v[174:177], v[50:53]
	s_waitcnt lgkmcnt(5)
	v_mfma_f32_16x16x32_bf16 v[42:45], v[142:145], v[182:185], v[42:45]
	v_mfma_f32_16x16x32_bf16 v[34:37], v[150:153], v[182:185], v[34:37]
	s_waitcnt lgkmcnt(3)
	v_mfma_f32_16x16x32_bf16 v[26:29], v[142:145], v[190:193], v[26:29]
	v_mfma_f32_16x16x32_bf16 v[18:21], v[150:153], v[190:193], v[18:21]
	s_waitcnt lgkmcnt(1)
	v_mfma_f32_16x16x32_bf16 v[10:13], v[142:145], v[198:201], v[10:13]
	v_mfma_f32_16x16x32_bf16 v[6:9], v[150:153], v[198:201], v[6:9]
	v_mfma_f32_16x16x32_bf16 v[58:61], v[146:149], v[178:181], v[58:61]
	v_mfma_f32_16x16x32_bf16 v[50:53], v[154:157], v[178:181], v[50:53]
	v_mfma_f32_16x16x32_bf16 v[42:45], v[146:149], v[186:189], v[42:45]
	v_mfma_f32_16x16x32_bf16 v[34:37], v[154:157], v[186:189], v[34:37]
	v_mfma_f32_16x16x32_bf16 v[26:29], v[146:149], v[194:197], v[26:29]
	v_mfma_f32_16x16x32_bf16 v[18:21], v[154:157], v[194:197], v[18:21]
	s_waitcnt lgkmcnt(0)
	v_mfma_f32_16x16x32_bf16 v[10:13], v[146:149], v[202:205], v[10:13]
	v_mfma_f32_16x16x32_bf16 v[6:9], v[154:157], v[202:205], v[6:9]
	v_mfma_f32_16x16x32_bf16 v[62:65], v[158:161], v[174:177], v[62:65]
	v_mfma_f32_16x16x32_bf16 v[54:57], v[166:169], v[174:177], v[54:57]
	v_mfma_f32_16x16x32_bf16 v[46:49], v[158:161], v[182:185], v[46:49]
	v_mfma_f32_16x16x32_bf16 v[38:41], v[166:169], v[182:185], v[38:41]
	v_mfma_f32_16x16x32_bf16 v[30:33], v[158:161], v[190:193], v[30:33]
	v_mfma_f32_16x16x32_bf16 v[22:25], v[166:169], v[190:193], v[22:25]
	v_mfma_f32_16x16x32_bf16 v[14:17], v[158:161], v[198:201], v[14:17]
	v_mfma_f32_16x16x32_bf16 v[2:5], v[166:169], v[198:201], v[2:5]
	v_mfma_f32_16x16x32_bf16 v[62:65], v[162:165], v[178:181], v[62:65]
	v_mfma_f32_16x16x32_bf16 v[54:57], v[170:173], v[178:181], v[54:57]
	v_mfma_f32_16x16x32_bf16 v[46:49], v[162:165], v[186:189], v[46:49]
	v_mfma_f32_16x16x32_bf16 v[38:41], v[170:173], v[186:189], v[38:41]
	v_mfma_f32_16x16x32_bf16 v[30:33], v[162:165], v[194:197], v[30:33]
	v_mfma_f32_16x16x32_bf16 v[22:25], v[170:173], v[194:197], v[22:25]
	v_mfma_f32_16x16x32_bf16 v[14:17], v[162:165], v[202:205], v[14:17]
	v_mfma_f32_16x16x32_bf16 v[2:5], v[170:173], v[202:205], v[2:5]
	s_barrier
	v_add_u32_e32 v134, 0x18000, v139
	ds_read_b128 v[142:145], v134
	ds_read_b128 v[146:149], v134 offset:1024
	ds_read_b128 v[150:153], v134 offset:2048
	ds_read_b128 v[154:157], v134 offset:3072
	v_add_u32_e32 v134, 0x1c000, v139
	ds_read_b128 v[158:161], v134
	ds_read_b128 v[162:165], v134 offset:1024
	ds_read_b128 v[166:169], v134 offset:2048
	ds_read_b128 v[170:173], v134 offset:3072
	ds_read_b128 v[174:177], v140 offset:32768
	ds_read_b128 v[178:181], v140 offset:33792
	ds_read_b128 v[182:185], v140 offset:34816
	ds_read_b128 v[186:189], v140 offset:35840
	ds_read_b128 v[190:193], v140 offset:36864
	ds_read_b128 v[194:197], v140 offset:37888
	ds_read_b128 v[198:201], v140 offset:38912
	ds_read_b128 v[202:205], v140 offset:39936
	s_add_u32 s2, s34, 0x40000
	s_addc_u32 s3, s35, 0
	s_mov_b32 s12, m0
	s_mov_b32 m0, s59
	s_nop 4
	global_load_lds_dwordx4 v1, s[2:3]
	s_mov_b32 m0, s12
	s_add_u32 s2, s34, 0x60000
	s_addc_u32 s3, s35, 0
	s_mov_b32 s12, m0
	s_mov_b32 m0, s60
	s_nop 4
	global_load_lds_dwordx4 v1, s[2:3]
	s_mov_b32 m0, s12
	s_waitcnt vmcnt(8)
	s_waitcnt lgkmcnt(0)
	s_barrier
	s_waitcnt lgkmcnt(7)
	v_mfma_f32_16x16x32_bf16 v[122:125], v[142:145], v[174:177], v[122:125]
	v_mfma_f32_16x16x32_bf16 v[114:117], v[150:153], v[174:177], v[114:117]
	s_waitcnt lgkmcnt(5)
	v_mfma_f32_16x16x32_bf16 v[106:109], v[142:145], v[182:185], v[106:109]
	v_mfma_f32_16x16x32_bf16 v[98:101], v[150:153], v[182:185], v[98:101]
	s_waitcnt lgkmcnt(3)
	v_mfma_f32_16x16x32_bf16 v[90:93], v[142:145], v[190:193], v[90:93]
	v_mfma_f32_16x16x32_bf16 v[82:85], v[150:153], v[190:193], v[82:85]
	s_waitcnt lgkmcnt(1)
	v_mfma_f32_16x16x32_bf16 v[74:77], v[142:145], v[198:201], v[74:77]
	v_mfma_f32_16x16x32_bf16 v[66:69], v[150:153], v[198:201], v[66:69]
	v_mfma_f32_16x16x32_bf16 v[122:125], v[146:149], v[178:181], v[122:125]
	v_mfma_f32_16x16x32_bf16 v[114:117], v[154:157], v[178:181], v[114:117]
	v_mfma_f32_16x16x32_bf16 v[106:109], v[146:149], v[186:189], v[106:109]
	v_mfma_f32_16x16x32_bf16 v[98:101], v[154:157], v[186:189], v[98:101]
	v_mfma_f32_16x16x32_bf16 v[90:93], v[146:149], v[194:197], v[90:93]
	v_mfma_f32_16x16x32_bf16 v[82:85], v[154:157], v[194:197], v[82:85]
	s_waitcnt lgkmcnt(0)
	v_mfma_f32_16x16x32_bf16 v[74:77], v[146:149], v[202:205], v[74:77]
	v_mfma_f32_16x16x32_bf16 v[66:69], v[154:157], v[202:205], v[66:69]
	v_mfma_f32_16x16x32_bf16 v[126:129], v[158:161], v[174:177], v[126:129]
	v_mfma_f32_16x16x32_bf16 v[118:121], v[166:169], v[174:177], v[118:121]
	v_mfma_f32_16x16x32_bf16 v[110:113], v[158:161], v[182:185], v[110:113]
	v_mfma_f32_16x16x32_bf16 v[102:105], v[166:169], v[182:185], v[102:105]
	v_mfma_f32_16x16x32_bf16 v[94:97], v[158:161], v[190:193], v[94:97]
	v_mfma_f32_16x16x32_bf16 v[86:89], v[166:169], v[190:193], v[86:89]
	v_mfma_f32_16x16x32_bf16 v[78:81], v[158:161], v[198:201], v[78:81]
	v_mfma_f32_16x16x32_bf16 v[70:73], v[166:169], v[198:201], v[70:73]
	v_mfma_f32_16x16x32_bf16 v[126:129], v[162:165], v[178:181], v[126:129]
	v_mfma_f32_16x16x32_bf16 v[118:121], v[170:173], v[178:181], v[118:121]
	v_mfma_f32_16x16x32_bf16 v[110:113], v[162:165], v[186:189], v[110:113]
	v_mfma_f32_16x16x32_bf16 v[102:105], v[170:173], v[186:189], v[102:105]
	v_mfma_f32_16x16x32_bf16 v[94:97], v[162:165], v[194:197], v[94:97]
	v_mfma_f32_16x16x32_bf16 v[86:89], v[170:173], v[194:197], v[86:89]
	v_mfma_f32_16x16x32_bf16 v[78:81], v[162:165], v[202:205], v[78:81]
	v_mfma_f32_16x16x32_bf16 v[70:73], v[170:173], v[202:205], v[70:73]
	s_barrier
	s_add_u32 s2, s50, 0x80
	s_addc_u32 s3, s51, 0
	ds_read_b128 v[174:177], v140 offset:49152
	ds_read_b128 v[178:181], v140 offset:50176
	ds_read_b128 v[182:185], v140 offset:51200
	ds_read_b128 v[186:189], v140 offset:52224
	ds_read_b128 v[190:193], v140 offset:53248
	ds_read_b128 v[194:197], v140 offset:54272
	ds_read_b128 v[198:201], v140 offset:55296
	ds_read_b128 v[202:205], v140 offset:56320
	s_mov_b32 s12, m0
	s_mov_b32 m0, s61
	s_nop 4
	global_load_lds_dwordx4 v136, s[2:3]
	s_mov_b32 m0, s12
	s_add_u32 s2, s50, 0x20080
	s_addc_u32 s3, s51, 0
	s_mov_b32 s12, m0
	s_mov_b32 m0, s62
	s_nop 4
	global_load_lds_dwordx4 v136, s[2:3]
	s_mov_b32 m0, s12
	s_add_u32 s2, s50, 0x40080
	s_addc_u32 s3, s51, 0
	s_mov_b32 s12, m0
	s_mov_b32 m0, s65
	s_nop 4
	global_load_lds_dwordx4 v136, s[2:3]
	s_mov_b32 m0, s12
	s_add_u32 s2, s50, 0x60080
	s_addc_u32 s3, s51, 0
	s_mov_b32 s12, m0
	s_mov_b32 m0, s66
	s_nop 4
	global_load_lds_dwordx4 v136, s[2:3]
	s_mov_b32 m0, s12
	s_mov_b32 s2, m0
	s_mov_b32 m0, s63
	s_nop 4
	global_load_lds_dwordx4 v1, s[44:45]
	s_mov_b32 m0, s2
	s_add_u32 s2, s34, 0x20080
	s_addc_u32 s3, s35, 0
	s_mov_b32 s12, m0
	s_mov_b32 m0, s64
	s_nop 4
	global_load_lds_dwordx4 v1, s[2:3]
	s_mov_b32 m0, s12
	s_waitcnt vmcnt(8)
	s_waitcnt lgkmcnt(0)
	s_barrier
	s_waitcnt lgkmcnt(7)
	v_mfma_f32_16x16x32_bf16 v[58:61], v[142:145], v[174:177], v[58:61]
	v_mfma_f32_16x16x32_bf16 v[50:53], v[150:153], v[174:177], v[50:53]
	s_waitcnt lgkmcnt(5)
	v_mfma_f32_16x16x32_bf16 v[42:45], v[142:145], v[182:185], v[42:45]
	v_mfma_f32_16x16x32_bf16 v[34:37], v[150:153], v[182:185], v[34:37]
	s_waitcnt lgkmcnt(3)
	v_mfma_f32_16x16x32_bf16 v[26:29], v[142:145], v[190:193], v[26:29]
	v_mfma_f32_16x16x32_bf16 v[18:21], v[150:153], v[190:193], v[18:21]
	s_waitcnt lgkmcnt(1)
	v_mfma_f32_16x16x32_bf16 v[10:13], v[142:145], v[198:201], v[10:13]
	v_mfma_f32_16x16x32_bf16 v[6:9], v[150:153], v[198:201], v[6:9]
	v_mfma_f32_16x16x32_bf16 v[58:61], v[146:149], v[178:181], v[58:61]
	v_mfma_f32_16x16x32_bf16 v[50:53], v[154:157], v[178:181], v[50:53]
	v_mfma_f32_16x16x32_bf16 v[42:45], v[146:149], v[186:189], v[42:45]
	v_mfma_f32_16x16x32_bf16 v[34:37], v[154:157], v[186:189], v[34:37]
	v_mfma_f32_16x16x32_bf16 v[26:29], v[146:149], v[194:197], v[26:29]
	v_mfma_f32_16x16x32_bf16 v[18:21], v[154:157], v[194:197], v[18:21]
	s_waitcnt lgkmcnt(0)
	v_mfma_f32_16x16x32_bf16 v[10:13], v[146:149], v[202:205], v[10:13]
	v_mfma_f32_16x16x32_bf16 v[6:9], v[154:157], v[202:205], v[6:9]
	v_mfma_f32_16x16x32_bf16 v[62:65], v[158:161], v[174:177], v[62:65]
	v_mfma_f32_16x16x32_bf16 v[54:57], v[166:169], v[174:177], v[54:57]
	v_mfma_f32_16x16x32_bf16 v[46:49], v[158:161], v[182:185], v[46:49]
	v_mfma_f32_16x16x32_bf16 v[38:41], v[166:169], v[182:185], v[38:41]
	v_mfma_f32_16x16x32_bf16 v[30:33], v[158:161], v[190:193], v[30:33]
	v_mfma_f32_16x16x32_bf16 v[22:25], v[166:169], v[190:193], v[22:25]
	v_mfma_f32_16x16x32_bf16 v[14:17], v[158:161], v[198:201], v[14:17]
	v_mfma_f32_16x16x32_bf16 v[2:5], v[166:169], v[198:201], v[2:5]
	v_mfma_f32_16x16x32_bf16 v[62:65], v[162:165], v[178:181], v[62:65]
	v_mfma_f32_16x16x32_bf16 v[54:57], v[170:173], v[178:181], v[54:57]
	v_mfma_f32_16x16x32_bf16 v[46:49], v[162:165], v[186:189], v[46:49]
	v_mfma_f32_16x16x32_bf16 v[38:41], v[170:173], v[186:189], v[38:41]
	v_mfma_f32_16x16x32_bf16 v[30:33], v[162:165], v[194:197], v[30:33]
	v_mfma_f32_16x16x32_bf16 v[22:25], v[170:173], v[194:197], v[22:25]
	v_mfma_f32_16x16x32_bf16 v[14:17], v[162:165], v[202:205], v[14:17]
	v_mfma_f32_16x16x32_bf16 v[2:5], v[170:173], v[202:205], v[2:5]
	s_barrier
	s_add_i32 s88, s88, 2
	s_add_u32 s86, s86, 0x100
	s_addc_u32 s87, s87, 0
	s_cmp_gt_u32 s88, 13
	s_mov_b64 s[42:43], s[0:1]
	s_cbranch_scc0 .LBB0_800
	s_and_b64 vcc, exec, s[8:9]
	s_cbranch_vccz .LBB0_803
	s_barrier

.LBB0_875:
	ds_read_b128 v[138:141], v132
	ds_read_b128 v[142:145], v132 offset:1024
	ds_read_b128 v[146:149], v132 offset:2048
	ds_read_b128 v[150:153], v132 offset:3072
	ds_read_b128 v[154:157], v134
	ds_read_b128 v[158:161], v134 offset:1024
	ds_read_b128 v[182:185], v134 offset:2048
	ds_read_b128 v[186:189], v134 offset:3072
	s_add_u32 s0, s34, 0x100
	s_addc_u32 s1, s35, 0
	s_cmp_eq_u32 s97, 18
	s_cselect_b32 s50, s8, s0
	s_cselect_b32 s51, s9, s1
	s_cselect_b32 s44, s4, s95
	s_cselect_b32 s45, s5, s96
	s_add_u32 s52, s50, 0x80
	s_addc_u32 s53, s51, 0
	s_add_u32 s12, s34, 0x58080
	s_addc_u32 s13, s35, 0
	s_mov_b32 m0, s94
	s_nop 4
	global_load_lds_dwordx4 v130, s[12:13]
	s_add_u32 s12, s34, 0x84080
	s_addc_u32 s13, s35, 0
	s_add_i32 s34, s66, 0xe000
	s_mov_b32 m0, s34
	s_nop 4
	global_load_lds_dwordx4 v130, s[12:13]
	ds_read_b128 v[190:193], v133
	ds_read_b128 v[194:197], v133 offset:1024
	ds_read_b128 v[198:201], v133 offset:2048
	ds_read_b128 v[202:205], v133 offset:3072
	ds_read_b128 v[206:209], v133 offset:4096
	ds_read_b128 v[210:213], v133 offset:5120
	ds_read_b128 v[214:217], v133 offset:6144
	ds_read_b128 v[218:221], v133 offset:7168
	s_waitcnt vmcnt(8)
	s_waitcnt lgkmcnt(0)
	s_barrier
	v_mfma_f32_16x16x128_f8f6f4 v[14:17], v[138:145], v[190:197], v[14:17]
	v_mfma_f32_16x16x128_f8f6f4 v[30:33], v[138:145], v[198:205], v[30:33]
	v_mfma_f32_16x16x128_f8f6f4 v[50:53], v[138:145], v[206:213], v[50:53]
	v_mfma_f32_16x16x128_f8f6f4 v[62:65], v[138:145], v[214:221], v[62:65]
	v_mfma_f32_16x16x128_f8f6f4 v[10:13], v[146:153], v[190:197], v[10:13]
	v_mfma_f32_16x16x128_f8f6f4 v[26:29], v[146:153], v[198:205], v[26:29]
	v_mfma_f32_16x16x128_f8f6f4 v[42:45], v[146:153], v[206:213], v[42:45]
	v_mfma_f32_16x16x128_f8f6f4 v[58:61], v[146:153], v[214:221], v[58:61]
	v_mfma_f32_16x16x128_f8f6f4 v[6:9], v[154:161], v[190:197], v[6:9]
	v_mfma_f32_16x16x128_f8f6f4 v[22:25], v[154:161], v[198:205], v[22:25]
	v_mfma_f32_16x16x128_f8f6f4 v[38:41], v[154:161], v[206:213], v[38:41]
	v_mfma_f32_16x16x128_f8f6f4 v[54:57], v[154:161], v[214:221], v[54:57]
	v_mfma_f32_16x16x128_f8f6f4 v[2:5], v[182:189], v[190:197], v[2:5]
	v_mfma_f32_16x16x128_f8f6f4 v[18:21], v[182:189], v[198:205], v[18:21]
	v_mfma_f32_16x16x128_f8f6f4 v[34:37], v[182:189], v[206:213], v[34:37]
	v_mfma_f32_16x16x128_f8f6f4 v[46:49], v[182:189], v[214:221], v[46:49]
	s_barrier
	ds_read_b128 v[190:193], v133 offset:16384
	ds_read_b128 v[194:197], v133 offset:17408
	ds_read_b128 v[198:201], v133 offset:18432
	ds_read_b128 v[202:205], v133 offset:19456
	ds_read_b128 v[206:209], v133 offset:20480
	ds_read_b128 v[210:213], v133 offset:21504
	ds_read_b128 v[214:217], v133 offset:22528
	ds_read_b128 v[218:221], v133 offset:23552
	s_mov_b32 m0, s67
	s_nop 4
	global_load_lds_dwordx4 v131, s[44:45]
	s_add_u32 s12, s44, 0x2c000
	s_addc_u32 s13, s45, 0
	s_mov_b32 m0, s73
	s_nop 4
	global_load_lds_dwordx4 v131, s[12:13]
	s_add_u32 s12, s44, 0x58000
	s_addc_u32 s13, s45, 0
	s_mov_b32 m0, s84
	s_nop 4
	global_load_lds_dwordx4 v131, s[12:13]
	s_add_u32 s12, s44, 0x84000
	s_addc_u32 s13, s45, 0
	s_mov_b32 m0, s85
	s_nop 4
	global_load_lds_dwordx4 v131, s[12:13]
	s_mov_b32 m0, s66
	s_nop 4
	global_load_lds_dwordx4 v130, s[50:51]
	s_add_u32 s12, s50, 0x2c000
	s_addc_u32 s13, s51, 0
	s_mov_b32 m0, s82
	s_nop 4
	global_load_lds_dwordx4 v130, s[12:13]
	s_waitcnt vmcnt(8)
	s_waitcnt lgkmcnt(0)
	s_barrier
	v_mfma_f32_16x16x128_f8f6f4 v[78:81], v[138:145], v[190:197], v[78:81]
	v_mfma_f32_16x16x128_f8f6f4 v[94:97], v[138:145], v[198:205], v[94:97]
	v_mfma_f32_16x16x128_f8f6f4 v[126:129], v[138:145], v[206:213], v[126:129]
	v_mfma_f32_16x16x128_f8f6f4 v[98:101], v[138:145], v[214:221], v[98:101]
	v_mfma_f32_16x16x128_f8f6f4 v[74:77], v[146:153], v[190:197], v[74:77]
	v_mfma_f32_16x16x128_f8f6f4 v[90:93], v[146:153], v[198:205], v[90:93]
	v_mfma_f32_16x16x128_f8f6f4 v[114:117], v[146:153], v[206:213], v[114:117]
	v_mfma_f32_16x16x128_f8f6f4 v[122:125], v[146:153], v[214:221], v[122:125]
	v_mfma_f32_16x16x128_f8f6f4 v[70:73], v[154:161], v[190:197], v[70:73]
	v_mfma_f32_16x16x128_f8f6f4 v[86:89], v[154:161], v[198:205], v[86:89]
	v_mfma_f32_16x16x128_f8f6f4 v[106:109], v[154:161], v[206:213], v[106:109]
	v_mfma_f32_16x16x128_f8f6f4 v[118:121], v[154:161], v[214:221], v[118:121]
	v_mfma_f32_16x16x128_f8f6f4 v[66:69], v[182:189], v[190:197], v[66:69]
	v_mfma_f32_16x16x128_f8f6f4 v[82:85], v[182:189], v[198:205], v[82:85]
	v_mfma_f32_16x16x128_f8f6f4 v[102:105], v[182:189], v[206:213], v[102:105]
	v_mfma_f32_16x16x128_f8f6f4 v[110:113], v[182:189], v[214:221], v[110:113]
	s_barrier
	ds_read_b128 v[138:141], v135
	ds_read_b128 v[142:145], v135 offset:1024
	ds_read_b128 v[146:149], v135 offset:2048
	ds_read_b128 v[150:153], v135 offset:3072
	ds_read_b128 v[154:157], v136
	ds_read_b128 v[158:161], v136 offset:1024
	ds_read_b128 v[182:185], v136 offset:2048
	ds_read_b128 v[186:189], v136 offset:3072
	s_add_u32 s12, s50, 0x58000
	s_addc_u32 s13, s51, 0
	s_mov_b32 m0, s86
	s_nop 4
	global_load_lds_dwordx4 v130, s[12:13]
	s_add_u32 s12, s50, 0x84000
	s_addc_u32 s13, s51, 0
	s_mov_b32 m0, s87
	s_nop 4
	global_load_lds_dwordx4 v130, s[12:13]
	ds_read_b128 v[190:193], v133 offset:32768
	ds_read_b128 v[194:197], v133 offset:33792
	ds_read_b128 v[198:201], v133 offset:34816
	ds_read_b128 v[202:205], v133 offset:35840
	ds_read_b128 v[206:209], v133 offset:36864
	ds_read_b128 v[210:213], v133 offset:37888
	ds_read_b128 v[214:217], v133 offset:38912
	ds_read_b128 v[218:221], v133 offset:39936
	s_waitcnt vmcnt(8)
	s_waitcnt lgkmcnt(0)
	s_barrier
	v_mfma_f32_16x16x128_f8f6f4 v[14:17], v[138:145], v[190:197], v[14:17]
	v_mfma_f32_16x16x128_f8f6f4 v[30:33], v[138:145], v[198:205], v[30:33]
	v_mfma_f32_16x16x128_f8f6f4 v[50:53], v[138:145], v[206:213], v[50:53]
	v_mfma_f32_16x16x128_f8f6f4 v[62:65], v[138:145], v[214:221], v[62:65]
	v_mfma_f32_16x16x128_f8f6f4 v[10:13], v[146:153], v[190:197], v[10:13]
	v_mfma_f32_16x16x128_f8f6f4 v[26:29], v[146:153], v[198:205], v[26:29]
	v_mfma_f32_16x16x128_f8f6f4 v[42:45], v[146:153], v[206:213], v[42:45]
	v_mfma_f32_16x16x128_f8f6f4 v[58:61], v[146:153], v[214:221], v[58:61]
	v_mfma_f32_16x16x128_f8f6f4 v[6:9], v[154:161], v[190:197], v[6:9]
	v_mfma_f32_16x16x128_f8f6f4 v[22:25], v[154:161], v[198:205], v[22:25]
	v_mfma_f32_16x16x128_f8f6f4 v[38:41], v[154:161], v[206:213], v[38:41]
	v_mfma_f32_16x16x128_f8f6f4 v[54:57], v[154:161], v[214:221], v[54:57]
	v_mfma_f32_16x16x128_f8f6f4 v[2:5], v[182:189], v[190:197], v[2:5]
	v_mfma_f32_16x16x128_f8f6f4 v[18:21], v[182:189], v[198:205], v[18:21]
	v_mfma_f32_16x16x128_f8f6f4 v[34:37], v[182:189], v[206:213], v[34:37]
	v_mfma_f32_16x16x128_f8f6f4 v[46:49], v[182:189], v[214:221], v[46:49]
	s_barrier
	ds_read_b128 v[190:193], v133 offset:49152
	ds_read_b128 v[194:197], v133 offset:50176
	ds_read_b128 v[198:201], v133 offset:51200
	ds_read_b128 v[202:205], v133 offset:52224
	ds_read_b128 v[206:209], v133 offset:53248
	ds_read_b128 v[210:213], v133 offset:54272
	ds_read_b128 v[214:217], v133 offset:55296
	ds_read_b128 v[218:221], v133 offset:56320
	s_add_u32 s12, s44, 0x80
	s_addc_u32 s13, s45, 0
	s_mov_b32 m0, s88
	s_nop 4
	global_load_lds_dwordx4 v131, s[12:13]
	s_add_u32 s12, s44, 0x2c080
	s_addc_u32 s13, s45, 0
	s_mov_b32 m0, s89
	s_nop 4
	global_load_lds_dwordx4 v131, s[12:13]
	s_add_u32 s12, s44, 0x58080
	s_addc_u32 s13, s45, 0
	s_mov_b32 m0, s92
	s_nop 4
	global_load_lds_dwordx4 v131, s[12:13]
	s_add_u32 s12, s44, 0x84080
	s_addc_u32 s13, s45, 0
	s_mov_b32 m0, s93
	s_nop 4
	global_load_lds_dwordx4 v131, s[12:13]
	s_mov_b32 m0, s90
	s_nop 4
	global_load_lds_dwordx4 v130, s[52:53]
	s_add_u32 s12, s50, 0x2c080
	s_addc_u32 s13, s51, 0
	s_mov_b32 m0, s91
	s_nop 4
	global_load_lds_dwordx4 v130, s[12:13]
	s_waitcnt vmcnt(8)
	s_waitcnt lgkmcnt(0)
	s_barrier
	v_mfma_f32_16x16x128_f8f6f4 v[78:81], v[138:145], v[190:197], v[78:81]
	v_mfma_f32_16x16x128_f8f6f4 v[94:97], v[138:145], v[198:205], v[94:97]
	v_mfma_f32_16x16x128_f8f6f4 v[126:129], v[138:145], v[206:213], v[126:129]
	v_mfma_f32_16x16x128_f8f6f4 v[98:101], v[138:145], v[214:221], v[98:101]
	v_mfma_f32_16x16x128_f8f6f4 v[74:77], v[146:153], v[190:197], v[74:77]
	v_mfma_f32_16x16x128_f8f6f4 v[90:93], v[146:153], v[198:205], v[90:93]
	v_mfma_f32_16x16x128_f8f6f4 v[114:117], v[146:153], v[206:213], v[114:117]
	v_mfma_f32_16x16x128_f8f6f4 v[122:125], v[146:153], v[214:221], v[122:125]
	v_mfma_f32_16x16x128_f8f6f4 v[70:73], v[154:161], v[190:197], v[70:73]
	v_mfma_f32_16x16x128_f8f6f4 v[86:89], v[154:161], v[198:205], v[86:89]
	v_mfma_f32_16x16x128_f8f6f4 v[106:109], v[154:161], v[206:213], v[106:109]
	v_mfma_f32_16x16x128_f8f6f4 v[118:121], v[154:161], v[214:221], v[118:121]
	v_mfma_f32_16x16x128_f8f6f4 v[66:69], v[182:189], v[190:197], v[66:69]
	v_mfma_f32_16x16x128_f8f6f4 v[82:85], v[182:189], v[198:205], v[82:85]
	v_mfma_f32_16x16x128_f8f6f4 v[102:105], v[182:189], v[206:213], v[102:105]
	v_mfma_f32_16x16x128_f8f6f4 v[110:113], v[182:189], v[214:221], v[110:113]
	s_add_i32 s97, s97, 2
	s_add_u32 s95, s95, 0x100
	s_addc_u32 s96, s96, 0
	s_cmp_lt_u32 s97, 20
	s_mov_b64 s[34:35], s[0:1]
	s_barrier
	s_cbranch_scc1 .LBB0_875
	s_waitcnt vmcnt(0)
	s_cmpk_gt_u32 s64, 0xff
	s_cbranch_scc1 .LBB0_878
	s_barrier

.LBB0_988:
	v_add_u32_e32 v130, 0x10000, v150
	ds_read_b128 v[152:155], v130
	ds_read_b128 v[156:159], v130 offset:1024
	ds_read_b128 v[160:163], v130 offset:2048
	ds_read_b128 v[164:167], v130 offset:3072
	v_add_u32_e32 v130, 0x14000, v150
	ds_read_b128 v[168:171], v130
	ds_read_b128 v[172:175], v130 offset:1024
	ds_read_b128 v[176:179], v130 offset:2048
	ds_read_b128 v[180:183], v130 offset:3072
	s_add_u32 s0, s40, 0x100
	s_addc_u32 s1, s41, 0
	s_cmp_eq_u32 s88, 12
	s_cselect_b32 s34, s15, s0
	s_cselect_b32 s35, s14, s1
	s_cselect_b32 s44, s25, s86
	s_cselect_b32 s45, s11, s87
	s_add_u32 s42, s34, 0x80
	s_addc_u32 s43, s35, 0
	ds_read_b128 v[184:187], v151
	ds_read_b128 v[188:191], v151 offset:1024
	ds_read_b128 v[192:195], v151 offset:2048
	ds_read_b128 v[196:199], v151 offset:3072
	ds_read_b128 v[200:203], v151 offset:4096
	ds_read_b128 v[204:207], v151 offset:5120
	ds_read_b128 v[208:211], v151 offset:6144
	ds_read_b128 v[212:215], v151 offset:7168
	s_add_u32 s12, s40, 0x40080
	s_addc_u32 s13, s41, 0
	s_mov_b32 s89, m0
	s_mov_b32 m0, s82
	s_nop 4
	global_load_lds_dwordx4 v1, s[12:13]
	s_mov_b32 m0, s89
	s_add_u32 s12, s40, 0x60080
	s_addc_u32 s13, s41, 0
	s_add_i32 s40, s54, 0xe000
	s_mov_b32 s41, m0
	s_mov_b32 m0, s40
	s_nop 4
	global_load_lds_dwordx4 v1, s[12:13]
	s_mov_b32 m0, s41
	s_waitcnt vmcnt(8)
	s_waitcnt lgkmcnt(0)
	s_barrier
	s_waitcnt lgkmcnt(7)
	v_mfma_f32_16x16x32_bf16 v[122:125], v[152:155], v[184:187], v[122:125]
	v_mfma_f32_16x16x32_bf16 v[114:117], v[160:163], v[184:187], v[114:117]
	s_waitcnt lgkmcnt(5)
	v_mfma_f32_16x16x32_bf16 v[106:109], v[152:155], v[192:195], v[106:109]
	v_mfma_f32_16x16x32_bf16 v[98:101], v[160:163], v[192:195], v[98:101]
	s_waitcnt lgkmcnt(3)
	v_mfma_f32_16x16x32_bf16 v[90:93], v[152:155], v[200:203], v[90:93]
	v_mfma_f32_16x16x32_bf16 v[82:85], v[160:163], v[200:203], v[82:85]
	s_waitcnt lgkmcnt(1)
	v_mfma_f32_16x16x32_bf16 v[74:77], v[152:155], v[208:211], v[74:77]
	v_mfma_f32_16x16x32_bf16 v[66:69], v[160:163], v[208:211], v[66:69]
	v_mfma_f32_16x16x32_bf16 v[122:125], v[156:159], v[188:191], v[122:125]
	v_mfma_f32_16x16x32_bf16 v[114:117], v[164:167], v[188:191], v[114:117]
	v_mfma_f32_16x16x32_bf16 v[106:109], v[156:159], v[196:199], v[106:109]
	v_mfma_f32_16x16x32_bf16 v[98:101], v[164:167], v[196:199], v[98:101]
	v_mfma_f32_16x16x32_bf16 v[90:93], v[156:159], v[204:207], v[90:93]
	v_mfma_f32_16x16x32_bf16 v[82:85], v[164:167], v[204:207], v[82:85]
	s_waitcnt lgkmcnt(0)
	v_mfma_f32_16x16x32_bf16 v[74:77], v[156:159], v[212:215], v[74:77]
	v_mfma_f32_16x16x32_bf16 v[66:69], v[164:167], v[212:215], v[66:69]
	v_mfma_f32_16x16x32_bf16 v[126:129], v[168:171], v[184:187], v[126:129]
	v_mfma_f32_16x16x32_bf16 v[118:121], v[176:179], v[184:187], v[118:121]
	v_mfma_f32_16x16x32_bf16 v[110:113], v[168:171], v[192:195], v[110:113]
	v_mfma_f32_16x16x32_bf16 v[102:105], v[176:179], v[192:195], v[102:105]
	v_mfma_f32_16x16x32_bf16 v[94:97], v[168:171], v[200:203], v[94:97]
	v_mfma_f32_16x16x32_bf16 v[86:89], v[176:179], v[200:203], v[86:89]
	v_mfma_f32_16x16x32_bf16 v[78:81], v[168:171], v[208:211], v[78:81]
	v_mfma_f32_16x16x32_bf16 v[70:73], v[176:179], v[208:211], v[70:73]
	v_mfma_f32_16x16x32_bf16 v[126:129], v[172:175], v[188:191], v[126:129]
	v_mfma_f32_16x16x32_bf16 v[118:121], v[180:183], v[188:191], v[118:121]
	v_mfma_f32_16x16x32_bf16 v[110:113], v[172:175], v[196:199], v[110:113]
	v_mfma_f32_16x16x32_bf16 v[102:105], v[180:183], v[196:199], v[102:105]
	v_mfma_f32_16x16x32_bf16 v[94:97], v[172:175], v[204:207], v[94:97]
	v_mfma_f32_16x16x32_bf16 v[86:89], v[180:183], v[204:207], v[86:89]
	v_mfma_f32_16x16x32_bf16 v[78:81], v[172:175], v[212:215], v[78:81]
	v_mfma_f32_16x16x32_bf16 v[70:73], v[180:183], v[212:215], v[70:73]
	s_barrier
	ds_read_b128 v[184:187], v151 offset:16384
	ds_read_b128 v[188:191], v151 offset:17408
	ds_read_b128 v[192:195], v151 offset:18432
	ds_read_b128 v[196:199], v151 offset:19456
	ds_read_b128 v[200:203], v151 offset:20480
	ds_read_b128 v[204:207], v151 offset:21504
	ds_read_b128 v[208:211], v151 offset:22528
	ds_read_b128 v[212:215], v151 offset:23552
	s_mov_b32 s12, m0
	s_mov_b32 m0, s56
	s_nop 4
	global_load_lds_dwordx4 v144, s[44:45]
	s_mov_b32 m0, s12
	s_add_u32 s12, s44, 0x20000
	s_addc_u32 s13, s45, 0
	s_mov_b32 s40, m0
	s_mov_b32 m0, s57
	s_nop 4
	global_load_lds_dwordx4 v144, s[12:13]
	s_mov_b32 m0, s40
	s_add_u32 s12, s44, 0x40000
	s_addc_u32 s13, s45, 0
	s_mov_b32 s40, m0
	s_mov_b32 m0, s58
	s_nop 4
	global_load_lds_dwordx4 v144, s[12:13]
	s_mov_b32 m0, s40
	s_add_u32 s12, s44, 0x60000
	s_addc_u32 s13, s45, 0
	s_mov_b32 s40, m0
	s_mov_b32 m0, s59
	s_nop 4
	global_load_lds_dwordx4 v144, s[12:13]
	s_mov_b32 m0, s40
	s_mov_b32 s12, m0
	s_mov_b32 m0, s54
	s_nop 4
	global_load_lds_dwordx4 v1, s[34:35]
	s_mov_b32 m0, s12
	s_add_u32 s12, s34, 0x20000
	s_addc_u32 s13, s35, 0
	s_mov_b32 s40, m0
	s_mov_b32 m0, s60
	s_nop 4
	global_load_lds_dwordx4 v1, s[12:13]
	s_mov_b32 m0, s40
	s_waitcnt vmcnt(8)
	s_waitcnt lgkmcnt(0)
	s_barrier
	s_waitcnt lgkmcnt(7)
	v_mfma_f32_16x16x32_bf16 v[58:61], v[152:155], v[184:187], v[58:61]
	v_mfma_f32_16x16x32_bf16 v[50:53], v[160:163], v[184:187], v[50:53]
	s_waitcnt lgkmcnt(5)
	v_mfma_f32_16x16x32_bf16 v[42:45], v[152:155], v[192:195], v[42:45]
	v_mfma_f32_16x16x32_bf16 v[34:37], v[160:163], v[192:195], v[34:37]
	s_waitcnt lgkmcnt(3)
	v_mfma_f32_16x16x32_bf16 v[26:29], v[152:155], v[200:203], v[26:29]
	v_mfma_f32_16x16x32_bf16 v[18:21], v[160:163], v[200:203], v[18:21]
	s_waitcnt lgkmcnt(1)
	v_mfma_f32_16x16x32_bf16 v[10:13], v[152:155], v[208:211], v[10:13]
	v_mfma_f32_16x16x32_bf16 v[6:9], v[160:163], v[208:211], v[6:9]
	v_mfma_f32_16x16x32_bf16 v[58:61], v[156:159], v[188:191], v[58:61]
	v_mfma_f32_16x16x32_bf16 v[50:53], v[164:167], v[188:191], v[50:53]
	v_mfma_f32_16x16x32_bf16 v[42:45], v[156:159], v[196:199], v[42:45]
	v_mfma_f32_16x16x32_bf16 v[34:37], v[164:167], v[196:199], v[34:37]
	v_mfma_f32_16x16x32_bf16 v[26:29], v[156:159], v[204:207], v[26:29]
	v_mfma_f32_16x16x32_bf16 v[18:21], v[164:167], v[204:207], v[18:21]
	s_waitcnt lgkmcnt(0)
	v_mfma_f32_16x16x32_bf16 v[10:13], v[156:159], v[212:215], v[10:13]
	v_mfma_f32_16x16x32_bf16 v[6:9], v[164:167], v[212:215], v[6:9]
	v_mfma_f32_16x16x32_bf16 v[62:65], v[168:171], v[184:187], v[62:65]
	v_mfma_f32_16x16x32_bf16 v[54:57], v[176:179], v[184:187], v[54:57]
	v_mfma_f32_16x16x32_bf16 v[46:49], v[168:171], v[192:195], v[46:49]
	v_mfma_f32_16x16x32_bf16 v[38:41], v[176:179], v[192:195], v[38:41]
	v_mfma_f32_16x16x32_bf16 v[30:33], v[168:171], v[200:203], v[30:33]
	v_mfma_f32_16x16x32_bf16 v[22:25], v[176:179], v[200:203], v[22:25]
	v_mfma_f32_16x16x32_bf16 v[14:17], v[168:171], v[208:211], v[14:17]
	v_mfma_f32_16x16x32_bf16 v[2:5], v[176:179], v[208:211], v[2:5]
	v_mfma_f32_16x16x32_bf16 v[62:65], v[172:175], v[188:191], v[62:65]
	v_mfma_f32_16x16x32_bf16 v[54:57], v[180:183], v[188:191], v[54:57]
	v_mfma_f32_16x16x32_bf16 v[46:49], v[172:175], v[196:199], v[46:49]
	v_mfma_f32_16x16x32_bf16 v[38:41], v[180:183], v[196:199], v[38:41]
	v_mfma_f32_16x16x32_bf16 v[30:33], v[172:175], v[204:207], v[30:33]
	v_mfma_f32_16x16x32_bf16 v[22:25], v[180:183], v[204:207], v[22:25]
	v_mfma_f32_16x16x32_bf16 v[14:17], v[172:175], v[212:215], v[14:17]
	v_mfma_f32_16x16x32_bf16 v[2:5], v[180:183], v[212:215], v[2:5]
	s_barrier
	v_add_u32_e32 v130, 0x18000, v150
	ds_read_b128 v[152:155], v130
	ds_read_b128 v[156:159], v130 offset:1024
	ds_read_b128 v[160:163], v130 offset:2048
	ds_read_b128 v[164:167], v130 offset:3072
	v_add_u32_e32 v130, 0x1c000, v150
	ds_read_b128 v[168:171], v130
	ds_read_b128 v[172:175], v130 offset:1024
	ds_read_b128 v[176:179], v130 offset:2048
	ds_read_b128 v[180:183], v130 offset:3072
	ds_read_b128 v[184:187], v151 offset:32768
	ds_read_b128 v[188:191], v151 offset:33792
	ds_read_b128 v[192:195], v151 offset:34816
	ds_read_b128 v[196:199], v151 offset:35840
	ds_read_b128 v[200:203], v151 offset:36864
	ds_read_b128 v[204:207], v151 offset:37888
	ds_read_b128 v[208:211], v151 offset:38912
	ds_read_b128 v[212:215], v151 offset:39936
	s_add_u32 s12, s34, 0x40000
	s_addc_u32 s13, s35, 0
	s_mov_b32 s40, m0
	s_mov_b32 m0, s61
	s_nop 4
	global_load_lds_dwordx4 v1, s[12:13]
	s_mov_b32 m0, s40
	s_add_u32 s12, s34, 0x60000
	s_addc_u32 s13, s35, 0
	s_mov_b32 s40, m0
	s_mov_b32 m0, s62
	s_nop 4
	global_load_lds_dwordx4 v1, s[12:13]
	s_mov_b32 m0, s40
	s_waitcnt vmcnt(8)
	s_waitcnt lgkmcnt(0)
	s_barrier
	s_waitcnt lgkmcnt(7)
	v_mfma_f32_16x16x32_bf16 v[122:125], v[152:155], v[184:187], v[122:125]
	v_mfma_f32_16x16x32_bf16 v[114:117], v[160:163], v[184:187], v[114:117]
	s_waitcnt lgkmcnt(5)
	v_mfma_f32_16x16x32_bf16 v[106:109], v[152:155], v[192:195], v[106:109]
	v_mfma_f32_16x16x32_bf16 v[98:101], v[160:163], v[192:195], v[98:101]
	s_waitcnt lgkmcnt(3)
	v_mfma_f32_16x16x32_bf16 v[90:93], v[152:155], v[200:203], v[90:93]
	v_mfma_f32_16x16x32_bf16 v[82:85], v[160:163], v[200:203], v[82:85]
	s_waitcnt lgkmcnt(1)
	v_mfma_f32_16x16x32_bf16 v[74:77], v[152:155], v[208:211], v[74:77]
	v_mfma_f32_16x16x32_bf16 v[66:69], v[160:163], v[208:211], v[66:69]
	v_mfma_f32_16x16x32_bf16 v[122:125], v[156:159], v[188:191], v[122:125]
	v_mfma_f32_16x16x32_bf16 v[114:117], v[164:167], v[188:191], v[114:117]
	v_mfma_f32_16x16x32_bf16 v[106:109], v[156:159], v[196:199], v[106:109]
	v_mfma_f32_16x16x32_bf16 v[98:101], v[164:167], v[196:199], v[98:101]
	v_mfma_f32_16x16x32_bf16 v[90:93], v[156:159], v[204:207], v[90:93]
	v_mfma_f32_16x16x32_bf16 v[82:85], v[164:167], v[204:207], v[82:85]
	s_waitcnt lgkmcnt(0)
	v_mfma_f32_16x16x32_bf16 v[74:77], v[156:159], v[212:215], v[74:77]
	v_mfma_f32_16x16x32_bf16 v[66:69], v[164:167], v[212:215], v[66:69]
	v_mfma_f32_16x16x32_bf16 v[126:129], v[168:171], v[184:187], v[126:129]
	v_mfma_f32_16x16x32_bf16 v[118:121], v[176:179], v[184:187], v[118:121]
	v_mfma_f32_16x16x32_bf16 v[110:113], v[168:171], v[192:195], v[110:113]
	v_mfma_f32_16x16x32_bf16 v[102:105], v[176:179], v[192:195], v[102:105]
	v_mfma_f32_16x16x32_bf16 v[94:97], v[168:171], v[200:203], v[94:97]
	v_mfma_f32_16x16x32_bf16 v[86:89], v[176:179], v[200:203], v[86:89]
	v_mfma_f32_16x16x32_bf16 v[78:81], v[168:171], v[208:211], v[78:81]
	v_mfma_f32_16x16x32_bf16 v[70:73], v[176:179], v[208:211], v[70:73]
	v_mfma_f32_16x16x32_bf16 v[126:129], v[172:175], v[188:191], v[126:129]
	v_mfma_f32_16x16x32_bf16 v[118:121], v[180:183], v[188:191], v[118:121]
	v_mfma_f32_16x16x32_bf16 v[110:113], v[172:175], v[196:199], v[110:113]
	v_mfma_f32_16x16x32_bf16 v[102:105], v[180:183], v[196:199], v[102:105]
	v_mfma_f32_16x16x32_bf16 v[94:97], v[172:175], v[204:207], v[94:97]
	v_mfma_f32_16x16x32_bf16 v[86:89], v[180:183], v[204:207], v[86:89]
	v_mfma_f32_16x16x32_bf16 v[78:81], v[172:175], v[212:215], v[78:81]
	v_mfma_f32_16x16x32_bf16 v[70:73], v[180:183], v[212:215], v[70:73]
	s_barrier
	s_add_u32 s12, s44, 0x80
	s_addc_u32 s13, s45, 0
	ds_read_b128 v[184:187], v151 offset:49152
	ds_read_b128 v[188:191], v151 offset:50176
	ds_read_b128 v[192:195], v151 offset:51200
	ds_read_b128 v[196:199], v151 offset:52224
	ds_read_b128 v[200:203], v151 offset:53248
	ds_read_b128 v[204:207], v151 offset:54272
	ds_read_b128 v[208:211], v151 offset:55296
	ds_read_b128 v[212:215], v151 offset:56320
	s_mov_b32 s40, m0
	s_mov_b32 m0, s63
	s_nop 4
	global_load_lds_dwordx4 v144, s[12:13]
	s_mov_b32 m0, s40
	s_add_u32 s12, s44, 0x20080
	s_addc_u32 s13, s45, 0
	s_mov_b32 s40, m0
	s_mov_b32 m0, s64
	s_nop 4
	global_load_lds_dwordx4 v144, s[12:13]
	s_mov_b32 m0, s40
	s_add_u32 s12, s44, 0x40080
	s_addc_u32 s13, s45, 0
	s_mov_b32 s40, m0
	s_mov_b32 m0, s67
	s_nop 4
	global_load_lds_dwordx4 v144, s[12:13]
	s_mov_b32 m0, s40
	s_add_u32 s12, s44, 0x60080
	s_addc_u32 s13, s45, 0
	s_mov_b32 s40, m0
	s_mov_b32 m0, s73
	s_nop 4
	global_load_lds_dwordx4 v144, s[12:13]
	s_mov_b32 m0, s40
	s_mov_b32 s12, m0
	s_mov_b32 m0, s65
	s_nop 4
	global_load_lds_dwordx4 v1, s[42:43]
	s_mov_b32 m0, s12
	s_add_u32 s12, s34, 0x20080
	s_addc_u32 s13, s35, 0
	s_mov_b32 s34, m0
	s_mov_b32 m0, s66
	s_nop 4
	global_load_lds_dwordx4 v1, s[12:13]
	s_mov_b32 m0, s34
	s_waitcnt vmcnt(8)
	s_waitcnt lgkmcnt(0)
	s_barrier
	s_waitcnt lgkmcnt(7)
	v_mfma_f32_16x16x32_bf16 v[58:61], v[152:155], v[184:187], v[58:61]
	v_mfma_f32_16x16x32_bf16 v[50:53], v[160:163], v[184:187], v[50:53]
	s_waitcnt lgkmcnt(5)
	v_mfma_f32_16x16x32_bf16 v[42:45], v[152:155], v[192:195], v[42:45]
	v_mfma_f32_16x16x32_bf16 v[34:37], v[160:163], v[192:195], v[34:37]
	s_waitcnt lgkmcnt(3)
	v_mfma_f32_16x16x32_bf16 v[26:29], v[152:155], v[200:203], v[26:29]
	v_mfma_f32_16x16x32_bf16 v[18:21], v[160:163], v[200:203], v[18:21]
	s_waitcnt lgkmcnt(1)
	v_mfma_f32_16x16x32_bf16 v[10:13], v[152:155], v[208:211], v[10:13]
	v_mfma_f32_16x16x32_bf16 v[6:9], v[160:163], v[208:211], v[6:9]
	v_mfma_f32_16x16x32_bf16 v[58:61], v[156:159], v[188:191], v[58:61]
	v_mfma_f32_16x16x32_bf16 v[50:53], v[164:167], v[188:191], v[50:53]
	v_mfma_f32_16x16x32_bf16 v[42:45], v[156:159], v[196:199], v[42:45]
	v_mfma_f32_16x16x32_bf16 v[34:37], v[164:167], v[196:199], v[34:37]
	v_mfma_f32_16x16x32_bf16 v[26:29], v[156:159], v[204:207], v[26:29]
	v_mfma_f32_16x16x32_bf16 v[18:21], v[164:167], v[204:207], v[18:21]
	s_waitcnt lgkmcnt(0)
	v_mfma_f32_16x16x32_bf16 v[10:13], v[156:159], v[212:215], v[10:13]
	v_mfma_f32_16x16x32_bf16 v[6:9], v[164:167], v[212:215], v[6:9]
	v_mfma_f32_16x16x32_bf16 v[62:65], v[168:171], v[184:187], v[62:65]
	v_mfma_f32_16x16x32_bf16 v[54:57], v[176:179], v[184:187], v[54:57]
	v_mfma_f32_16x16x32_bf16 v[46:49], v[168:171], v[192:195], v[46:49]
	v_mfma_f32_16x16x32_bf16 v[38:41], v[176:179], v[192:195], v[38:41]
	v_mfma_f32_16x16x32_bf16 v[30:33], v[168:171], v[200:203], v[30:33]
	v_mfma_f32_16x16x32_bf16 v[22:25], v[176:179], v[200:203], v[22:25]
	v_mfma_f32_16x16x32_bf16 v[14:17], v[168:171], v[208:211], v[14:17]
	v_mfma_f32_16x16x32_bf16 v[2:5], v[176:179], v[208:211], v[2:5]
	v_mfma_f32_16x16x32_bf16 v[62:65], v[172:175], v[188:191], v[62:65]
	v_mfma_f32_16x16x32_bf16 v[54:57], v[180:183], v[188:191], v[54:57]
	v_mfma_f32_16x16x32_bf16 v[46:49], v[172:175], v[196:199], v[46:49]
	v_mfma_f32_16x16x32_bf16 v[38:41], v[180:183], v[196:199], v[38:41]
	v_mfma_f32_16x16x32_bf16 v[30:33], v[172:175], v[204:207], v[30:33]
	v_mfma_f32_16x16x32_bf16 v[22:25], v[180:183], v[204:207], v[22:25]
	v_mfma_f32_16x16x32_bf16 v[14:17], v[172:175], v[212:215], v[14:17]
	v_mfma_f32_16x16x32_bf16 v[2:5], v[180:183], v[212:215], v[2:5]
	s_barrier
	s_add_i32 s88, s88, 2
	s_add_u32 s86, s86, 0x100
	s_addc_u32 s87, s87, 0
	s_cmp_gt_u32 s88, 13
	s_mov_b64 s[40:41], s[0:1]
	s_cbranch_scc0 .LBB0_988
	s_and_b64 vcc, exec, s[8:9]
	s_cbranch_vccz .LBB0_991
	s_barrier

.LBB0_1317:
	ds_read_b128 v[138:141], v132
	ds_read_b128 v[142:145], v132 offset:1024
	ds_read_b128 v[146:149], v132 offset:2048
	ds_read_b128 v[150:153], v132 offset:3072
	ds_read_b128 v[154:157], v133
	ds_read_b128 v[158:161], v133 offset:1024
	ds_read_b128 v[166:169], v133 offset:2048
	ds_read_b128 v[170:173], v133 offset:3072
	s_add_u32 s0, s46, 0xea3c0080
	s_addc_u32 s1, s47, -1
	s_cmp_lg_u32 s90, 12
	s_cselect_b32 s13, s0, 0
	s_cselect_b32 s12, s1, 0
	s_add_u32 s0, s8, s13
	s_addc_u32 s1, s9, s12
	s_add_u32 s34, s0, 0x80
	s_addc_u32 s35, s1, 0
	s_add_u32 s48, s4, s13
	s_addc_u32 s49, s5, s12
	ds_read_b128 v[174:177], v134
	ds_read_b128 v[184:187], v134 offset:1024
	ds_read_b128 v[188:191], v134 offset:2048
	ds_read_b128 v[192:195], v134 offset:3072
	ds_read_b128 v[196:199], v134 offset:4096
	ds_read_b128 v[200:203], v134 offset:5120
	ds_read_b128 v[204:207], v134 offset:6144
	ds_read_b128 v[208:211], v134 offset:7168
	s_add_u32 s12, s88, s46
	s_addc_u32 s13, s89, s47
	s_mov_b32 s91, m0
	s_mov_b32 m0, s87
	s_nop 4
	global_load_lds_dwordx4 v130, s[12:13]
	s_mov_b32 m0, s91
	s_add_u32 s12, s12, 0x20000
	s_addc_u32 s13, s13, 0
	s_add_i32 s91, s66, 0xe000
	s_mov_b32 s92, m0
	s_mov_b32 m0, s91
	s_nop 4
	global_load_lds_dwordx4 v130, s[12:13]
	s_mov_b32 m0, s92
	s_waitcnt vmcnt(8)
	s_waitcnt lgkmcnt(0)
	s_barrier
	s_waitcnt lgkmcnt(7)
	v_mfma_f32_16x16x32_bf16 v[2:5], v[138:141], v[174:177], v[2:5]
	v_mfma_f32_16x16x32_bf16 v[6:9], v[146:149], v[174:177], v[6:9]
	s_waitcnt lgkmcnt(5)
	v_mfma_f32_16x16x32_bf16 v[30:33], v[138:141], v[188:191], v[30:33]
	v_mfma_f32_16x16x32_bf16 v[34:37], v[146:149], v[188:191], v[34:37]
	s_waitcnt lgkmcnt(3)
	v_mfma_f32_16x16x32_bf16 v[54:57], v[138:141], v[196:199], v[54:57]
	v_mfma_f32_16x16x32_bf16 v[50:53], v[146:149], v[196:199], v[50:53]
	s_waitcnt lgkmcnt(1)
	v_mfma_f32_16x16x32_bf16 v[70:73], v[138:141], v[204:207], v[70:73]
	v_mfma_f32_16x16x32_bf16 v[66:69], v[146:149], v[204:207], v[66:69]
	v_mfma_f32_16x16x32_bf16 v[2:5], v[142:145], v[184:187], v[2:5]
	v_mfma_f32_16x16x32_bf16 v[6:9], v[150:153], v[184:187], v[6:9]
	v_mfma_f32_16x16x32_bf16 v[30:33], v[142:145], v[192:195], v[30:33]
	v_mfma_f32_16x16x32_bf16 v[34:37], v[150:153], v[192:195], v[34:37]
	v_mfma_f32_16x16x32_bf16 v[54:57], v[142:145], v[200:203], v[54:57]
	v_mfma_f32_16x16x32_bf16 v[50:53], v[150:153], v[200:203], v[50:53]
	s_waitcnt lgkmcnt(0)
	v_mfma_f32_16x16x32_bf16 v[70:73], v[142:145], v[208:211], v[70:73]
	v_mfma_f32_16x16x32_bf16 v[66:69], v[150:153], v[208:211], v[66:69]
	v_mfma_f32_16x16x32_bf16 v[10:13], v[154:157], v[174:177], v[10:13]
	v_mfma_f32_16x16x32_bf16 v[14:17], v[166:169], v[174:177], v[14:17]
	v_mfma_f32_16x16x32_bf16 v[22:25], v[154:157], v[188:191], v[22:25]
	v_mfma_f32_16x16x32_bf16 v[18:21], v[166:169], v[188:191], v[18:21]
	v_mfma_f32_16x16x32_bf16 v[38:41], v[154:157], v[196:199], v[38:41]
	v_mfma_f32_16x16x32_bf16 v[26:29], v[166:169], v[196:199], v[26:29]
	v_mfma_f32_16x16x32_bf16 v[46:49], v[154:157], v[204:207], v[46:49]
	v_mfma_f32_16x16x32_bf16 v[42:45], v[166:169], v[204:207], v[42:45]
	v_mfma_f32_16x16x32_bf16 v[10:13], v[158:161], v[184:187], v[10:13]
	v_mfma_f32_16x16x32_bf16 v[14:17], v[170:173], v[184:187], v[14:17]
	v_mfma_f32_16x16x32_bf16 v[22:25], v[158:161], v[192:195], v[22:25]
	v_mfma_f32_16x16x32_bf16 v[18:21], v[170:173], v[192:195], v[18:21]
	v_mfma_f32_16x16x32_bf16 v[38:41], v[158:161], v[200:203], v[38:41]
	v_mfma_f32_16x16x32_bf16 v[26:29], v[170:173], v[200:203], v[26:29]
	v_mfma_f32_16x16x32_bf16 v[46:49], v[158:161], v[208:211], v[46:49]
	v_mfma_f32_16x16x32_bf16 v[42:45], v[170:173], v[208:211], v[42:45]
	s_barrier
	ds_read_b128 v[174:177], v134 offset:16384
	ds_read_b128 v[184:187], v134 offset:17408
	ds_read_b128 v[188:191], v134 offset:18432
	ds_read_b128 v[192:195], v134 offset:19456
	ds_read_b128 v[196:199], v134 offset:20480
	ds_read_b128 v[200:203], v134 offset:21504
	ds_read_b128 v[204:207], v134 offset:22528
	ds_read_b128 v[208:211], v134 offset:23552
	s_mov_b32 s12, m0
	s_mov_b32 m0, s67
	s_nop 4
	global_load_lds_dwordx4 v131, s[48:49]
	s_mov_b32 m0, s12
	s_add_u32 s12, s48, 0x20000
	s_addc_u32 s13, s49, 0
	s_mov_b32 s91, m0
	s_mov_b32 m0, s73
	s_nop 4
	global_load_lds_dwordx4 v131, s[12:13]
	s_mov_b32 m0, s91
	s_add_u32 s12, s48, 0x40000
	s_addc_u32 s13, s49, 0
	s_mov_b32 s91, m0
	s_mov_b32 m0, s74
	s_nop 4
	global_load_lds_dwordx4 v131, s[12:13]
	s_mov_b32 m0, s91
	s_add_u32 s12, s48, 0x60000
	s_addc_u32 s13, s49, 0
	s_mov_b32 s91, m0
	s_mov_b32 m0, s75
	s_nop 4
	global_load_lds_dwordx4 v131, s[12:13]
	s_mov_b32 m0, s91
	s_mov_b32 s12, m0
	s_mov_b32 m0, s66
	s_nop 4
	global_load_lds_dwordx4 v130, s[0:1]
	s_mov_b32 m0, s12
	s_add_u32 s12, s0, 0x20000
	s_addc_u32 s13, s1, 0
	s_mov_b32 s91, m0
	s_mov_b32 m0, s76
	s_nop 4
	global_load_lds_dwordx4 v130, s[12:13]
	s_mov_b32 m0, s91
	s_waitcnt vmcnt(8)
	s_waitcnt lgkmcnt(0)
	s_barrier
	s_waitcnt lgkmcnt(7)
	v_mfma_f32_16x16x32_bf16 v[82:85], v[138:141], v[174:177], v[82:85]
	v_mfma_f32_16x16x32_bf16 v[74:77], v[146:149], v[174:177], v[74:77]
	s_waitcnt lgkmcnt(5)
	v_mfma_f32_16x16x32_bf16 v[98:101], v[138:141], v[188:191], v[98:101]
	v_mfma_f32_16x16x32_bf16 v[90:93], v[146:149], v[188:191], v[90:93]
	s_waitcnt lgkmcnt(3)
	v_mfma_f32_16x16x32_bf16 v[118:121], v[138:141], v[196:199], v[118:121]
	v_mfma_f32_16x16x32_bf16 v[114:117], v[146:149], v[196:199], v[114:117]
	s_waitcnt lgkmcnt(1)
	v_mfma_f32_16x16x32_bf16 v[126:129], v[138:141], v[204:207], v[126:129]
	v_mfma_f32_16x16x32_bf16 v[122:125], v[146:149], v[204:207], v[122:125]
	v_mfma_f32_16x16x32_bf16 v[82:85], v[142:145], v[184:187], v[82:85]
	v_mfma_f32_16x16x32_bf16 v[74:77], v[150:153], v[184:187], v[74:77]
	v_mfma_f32_16x16x32_bf16 v[98:101], v[142:145], v[192:195], v[98:101]
	v_mfma_f32_16x16x32_bf16 v[90:93], v[150:153], v[192:195], v[90:93]
	v_mfma_f32_16x16x32_bf16 v[118:121], v[142:145], v[200:203], v[118:121]
	v_mfma_f32_16x16x32_bf16 v[114:117], v[150:153], v[200:203], v[114:117]
	s_waitcnt lgkmcnt(0)
	v_mfma_f32_16x16x32_bf16 v[126:129], v[142:145], v[208:211], v[126:129]
	v_mfma_f32_16x16x32_bf16 v[122:125], v[150:153], v[208:211], v[122:125]
	v_mfma_f32_16x16x32_bf16 v[62:65], v[154:157], v[174:177], v[62:65]
	v_mfma_f32_16x16x32_bf16 v[58:61], v[166:169], v[174:177], v[58:61]
	v_mfma_f32_16x16x32_bf16 v[86:89], v[154:157], v[188:191], v[86:89]
	v_mfma_f32_16x16x32_bf16 v[78:81], v[166:169], v[188:191], v[78:81]
	v_mfma_f32_16x16x32_bf16 v[102:105], v[154:157], v[196:199], v[102:105]
	v_mfma_f32_16x16x32_bf16 v[94:97], v[166:169], v[196:199], v[94:97]
	v_mfma_f32_16x16x32_bf16 v[110:113], v[154:157], v[204:207], v[110:113]
	v_mfma_f32_16x16x32_bf16 v[106:109], v[166:169], v[204:207], v[106:109]
	v_mfma_f32_16x16x32_bf16 v[62:65], v[158:161], v[184:187], v[62:65]
	v_mfma_f32_16x16x32_bf16 v[58:61], v[170:173], v[184:187], v[58:61]
	v_mfma_f32_16x16x32_bf16 v[86:89], v[158:161], v[192:195], v[86:89]
	v_mfma_f32_16x16x32_bf16 v[78:81], v[170:173], v[192:195], v[78:81]
	v_mfma_f32_16x16x32_bf16 v[102:105], v[158:161], v[200:203], v[102:105]
	v_mfma_f32_16x16x32_bf16 v[94:97], v[170:173], v[200:203], v[94:97]
	v_mfma_f32_16x16x32_bf16 v[110:113], v[158:161], v[208:211], v[110:113]
	v_mfma_f32_16x16x32_bf16 v[106:109], v[170:173], v[208:211], v[106:109]
	s_barrier
	ds_read_b128 v[138:141], v135
	ds_read_b128 v[142:145], v135 offset:1024
	ds_read_b128 v[146:149], v135 offset:2048
	ds_read_b128 v[150:153], v135 offset:3072
	ds_read_b128 v[154:157], v136
	ds_read_b128 v[158:161], v136 offset:1024
	ds_read_b128 v[166:169], v136 offset:2048
	ds_read_b128 v[170:173], v136 offset:3072
	ds_read_b128 v[174:177], v134 offset:32768
	ds_read_b128 v[184:187], v134 offset:33792
	ds_read_b128 v[188:191], v134 offset:34816
	ds_read_b128 v[192:195], v134 offset:35840
	ds_read_b128 v[196:199], v134 offset:36864
	ds_read_b128 v[200:203], v134 offset:37888
	ds_read_b128 v[204:207], v134 offset:38912
	ds_read_b128 v[208:211], v134 offset:39936
	s_add_u32 s12, s0, 0x40000
	s_addc_u32 s13, s1, 0
	s_mov_b32 s91, m0
	s_mov_b32 m0, s77
	s_nop 4
	global_load_lds_dwordx4 v130, s[12:13]
	s_mov_b32 m0, s91
	s_add_u32 s12, s0, 0x60000
	s_addc_u32 s13, s1, 0
	s_mov_b32 s91, m0
	s_mov_b32 m0, s79
	s_nop 4
	global_load_lds_dwordx4 v130, s[12:13]
	s_mov_b32 m0, s91
	s_waitcnt vmcnt(8)
	s_waitcnt lgkmcnt(0)
	s_barrier
	s_waitcnt lgkmcnt(7)
	v_mfma_f32_16x16x32_bf16 v[2:5], v[138:141], v[174:177], v[2:5]
	v_mfma_f32_16x16x32_bf16 v[6:9], v[146:149], v[174:177], v[6:9]
	s_waitcnt lgkmcnt(5)
	v_mfma_f32_16x16x32_bf16 v[30:33], v[138:141], v[188:191], v[30:33]
	v_mfma_f32_16x16x32_bf16 v[34:37], v[146:149], v[188:191], v[34:37]
	s_waitcnt lgkmcnt(3)
	v_mfma_f32_16x16x32_bf16 v[54:57], v[138:141], v[196:199], v[54:57]
	v_mfma_f32_16x16x32_bf16 v[50:53], v[146:149], v[196:199], v[50:53]
	s_waitcnt lgkmcnt(1)
	v_mfma_f32_16x16x32_bf16 v[70:73], v[138:141], v[204:207], v[70:73]
	v_mfma_f32_16x16x32_bf16 v[66:69], v[146:149], v[204:207], v[66:69]
	v_mfma_f32_16x16x32_bf16 v[2:5], v[142:145], v[184:187], v[2:5]
	v_mfma_f32_16x16x32_bf16 v[6:9], v[150:153], v[184:187], v[6:9]
	v_mfma_f32_16x16x32_bf16 v[30:33], v[142:145], v[192:195], v[30:33]
	v_mfma_f32_16x16x32_bf16 v[34:37], v[150:153], v[192:195], v[34:37]
	v_mfma_f32_16x16x32_bf16 v[54:57], v[142:145], v[200:203], v[54:57]
	v_mfma_f32_16x16x32_bf16 v[50:53], v[150:153], v[200:203], v[50:53]
	s_waitcnt lgkmcnt(0)
	v_mfma_f32_16x16x32_bf16 v[70:73], v[142:145], v[208:211], v[70:73]
	v_mfma_f32_16x16x32_bf16 v[66:69], v[150:153], v[208:211], v[66:69]
	v_mfma_f32_16x16x32_bf16 v[10:13], v[154:157], v[174:177], v[10:13]
	v_mfma_f32_16x16x32_bf16 v[14:17], v[166:169], v[174:177], v[14:17]
	v_mfma_f32_16x16x32_bf16 v[22:25], v[154:157], v[188:191], v[22:25]
	v_mfma_f32_16x16x32_bf16 v[18:21], v[166:169], v[188:191], v[18:21]
	v_mfma_f32_16x16x32_bf16 v[38:41], v[154:157], v[196:199], v[38:41]
	v_mfma_f32_16x16x32_bf16 v[26:29], v[166:169], v[196:199], v[26:29]
	v_mfma_f32_16x16x32_bf16 v[46:49], v[154:157], v[204:207], v[46:49]
	v_mfma_f32_16x16x32_bf16 v[42:45], v[166:169], v[204:207], v[42:45]
	v_mfma_f32_16x16x32_bf16 v[10:13], v[158:161], v[184:187], v[10:13]
	v_mfma_f32_16x16x32_bf16 v[14:17], v[170:173], v[184:187], v[14:17]
	v_mfma_f32_16x16x32_bf16 v[22:25], v[158:161], v[192:195], v[22:25]
	v_mfma_f32_16x16x32_bf16 v[18:21], v[170:173], v[192:195], v[18:21]
	v_mfma_f32_16x16x32_bf16 v[38:41], v[158:161], v[200:203], v[38:41]
	v_mfma_f32_16x16x32_bf16 v[26:29], v[170:173], v[200:203], v[26:29]
	v_mfma_f32_16x16x32_bf16 v[46:49], v[158:161], v[208:211], v[46:49]
	v_mfma_f32_16x16x32_bf16 v[42:45], v[170:173], v[208:211], v[42:45]
	s_barrier
	s_add_u32 s12, s48, 0x80
	s_addc_u32 s13, s49, 0
	ds_read_b128 v[174:177], v134 offset:49152
	ds_read_b128 v[184:187], v134 offset:50176
	ds_read_b128 v[188:191], v134 offset:51200
	ds_read_b128 v[192:195], v134 offset:52224
	ds_read_b128 v[196:199], v134 offset:53248
	ds_read_b128 v[200:203], v134 offset:54272
	ds_read_b128 v[204:207], v134 offset:55296
	ds_read_b128 v[208:211], v134 offset:56320
	s_mov_b32 s91, m0
	s_mov_b32 m0, s80
	s_nop 4
	global_load_lds_dwordx4 v131, s[12:13]
	s_mov_b32 m0, s91
	s_add_u32 s12, s48, 0x20080
	s_addc_u32 s13, s49, 0
	s_mov_b32 s91, m0
	s_mov_b32 m0, s81
	s_nop 4
	global_load_lds_dwordx4 v131, s[12:13]
	s_mov_b32 m0, s91
	s_add_u32 s12, s48, 0x40080
	s_addc_u32 s13, s49, 0
	s_mov_b32 s91, m0
	s_mov_b32 m0, s85
	s_nop 4
	global_load_lds_dwordx4 v131, s[12:13]
	s_mov_b32 m0, s91
	s_add_u32 s12, s48, 0x60080
	s_addc_u32 s13, s49, 0
	s_mov_b32 s48, m0
	s_mov_b32 m0, s86
	s_nop 4
	global_load_lds_dwordx4 v131, s[12:13]
	s_mov_b32 m0, s48
	s_mov_b32 s12, m0
	s_mov_b32 m0, s82
	s_nop 4
	global_load_lds_dwordx4 v130, s[34:35]
	s_mov_b32 m0, s12
	s_add_u32 s0, s0, 0x20080
	s_addc_u32 s1, s1, 0
	s_mov_b32 s12, m0
	s_mov_b32 m0, s84
	s_nop 4
	global_load_lds_dwordx4 v130, s[0:1]
	s_mov_b32 m0, s12
	s_waitcnt vmcnt(8)
	s_waitcnt lgkmcnt(0)
	s_barrier
	s_waitcnt lgkmcnt(7)
	v_mfma_f32_16x16x32_bf16 v[82:85], v[138:141], v[174:177], v[82:85]
	v_mfma_f32_16x16x32_bf16 v[74:77], v[146:149], v[174:177], v[74:77]
	s_waitcnt lgkmcnt(5)
	v_mfma_f32_16x16x32_bf16 v[98:101], v[138:141], v[188:191], v[98:101]
	v_mfma_f32_16x16x32_bf16 v[90:93], v[146:149], v[188:191], v[90:93]
	s_waitcnt lgkmcnt(3)
	v_mfma_f32_16x16x32_bf16 v[118:121], v[138:141], v[196:199], v[118:121]
	v_mfma_f32_16x16x32_bf16 v[114:117], v[146:149], v[196:199], v[114:117]
	s_waitcnt lgkmcnt(1)
	v_mfma_f32_16x16x32_bf16 v[126:129], v[138:141], v[204:207], v[126:129]
	v_mfma_f32_16x16x32_bf16 v[122:125], v[146:149], v[204:207], v[122:125]
	v_mfma_f32_16x16x32_bf16 v[82:85], v[142:145], v[184:187], v[82:85]
	v_mfma_f32_16x16x32_bf16 v[74:77], v[150:153], v[184:187], v[74:77]
	v_mfma_f32_16x16x32_bf16 v[98:101], v[142:145], v[192:195], v[98:101]
	v_mfma_f32_16x16x32_bf16 v[90:93], v[150:153], v[192:195], v[90:93]
	v_mfma_f32_16x16x32_bf16 v[118:121], v[142:145], v[200:203], v[118:121]
	v_mfma_f32_16x16x32_bf16 v[114:117], v[150:153], v[200:203], v[114:117]
	s_waitcnt lgkmcnt(0)
	v_mfma_f32_16x16x32_bf16 v[126:129], v[142:145], v[208:211], v[126:129]
	v_mfma_f32_16x16x32_bf16 v[122:125], v[150:153], v[208:211], v[122:125]
	v_mfma_f32_16x16x32_bf16 v[62:65], v[154:157], v[174:177], v[62:65]
	v_mfma_f32_16x16x32_bf16 v[58:61], v[166:169], v[174:177], v[58:61]
	v_mfma_f32_16x16x32_bf16 v[86:89], v[154:157], v[188:191], v[86:89]
	v_mfma_f32_16x16x32_bf16 v[78:81], v[166:169], v[188:191], v[78:81]
	v_mfma_f32_16x16x32_bf16 v[102:105], v[154:157], v[196:199], v[102:105]
	v_mfma_f32_16x16x32_bf16 v[94:97], v[166:169], v[196:199], v[94:97]
	v_mfma_f32_16x16x32_bf16 v[110:113], v[154:157], v[204:207], v[110:113]
	v_mfma_f32_16x16x32_bf16 v[106:109], v[166:169], v[204:207], v[106:109]
	v_mfma_f32_16x16x32_bf16 v[62:65], v[158:161], v[184:187], v[62:65]
	v_mfma_f32_16x16x32_bf16 v[58:61], v[170:173], v[184:187], v[58:61]
	v_mfma_f32_16x16x32_bf16 v[86:89], v[158:161], v[192:195], v[86:89]
	v_mfma_f32_16x16x32_bf16 v[78:81], v[170:173], v[192:195], v[78:81]
	v_mfma_f32_16x16x32_bf16 v[102:105], v[158:161], v[200:203], v[102:105]
	v_mfma_f32_16x16x32_bf16 v[94:97], v[170:173], v[200:203], v[94:97]
	v_mfma_f32_16x16x32_bf16 v[110:113], v[158:161], v[208:211], v[110:113]
	v_mfma_f32_16x16x32_bf16 v[106:109], v[170:173], v[208:211], v[106:109]
	s_barrier
	s_add_i32 s90, s90, 2
	s_add_u32 s46, s46, 0x100
	s_addc_u32 s47, s47, 0
	s_cmp_lt_u32 s90, 14
	s_cbranch_scc1 .LBB0_1317
	s_waitcnt vmcnt(0)
	s_cmpk_gt_u32 s65, 0xff
	s_cbranch_scc1 .LBB0_1320
	s_barrier

.LBB0_1424:
	v_add_u32_e32 v134, 0x10000, v139
	ds_read_b128 v[142:145], v134
	ds_read_b128 v[146:149], v134 offset:1024
	ds_read_b128 v[150:153], v134 offset:2048
	ds_read_b128 v[154:157], v134 offset:3072
	v_add_u32_e32 v134, 0x14000, v139
	ds_read_b128 v[158:161], v134
	ds_read_b128 v[162:165], v134 offset:1024
	ds_read_b128 v[166:169], v134 offset:2048
	ds_read_b128 v[170:173], v134 offset:3072
	s_add_u32 s0, s36, 0x100
	s_addc_u32 s1, s37, 0
	s_cmp_eq_u32 s66, 12
	s_cselect_b32 s34, s15, s0
	s_cselect_b32 s35, s14, s1
	s_cselect_b32 s40, s21, s64
	s_cselect_b32 s41, s11, s65
	s_add_u32 s38, s34, 0x80
	s_addc_u32 s39, s35, 0
	ds_read_b128 v[174:177], v140
	ds_read_b128 v[178:181], v140 offset:1024
	ds_read_b128 v[182:185], v140 offset:2048
	ds_read_b128 v[186:189], v140 offset:3072
	ds_read_b128 v[190:193], v140 offset:4096
	ds_read_b128 v[194:197], v140 offset:5120
	ds_read_b128 v[198:201], v140 offset:6144
	ds_read_b128 v[202:205], v140 offset:7168
	s_add_u32 s12, s36, 0x40080
	s_addc_u32 s13, s37, 0
	s_mov_b32 s67, m0
	s_mov_b32 m0, s59
	s_nop 4
	global_load_lds_dwordx4 v1, s[12:13]
	s_mov_b32 m0, s67
	s_add_u32 s12, s36, 0x60080
	s_addc_u32 s13, s37, 0
	s_add_i32 s36, s27, 0xe000
	s_mov_b32 s37, m0
	s_mov_b32 m0, s36
	s_nop 4
	global_load_lds_dwordx4 v1, s[12:13]
	s_mov_b32 m0, s37
	s_waitcnt vmcnt(8)
	s_waitcnt lgkmcnt(0)
	s_barrier
	s_waitcnt lgkmcnt(7)
	v_mfma_f32_16x16x32_bf16 v[122:125], v[142:145], v[174:177], v[122:125]
	v_mfma_f32_16x16x32_bf16 v[114:117], v[150:153], v[174:177], v[114:117]
	s_waitcnt lgkmcnt(5)
	v_mfma_f32_16x16x32_bf16 v[106:109], v[142:145], v[182:185], v[106:109]
	v_mfma_f32_16x16x32_bf16 v[98:101], v[150:153], v[182:185], v[98:101]
	s_waitcnt lgkmcnt(3)
	v_mfma_f32_16x16x32_bf16 v[90:93], v[142:145], v[190:193], v[90:93]
	v_mfma_f32_16x16x32_bf16 v[82:85], v[150:153], v[190:193], v[82:85]
	s_waitcnt lgkmcnt(1)
	v_mfma_f32_16x16x32_bf16 v[74:77], v[142:145], v[198:201], v[74:77]
	v_mfma_f32_16x16x32_bf16 v[66:69], v[150:153], v[198:201], v[66:69]
	v_mfma_f32_16x16x32_bf16 v[122:125], v[146:149], v[178:181], v[122:125]
	v_mfma_f32_16x16x32_bf16 v[114:117], v[154:157], v[178:181], v[114:117]
	v_mfma_f32_16x16x32_bf16 v[106:109], v[146:149], v[186:189], v[106:109]
	v_mfma_f32_16x16x32_bf16 v[98:101], v[154:157], v[186:189], v[98:101]
	v_mfma_f32_16x16x32_bf16 v[90:93], v[146:149], v[194:197], v[90:93]
	v_mfma_f32_16x16x32_bf16 v[82:85], v[154:157], v[194:197], v[82:85]
	s_waitcnt lgkmcnt(0)
	v_mfma_f32_16x16x32_bf16 v[74:77], v[146:149], v[202:205], v[74:77]
	v_mfma_f32_16x16x32_bf16 v[66:69], v[154:157], v[202:205], v[66:69]
	v_mfma_f32_16x16x32_bf16 v[126:129], v[158:161], v[174:177], v[126:129]
	v_mfma_f32_16x16x32_bf16 v[118:121], v[166:169], v[174:177], v[118:121]
	v_mfma_f32_16x16x32_bf16 v[110:113], v[158:161], v[182:185], v[110:113]
	v_mfma_f32_16x16x32_bf16 v[102:105], v[166:169], v[182:185], v[102:105]
	v_mfma_f32_16x16x32_bf16 v[94:97], v[158:161], v[190:193], v[94:97]
	v_mfma_f32_16x16x32_bf16 v[86:89], v[166:169], v[190:193], v[86:89]
	v_mfma_f32_16x16x32_bf16 v[78:81], v[158:161], v[198:201], v[78:81]
	v_mfma_f32_16x16x32_bf16 v[70:73], v[166:169], v[198:201], v[70:73]
	v_mfma_f32_16x16x32_bf16 v[126:129], v[162:165], v[178:181], v[126:129]
	v_mfma_f32_16x16x32_bf16 v[118:121], v[170:173], v[178:181], v[118:121]
	v_mfma_f32_16x16x32_bf16 v[110:113], v[162:165], v[186:189], v[110:113]
	v_mfma_f32_16x16x32_bf16 v[102:105], v[170:173], v[186:189], v[102:105]
	v_mfma_f32_16x16x32_bf16 v[94:97], v[162:165], v[194:197], v[94:97]
	v_mfma_f32_16x16x32_bf16 v[86:89], v[170:173], v[194:197], v[86:89]
	v_mfma_f32_16x16x32_bf16 v[78:81], v[162:165], v[202:205], v[78:81]
	v_mfma_f32_16x16x32_bf16 v[70:73], v[170:173], v[202:205], v[70:73]
	s_barrier
	ds_read_b128 v[174:177], v140 offset:16384
	ds_read_b128 v[178:181], v140 offset:17408
	ds_read_b128 v[182:185], v140 offset:18432
	ds_read_b128 v[186:189], v140 offset:19456
	ds_read_b128 v[190:193], v140 offset:20480
	ds_read_b128 v[194:197], v140 offset:21504
	ds_read_b128 v[198:201], v140 offset:22528
	ds_read_b128 v[202:205], v140 offset:23552
	s_mov_b32 s12, m0
	s_mov_b32 m0, s46
	s_nop 4
	global_load_lds_dwordx4 v136, s[40:41]
	s_mov_b32 m0, s12
	s_add_u32 s12, s40, 0x20000
	s_addc_u32 s13, s41, 0
	s_mov_b32 s36, m0
	s_mov_b32 m0, s47
	s_nop 4
	global_load_lds_dwordx4 v136, s[12:13]
	s_mov_b32 m0, s36
	s_add_u32 s12, s40, 0x40000
	s_addc_u32 s13, s41, 0
	s_mov_b32 s36, m0
	s_mov_b32 m0, s48
	s_nop 4
	global_load_lds_dwordx4 v136, s[12:13]
	s_mov_b32 m0, s36
	s_add_u32 s12, s40, 0x60000
	s_addc_u32 s13, s41, 0
	s_mov_b32 s36, m0
	s_mov_b32 m0, s49
	s_nop 4
	global_load_lds_dwordx4 v136, s[12:13]
	s_mov_b32 m0, s36
	s_mov_b32 s12, m0
	s_mov_b32 m0, s27
	s_nop 4
	global_load_lds_dwordx4 v1, s[34:35]
	s_mov_b32 m0, s12
	s_add_u32 s12, s34, 0x20000
	s_addc_u32 s13, s35, 0
	s_mov_b32 s36, m0
	s_mov_b32 m0, s50
	s_nop 4
	global_load_lds_dwordx4 v1, s[12:13]
	s_mov_b32 m0, s36
	s_waitcnt vmcnt(8)
	s_waitcnt lgkmcnt(0)
	s_barrier
	s_waitcnt lgkmcnt(7)
	v_mfma_f32_16x16x32_bf16 v[58:61], v[142:145], v[174:177], v[58:61]
	v_mfma_f32_16x16x32_bf16 v[50:53], v[150:153], v[174:177], v[50:53]
	s_waitcnt lgkmcnt(5)
	v_mfma_f32_16x16x32_bf16 v[42:45], v[142:145], v[182:185], v[42:45]
	v_mfma_f32_16x16x32_bf16 v[34:37], v[150:153], v[182:185], v[34:37]
	s_waitcnt lgkmcnt(3)
	v_mfma_f32_16x16x32_bf16 v[26:29], v[142:145], v[190:193], v[26:29]
	v_mfma_f32_16x16x32_bf16 v[18:21], v[150:153], v[190:193], v[18:21]
	s_waitcnt lgkmcnt(1)
	v_mfma_f32_16x16x32_bf16 v[10:13], v[142:145], v[198:201], v[10:13]
	v_mfma_f32_16x16x32_bf16 v[6:9], v[150:153], v[198:201], v[6:9]
	v_mfma_f32_16x16x32_bf16 v[58:61], v[146:149], v[178:181], v[58:61]
	v_mfma_f32_16x16x32_bf16 v[50:53], v[154:157], v[178:181], v[50:53]
	v_mfma_f32_16x16x32_bf16 v[42:45], v[146:149], v[186:189], v[42:45]
	v_mfma_f32_16x16x32_bf16 v[34:37], v[154:157], v[186:189], v[34:37]
	v_mfma_f32_16x16x32_bf16 v[26:29], v[146:149], v[194:197], v[26:29]
	v_mfma_f32_16x16x32_bf16 v[18:21], v[154:157], v[194:197], v[18:21]
	s_waitcnt lgkmcnt(0)
	v_mfma_f32_16x16x32_bf16 v[10:13], v[146:149], v[202:205], v[10:13]
	v_mfma_f32_16x16x32_bf16 v[6:9], v[154:157], v[202:205], v[6:9]
	v_mfma_f32_16x16x32_bf16 v[62:65], v[158:161], v[174:177], v[62:65]
	v_mfma_f32_16x16x32_bf16 v[54:57], v[166:169], v[174:177], v[54:57]
	v_mfma_f32_16x16x32_bf16 v[46:49], v[158:161], v[182:185], v[46:49]
	v_mfma_f32_16x16x32_bf16 v[38:41], v[166:169], v[182:185], v[38:41]
	v_mfma_f32_16x16x32_bf16 v[30:33], v[158:161], v[190:193], v[30:33]
	v_mfma_f32_16x16x32_bf16 v[22:25], v[166:169], v[190:193], v[22:25]
	v_mfma_f32_16x16x32_bf16 v[14:17], v[158:161], v[198:201], v[14:17]
	v_mfma_f32_16x16x32_bf16 v[2:5], v[166:169], v[198:201], v[2:5]
	v_mfma_f32_16x16x32_bf16 v[62:65], v[162:165], v[178:181], v[62:65]
	v_mfma_f32_16x16x32_bf16 v[54:57], v[170:173], v[178:181], v[54:57]
	v_mfma_f32_16x16x32_bf16 v[46:49], v[162:165], v[186:189], v[46:49]
	v_mfma_f32_16x16x32_bf16 v[38:41], v[170:173], v[186:189], v[38:41]
	v_mfma_f32_16x16x32_bf16 v[30:33], v[162:165], v[194:197], v[30:33]
	v_mfma_f32_16x16x32_bf16 v[22:25], v[170:173], v[194:197], v[22:25]
	v_mfma_f32_16x16x32_bf16 v[14:17], v[162:165], v[202:205], v[14:17]
	v_mfma_f32_16x16x32_bf16 v[2:5], v[170:173], v[202:205], v[2:5]
	s_barrier
	v_add_u32_e32 v134, 0x18000, v139
	ds_read_b128 v[142:145], v134
	ds_read_b128 v[146:149], v134 offset:1024
	ds_read_b128 v[150:153], v134 offset:2048
	ds_read_b128 v[154:157], v134 offset:3072
	v_add_u32_e32 v134, 0x1c000, v139
	ds_read_b128 v[158:161], v134
	ds_read_b128 v[162:165], v134 offset:1024
	ds_read_b128 v[166:169], v134 offset:2048
	ds_read_b128 v[170:173], v134 offset:3072
	ds_read_b128 v[174:177], v140 offset:32768
	ds_read_b128 v[178:181], v140 offset:33792
	ds_read_b128 v[182:185], v140 offset:34816
	ds_read_b128 v[186:189], v140 offset:35840
	ds_read_b128 v[190:193], v140 offset:36864
	ds_read_b128 v[194:197], v140 offset:37888
	ds_read_b128 v[198:201], v140 offset:38912
	ds_read_b128 v[202:205], v140 offset:39936
	s_add_u32 s12, s34, 0x40000
	s_addc_u32 s13, s35, 0
	s_mov_b32 s36, m0
	s_mov_b32 m0, s51
	s_nop 4
	global_load_lds_dwordx4 v1, s[12:13]
	s_mov_b32 m0, s36
	s_add_u32 s12, s34, 0x60000
	s_addc_u32 s13, s35, 0
	s_mov_b32 s36, m0
	s_mov_b32 m0, s52
	s_nop 4
	global_load_lds_dwordx4 v1, s[12:13]
	s_mov_b32 m0, s36
	s_waitcnt vmcnt(8)
	s_waitcnt lgkmcnt(0)
	s_barrier
	s_waitcnt lgkmcnt(7)
	v_mfma_f32_16x16x32_bf16 v[122:125], v[142:145], v[174:177], v[122:125]
	v_mfma_f32_16x16x32_bf16 v[114:117], v[150:153], v[174:177], v[114:117]
	s_waitcnt lgkmcnt(5)
	v_mfma_f32_16x16x32_bf16 v[106:109], v[142:145], v[182:185], v[106:109]
	v_mfma_f32_16x16x32_bf16 v[98:101], v[150:153], v[182:185], v[98:101]
	s_waitcnt lgkmcnt(3)
	v_mfma_f32_16x16x32_bf16 v[90:93], v[142:145], v[190:193], v[90:93]
	v_mfma_f32_16x16x32_bf16 v[82:85], v[150:153], v[190:193], v[82:85]
	s_waitcnt lgkmcnt(1)
	v_mfma_f32_16x16x32_bf16 v[74:77], v[142:145], v[198:201], v[74:77]
	v_mfma_f32_16x16x32_bf16 v[66:69], v[150:153], v[198:201], v[66:69]
	v_mfma_f32_16x16x32_bf16 v[122:125], v[146:149], v[178:181], v[122:125]
	v_mfma_f32_16x16x32_bf16 v[114:117], v[154:157], v[178:181], v[114:117]
	v_mfma_f32_16x16x32_bf16 v[106:109], v[146:149], v[186:189], v[106:109]
	v_mfma_f32_16x16x32_bf16 v[98:101], v[154:157], v[186:189], v[98:101]
	v_mfma_f32_16x16x32_bf16 v[90:93], v[146:149], v[194:197], v[90:93]
	v_mfma_f32_16x16x32_bf16 v[82:85], v[154:157], v[194:197], v[82:85]
	s_waitcnt lgkmcnt(0)
	v_mfma_f32_16x16x32_bf16 v[74:77], v[146:149], v[202:205], v[74:77]
	v_mfma_f32_16x16x32_bf16 v[66:69], v[154:157], v[202:205], v[66:69]
	v_mfma_f32_16x16x32_bf16 v[126:129], v[158:161], v[174:177], v[126:129]
	v_mfma_f32_16x16x32_bf16 v[118:121], v[166:169], v[174:177], v[118:121]
	v_mfma_f32_16x16x32_bf16 v[110:113], v[158:161], v[182:185], v[110:113]
	v_mfma_f32_16x16x32_bf16 v[102:105], v[166:169], v[182:185], v[102:105]
	v_mfma_f32_16x16x32_bf16 v[94:97], v[158:161], v[190:193], v[94:97]
	v_mfma_f32_16x16x32_bf16 v[86:89], v[166:169], v[190:193], v[86:89]
	v_mfma_f32_16x16x32_bf16 v[78:81], v[158:161], v[198:201], v[78:81]
	v_mfma_f32_16x16x32_bf16 v[70:73], v[166:169], v[198:201], v[70:73]
	v_mfma_f32_16x16x32_bf16 v[126:129], v[162:165], v[178:181], v[126:129]
	v_mfma_f32_16x16x32_bf16 v[118:121], v[170:173], v[178:181], v[118:121]
	v_mfma_f32_16x16x32_bf16 v[110:113], v[162:165], v[186:189], v[110:113]
	v_mfma_f32_16x16x32_bf16 v[102:105], v[170:173], v[186:189], v[102:105]
	v_mfma_f32_16x16x32_bf16 v[94:97], v[162:165], v[194:197], v[94:97]
	v_mfma_f32_16x16x32_bf16 v[86:89], v[170:173], v[194:197], v[86:89]
	v_mfma_f32_16x16x32_bf16 v[78:81], v[162:165], v[202:205], v[78:81]
	v_mfma_f32_16x16x32_bf16 v[70:73], v[170:173], v[202:205], v[70:73]
	s_barrier
	s_add_u32 s12, s40, 0x80
	s_addc_u32 s13, s41, 0
	ds_read_b128 v[174:177], v140 offset:49152
	ds_read_b128 v[178:181], v140 offset:50176
	ds_read_b128 v[182:185], v140 offset:51200
	ds_read_b128 v[186:189], v140 offset:52224
	ds_read_b128 v[190:193], v140 offset:53248
	ds_read_b128 v[194:197], v140 offset:54272
	ds_read_b128 v[198:201], v140 offset:55296
	ds_read_b128 v[202:205], v140 offset:56320
	s_mov_b32 s36, m0
	s_mov_b32 m0, s53
	s_nop 4
	global_load_lds_dwordx4 v136, s[12:13]
	s_mov_b32 m0, s36
	s_add_u32 s12, s40, 0x20080
	s_addc_u32 s13, s41, 0
	s_mov_b32 s36, m0
	s_mov_b32 m0, s54
	s_nop 4
	global_load_lds_dwordx4 v136, s[12:13]
	s_mov_b32 m0, s36
	s_add_u32 s12, s40, 0x40080
	s_addc_u32 s13, s41, 0
	s_mov_b32 s36, m0
	s_mov_b32 m0, s57
	s_nop 4
	global_load_lds_dwordx4 v136, s[12:13]
	s_mov_b32 m0, s36
	s_add_u32 s12, s40, 0x60080
	s_addc_u32 s13, s41, 0
	s_mov_b32 s36, m0
	s_mov_b32 m0, s58
	s_nop 4
	global_load_lds_dwordx4 v136, s[12:13]
	s_mov_b32 m0, s36
	s_mov_b32 s12, m0
	s_mov_b32 m0, s55
	s_nop 4
	global_load_lds_dwordx4 v1, s[38:39]
	s_mov_b32 m0, s12
	s_add_u32 s12, s34, 0x20080
	s_addc_u32 s13, s35, 0
	s_mov_b32 s34, m0
	s_mov_b32 m0, s56
	s_nop 4
	global_load_lds_dwordx4 v1, s[12:13]
	s_mov_b32 m0, s34
	s_waitcnt vmcnt(8)
	s_waitcnt lgkmcnt(0)
	s_barrier
	s_waitcnt lgkmcnt(7)
	v_mfma_f32_16x16x32_bf16 v[58:61], v[142:145], v[174:177], v[58:61]
	v_mfma_f32_16x16x32_bf16 v[50:53], v[150:153], v[174:177], v[50:53]
	s_waitcnt lgkmcnt(5)
	v_mfma_f32_16x16x32_bf16 v[42:45], v[142:145], v[182:185], v[42:45]
	v_mfma_f32_16x16x32_bf16 v[34:37], v[150:153], v[182:185], v[34:37]
	s_waitcnt lgkmcnt(3)
	v_mfma_f32_16x16x32_bf16 v[26:29], v[142:145], v[190:193], v[26:29]
	v_mfma_f32_16x16x32_bf16 v[18:21], v[150:153], v[190:193], v[18:21]
	s_waitcnt lgkmcnt(1)
	v_mfma_f32_16x16x32_bf16 v[10:13], v[142:145], v[198:201], v[10:13]
	v_mfma_f32_16x16x32_bf16 v[6:9], v[150:153], v[198:201], v[6:9]
	v_mfma_f32_16x16x32_bf16 v[58:61], v[146:149], v[178:181], v[58:61]
	v_mfma_f32_16x16x32_bf16 v[50:53], v[154:157], v[178:181], v[50:53]
	v_mfma_f32_16x16x32_bf16 v[42:45], v[146:149], v[186:189], v[42:45]
	v_mfma_f32_16x16x32_bf16 v[34:37], v[154:157], v[186:189], v[34:37]
	v_mfma_f32_16x16x32_bf16 v[26:29], v[146:149], v[194:197], v[26:29]
	v_mfma_f32_16x16x32_bf16 v[18:21], v[154:157], v[194:197], v[18:21]
	s_waitcnt lgkmcnt(0)
	v_mfma_f32_16x16x32_bf16 v[10:13], v[146:149], v[202:205], v[10:13]
	v_mfma_f32_16x16x32_bf16 v[6:9], v[154:157], v[202:205], v[6:9]
	v_mfma_f32_16x16x32_bf16 v[62:65], v[158:161], v[174:177], v[62:65]
	v_mfma_f32_16x16x32_bf16 v[54:57], v[166:169], v[174:177], v[54:57]
	v_mfma_f32_16x16x32_bf16 v[46:49], v[158:161], v[182:185], v[46:49]
	v_mfma_f32_16x16x32_bf16 v[38:41], v[166:169], v[182:185], v[38:41]
	v_mfma_f32_16x16x32_bf16 v[30:33], v[158:161], v[190:193], v[30:33]
	v_mfma_f32_16x16x32_bf16 v[22:25], v[166:169], v[190:193], v[22:25]
	v_mfma_f32_16x16x32_bf16 v[14:17], v[158:161], v[198:201], v[14:17]
	v_mfma_f32_16x16x32_bf16 v[2:5], v[166:169], v[198:201], v[2:5]
	v_mfma_f32_16x16x32_bf16 v[62:65], v[162:165], v[178:181], v[62:65]
	v_mfma_f32_16x16x32_bf16 v[54:57], v[170:173], v[178:181], v[54:57]
	v_mfma_f32_16x16x32_bf16 v[46:49], v[162:165], v[186:189], v[46:49]
	v_mfma_f32_16x16x32_bf16 v[38:41], v[170:173], v[186:189], v[38:41]
	v_mfma_f32_16x16x32_bf16 v[30:33], v[162:165], v[194:197], v[30:33]
	v_mfma_f32_16x16x32_bf16 v[22:25], v[170:173], v[194:197], v[22:25]
	v_mfma_f32_16x16x32_bf16 v[14:17], v[162:165], v[202:205], v[14:17]
	v_mfma_f32_16x16x32_bf16 v[2:5], v[170:173], v[202:205], v[2:5]
	s_barrier
	s_add_i32 s66, s66, 2
	s_add_u32 s64, s64, 0x100
	s_addc_u32 s65, s65, 0
	s_cmp_gt_u32 s66, 13
	s_mov_b64 s[36:37], s[0:1]
	s_cbranch_scc0 .LBB0_1424
	s_and_b64 vcc, exec, s[8:9]
	s_cbranch_vccz .LBB0_1427
	s_barrier

.LBB0_1493:
	ds_read_b128 v[138:141], v132
	ds_read_b128 v[142:145], v132 offset:1024
	ds_read_b128 v[146:149], v132 offset:2048
	ds_read_b128 v[150:153], v132 offset:3072
	ds_read_b128 v[154:157], v134
	ds_read_b128 v[158:161], v134 offset:1024
	ds_read_b128 v[162:165], v134 offset:2048
	ds_read_b128 v[166:169], v134 offset:3072
	s_add_u32 s34, s36, 0x100
	s_addc_u32 s35, s37, 0
	s_cmp_eq_u32 s87, 18
	s_cselect_b32 s40, s6, s34
	s_cselect_b32 s41, s7, s35
	s_cselect_b32 s38, s2, s85
	s_cselect_b32 s39, s3, s86
	s_add_u32 s42, s40, 0x80
	s_addc_u32 s43, s41, 0
	s_add_u32 s88, s36, 0x58080
	s_addc_u32 s89, s37, 0
	s_mov_b32 m0, s84
	s_nop 4
	global_load_lds_dwordx4 v130, s[88:89]
	s_add_u32 s36, s36, 0x84080
	s_addc_u32 s37, s37, 0
	s_add_i32 s88, s66, 0xe000
	s_mov_b32 m0, s88
	s_nop 4
	global_load_lds_dwordx4 v130, s[36:37]
	ds_read_b128 v[176:179], v133
	ds_read_b128 v[180:183], v133 offset:1024
	ds_read_b128 v[186:189], v133 offset:2048
	ds_read_b128 v[190:193], v133 offset:3072
	ds_read_b128 v[194:197], v133 offset:4096
	ds_read_b128 v[198:201], v133 offset:5120
	ds_read_b128 v[202:205], v133 offset:6144
	ds_read_b128 v[206:209], v133 offset:7168
	s_waitcnt vmcnt(8)
	s_waitcnt lgkmcnt(0)
	s_barrier
	v_mfma_f32_16x16x128_f8f6f4 v[126:129], v[138:145], v[176:183], v[126:129]
	v_mfma_f32_16x16x128_f8f6f4 v[118:121], v[138:145], v[186:193], v[118:121]
	v_mfma_f32_16x16x128_f8f6f4 v[102:105], v[138:145], v[194:201], v[102:105]
	v_mfma_f32_16x16x128_f8f6f4 v[86:89], v[138:145], v[202:209], v[86:89]
	v_mfma_f32_16x16x128_f8f6f4 v[122:125], v[146:153], v[176:183], v[122:125]
	v_mfma_f32_16x16x128_f8f6f4 v[114:117], v[146:153], v[186:193], v[114:117]
	v_mfma_f32_16x16x128_f8f6f4 v[98:101], v[146:153], v[194:201], v[98:101]
	v_mfma_f32_16x16x128_f8f6f4 v[82:85], v[146:153], v[202:209], v[82:85]
	v_mfma_f32_16x16x128_f8f6f4 v[110:113], v[154:161], v[176:183], v[110:113]
	v_mfma_f32_16x16x128_f8f6f4 v[94:97], v[154:161], v[186:193], v[94:97]
	v_mfma_f32_16x16x128_f8f6f4 v[78:81], v[154:161], v[194:201], v[78:81]
	v_mfma_f32_16x16x128_f8f6f4 v[62:65], v[154:161], v[202:209], v[62:65]
	v_mfma_f32_16x16x128_f8f6f4 v[106:109], v[162:169], v[176:183], v[106:109]
	v_mfma_f32_16x16x128_f8f6f4 v[90:93], v[162:169], v[186:193], v[90:93]
	v_mfma_f32_16x16x128_f8f6f4 v[74:77], v[162:169], v[194:201], v[74:77]
	v_mfma_f32_16x16x128_f8f6f4 v[42:45], v[162:169], v[202:209], v[42:45]
	s_barrier
	ds_read_b128 v[176:179], v133 offset:16384
	ds_read_b128 v[180:183], v133 offset:17408
	ds_read_b128 v[186:189], v133 offset:18432
	ds_read_b128 v[190:193], v133 offset:19456
	ds_read_b128 v[194:197], v133 offset:20480
	ds_read_b128 v[198:201], v133 offset:21504
	ds_read_b128 v[202:205], v133 offset:22528
	ds_read_b128 v[206:209], v133 offset:23552
	s_nop 4
	s_mov_b32 m0, s67
	s_nop 4
	global_load_lds_dwordx4 v131, s[38:39]
	s_add_u32 s36, s38, 0x2c000
	s_addc_u32 s37, s39, 0
	s_mov_b32 m0, s72
	s_nop 4
	global_load_lds_dwordx4 v131, s[36:37]
	s_add_u32 s36, s38, 0x58000
	s_addc_u32 s37, s39, 0
	s_mov_b32 m0, s74
	s_nop 4
	global_load_lds_dwordx4 v131, s[36:37]
	s_add_u32 s36, s38, 0x84000
	s_addc_u32 s37, s39, 0
	s_mov_b32 m0, s75
	s_nop 4
	global_load_lds_dwordx4 v131, s[36:37]
	s_nop 2
	s_mov_b32 m0, s66
	s_nop 4
	global_load_lds_dwordx4 v130, s[40:41]
	s_add_u32 s36, s40, 0x2c000
	s_addc_u32 s37, s41, 0
	s_mov_b32 m0, s73
	s_nop 4
	global_load_lds_dwordx4 v130, s[36:37]
	s_waitcnt vmcnt(8)
	s_waitcnt lgkmcnt(0)
	s_barrier
	v_mfma_f32_16x16x128_f8f6f4 v[70:73], v[138:145], v[176:183], v[70:73]
	v_mfma_f32_16x16x128_f8f6f4 v[50:53], v[138:145], v[186:193], v[50:53]
	v_mfma_f32_16x16x128_f8f6f4 v[22:25], v[138:145], v[194:201], v[22:25]
	v_mfma_f32_16x16x128_f8f6f4 v[54:57], v[138:145], v[202:209], v[54:57]
	v_mfma_f32_16x16x128_f8f6f4 v[66:69], v[146:153], v[176:183], v[66:69]
	v_mfma_f32_16x16x128_f8f6f4 v[38:41], v[146:153], v[186:193], v[38:41]
	v_mfma_f32_16x16x128_f8f6f4 v[18:21], v[146:153], v[194:201], v[18:21]
	v_mfma_f32_16x16x128_f8f6f4 v[46:49], v[146:153], v[202:209], v[46:49]
	v_mfma_f32_16x16x128_f8f6f4 v[30:33], v[154:161], v[176:183], v[30:33]
	v_mfma_f32_16x16x128_f8f6f4 v[14:17], v[154:161], v[186:193], v[14:17]
	v_mfma_f32_16x16x128_f8f6f4 v[6:9], v[154:161], v[194:201], v[6:9]
	v_mfma_f32_16x16x128_f8f6f4 v[170:173], v[154:161], v[202:209], v[170:173]
	v_mfma_f32_16x16x128_f8f6f4 v[26:29], v[162:169], v[176:183], v[26:29]
	v_mfma_f32_16x16x128_f8f6f4 v[10:13], v[162:169], v[186:193], v[10:13]
	v_mfma_f32_16x16x128_f8f6f4 v[2:5], v[162:169], v[194:201], v[2:5]
	v_mfma_f32_16x16x128_f8f6f4 v[34:37], v[162:169], v[202:209], v[34:37]
	s_barrier
	ds_read_b128 v[138:141], v135
	ds_read_b128 v[142:145], v135 offset:1024
	ds_read_b128 v[146:149], v135 offset:2048
	ds_read_b128 v[150:153], v135 offset:3072
	ds_read_b128 v[154:157], v136
	ds_read_b128 v[158:161], v136 offset:1024
	ds_read_b128 v[162:165], v136 offset:2048
	ds_read_b128 v[166:169], v136 offset:3072
	s_nop 3
	s_add_u32 s36, s40, 0x58000
	s_addc_u32 s37, s41, 0
	s_mov_b32 m0, s76
	s_nop 4
	global_load_lds_dwordx4 v130, s[36:37]
	s_add_u32 s36, s40, 0x84000
	s_addc_u32 s37, s41, 0
	s_mov_b32 m0, s77
	s_nop 4
	global_load_lds_dwordx4 v130, s[36:37]
	ds_read_b128 v[176:179], v133 offset:32768
	ds_read_b128 v[180:183], v133 offset:33792
	ds_read_b128 v[186:189], v133 offset:34816
	ds_read_b128 v[190:193], v133 offset:35840
	ds_read_b128 v[194:197], v133 offset:36864
	ds_read_b128 v[198:201], v133 offset:37888
	ds_read_b128 v[202:205], v133 offset:38912
	ds_read_b128 v[206:209], v133 offset:39936
	s_waitcnt vmcnt(8)
	s_waitcnt lgkmcnt(0)
	s_barrier
	v_mfma_f32_16x16x128_f8f6f4 v[126:129], v[138:145], v[176:183], v[126:129]
	v_mfma_f32_16x16x128_f8f6f4 v[118:121], v[138:145], v[186:193], v[118:121]
	v_mfma_f32_16x16x128_f8f6f4 v[102:105], v[138:145], v[194:201], v[102:105]
	v_mfma_f32_16x16x128_f8f6f4 v[86:89], v[138:145], v[202:209], v[86:89]
	v_mfma_f32_16x16x128_f8f6f4 v[122:125], v[146:153], v[176:183], v[122:125]
	v_mfma_f32_16x16x128_f8f6f4 v[114:117], v[146:153], v[186:193], v[114:117]
	v_mfma_f32_16x16x128_f8f6f4 v[98:101], v[146:153], v[194:201], v[98:101]
	v_mfma_f32_16x16x128_f8f6f4 v[82:85], v[146:153], v[202:209], v[82:85]
	v_mfma_f32_16x16x128_f8f6f4 v[110:113], v[154:161], v[176:183], v[110:113]
	v_mfma_f32_16x16x128_f8f6f4 v[94:97], v[154:161], v[186:193], v[94:97]
	v_mfma_f32_16x16x128_f8f6f4 v[78:81], v[154:161], v[194:201], v[78:81]
	v_mfma_f32_16x16x128_f8f6f4 v[62:65], v[154:161], v[202:209], v[62:65]
	v_mfma_f32_16x16x128_f8f6f4 v[106:109], v[162:169], v[176:183], v[106:109]
	v_mfma_f32_16x16x128_f8f6f4 v[90:93], v[162:169], v[186:193], v[90:93]
	v_mfma_f32_16x16x128_f8f6f4 v[74:77], v[162:169], v[194:201], v[74:77]
	v_mfma_f32_16x16x128_f8f6f4 v[42:45], v[162:169], v[202:209], v[42:45]
	s_barrier
	ds_read_b128 v[176:179], v133 offset:49152
	ds_read_b128 v[180:183], v133 offset:50176
	ds_read_b128 v[186:189], v133 offset:51200
	ds_read_b128 v[190:193], v133 offset:52224
	ds_read_b128 v[194:197], v133 offset:53248
	ds_read_b128 v[198:201], v133 offset:54272
	ds_read_b128 v[202:205], v133 offset:55296
	ds_read_b128 v[206:209], v133 offset:56320
	s_add_u32 s36, s38, 0x80
	s_addc_u32 s37, s39, 0
	s_mov_b32 m0, s78
	s_nop 4
	global_load_lds_dwordx4 v131, s[36:37]
	s_add_u32 s36, s38, 0x2c080
	s_addc_u32 s37, s39, 0
	s_mov_b32 m0, s79
	s_nop 4
	global_load_lds_dwordx4 v131, s[36:37]
	s_add_u32 s36, s38, 0x58080
	s_addc_u32 s37, s39, 0
	s_mov_b32 m0, s82
	s_nop 4
	global_load_lds_dwordx4 v131, s[36:37]
	s_add_u32 s36, s38, 0x84080
	s_addc_u32 s37, s39, 0
	s_mov_b32 m0, s83
	s_nop 4
	global_load_lds_dwordx4 v131, s[36:37]
	s_mov_b32 m0, s80
	s_nop 4
	global_load_lds_dwordx4 v130, s[42:43]
	s_add_u32 s36, s40, 0x2c080
	s_addc_u32 s37, s41, 0
	s_mov_b32 m0, s81
	s_nop 4
	global_load_lds_dwordx4 v130, s[36:37]
	s_waitcnt vmcnt(8)
	s_waitcnt lgkmcnt(0)
	s_barrier
	v_mfma_f32_16x16x128_f8f6f4 v[70:73], v[138:145], v[176:183], v[70:73]
	v_mfma_f32_16x16x128_f8f6f4 v[50:53], v[138:145], v[186:193], v[50:53]
	v_mfma_f32_16x16x128_f8f6f4 v[22:25], v[138:145], v[194:201], v[22:25]
	v_mfma_f32_16x16x128_f8f6f4 v[54:57], v[138:145], v[202:209], v[54:57]
	v_mfma_f32_16x16x128_f8f6f4 v[66:69], v[146:153], v[176:183], v[66:69]
	v_mfma_f32_16x16x128_f8f6f4 v[38:41], v[146:153], v[186:193], v[38:41]
	v_mfma_f32_16x16x128_f8f6f4 v[18:21], v[146:153], v[194:201], v[18:21]
	v_mfma_f32_16x16x128_f8f6f4 v[46:49], v[146:153], v[202:209], v[46:49]
	v_mfma_f32_16x16x128_f8f6f4 v[30:33], v[154:161], v[176:183], v[30:33]
	v_mfma_f32_16x16x128_f8f6f4 v[14:17], v[154:161], v[186:193], v[14:17]
	v_mfma_f32_16x16x128_f8f6f4 v[6:9], v[154:161], v[194:201], v[6:9]
	v_mfma_f32_16x16x128_f8f6f4 v[170:173], v[154:161], v[202:209], v[170:173]
	v_mfma_f32_16x16x128_f8f6f4 v[26:29], v[162:169], v[176:183], v[26:29]
	v_mfma_f32_16x16x128_f8f6f4 v[10:13], v[162:169], v[186:193], v[10:13]
	v_mfma_f32_16x16x128_f8f6f4 v[2:5], v[162:169], v[194:201], v[2:5]
	v_mfma_f32_16x16x128_f8f6f4 v[34:37], v[162:169], v[202:209], v[34:37]
	s_add_i32 s87, s87, 2
	s_add_u32 s85, s85, 0x100
	s_addc_u32 s86, s86, 0
	s_cmp_lt_u32 s87, 20
	s_mov_b64 s[36:37], s[34:35]
	s_barrier
	s_cbranch_scc1 .LBB0_1493
	s_waitcnt vmcnt(0)
	s_cmpk_gt_u32 s62, 0xff
	s_cbranch_scc1 .LBB0_1496
	s_barrier
